# hoist per-iteration address VALU out of GEMM k-loops (saddr base + VGPR offsets), plus MFMA-interleaved loads/writes
# speedup vs baseline: 1.0139x; 1.0139x over previous
.LBB0_197:
	s_ashr_i32 s6, s74, 3
	s_add_i32 s2, s6, s72
	s_and_b32 s7, s74, 7
	s_or_b32 s7, s7, s45
	s_lshl_b32 s47, s2, 6
	s_or_b32 s7, s7, s47
	s_lshl_b32 s75, s7, 7
	v_mov_b32_e32 v102, v234
	v_mov_b32_e32 v33, v234
	s_and_b32 s24, s75, 0x1f80
	s_lshl_b32 s54, s7, 1
	v_ashrrev_i32_e32 v32, 3, v33
	v_add_u32_e32 v0, s24, v32
	v_ashrrev_i32_e32 v1, 31, v0
	v_lshlrev_b64 v[0:1], 11, v[0:1]
	v_lshlrev_b32_e32 v2, 4, v33
	v_lshl_add_u64 v[0:1], s[18:19], 0, v[0:1]
	v_and_b32_e32 v96, 0x70, v2
	v_lshl_add_u64 v[34:35], v[0:1], 0, v[96:97]
	s_and_b32 s46, s54, 0xffffff80
	v_add_co_u32_e32 v38, vcc, s57, v34
	v_add_u32_e32 v0, s46, v32
	s_nop 0
	v_addc_co_u32_e32 v39, vcc, 0, v35, vcc
	v_ashrrev_i32_e32 v1, 31, v0
	v_add_co_u32_e32 v40, vcc, s58, v34
	v_lshlrev_b64 v[0:1], 11, v[0:1]
	s_nop 0
	v_addc_co_u32_e32 v41, vcc, 0, v35, vcc
	v_lshl_add_u64 v[0:1], s[20:21], 0, v[0:1]
	v_add_co_u32_e32 v42, vcc, s59, v34
	v_lshl_add_u64 v[36:37], v[0:1], 0, v[96:97]
	s_nop 0
	v_addc_co_u32_e32 v43, vcc, 0, v35, vcc
	v_add_co_u32_e32 v44, vcc, s57, v36
	s_nop 1
	v_addc_co_u32_e32 v45, vcc, 0, v37, vcc
	v_add_co_u32_e32 v46, vcc, s58, v36
	s_barrier
	global_load_dwordx4 v[0:3], v[34:35], off
	global_load_dwordx4 v[4:7], v[38:39], off
	global_load_dwordx4 v[8:11], v[40:41], off
	global_load_dwordx4 v[12:15], v[42:43], off
	global_load_dwordx4 v[16:19], v[36:37], off
	v_addc_co_u32_e32 v47, vcc, 0, v37, vcc
	v_add_co_u32_e32 v48, vcc, s59, v36
	global_load_dwordx4 v[20:23], v[44:45], off
	global_load_dwordx4 v[24:27], v[46:47], off
	v_addc_co_u32_e32 v49, vcc, 0, v37, vcc
	global_load_dwordx4 v[28:31], v[48:49], off
	global_load_dwordx4 v[68:71], v[34:35], off offset:128
	global_load_dwordx4 v[64:67], v[36:37], off offset:128
	global_load_dwordx4 v[84:87], v[38:39], off offset:128
	global_load_dwordx4 v[88:91], v[40:41], off offset:128
	global_load_dwordx4 v[92:95], v[42:43], off offset:128
	global_load_dwordx4 v[72:75], v[44:45], off offset:128
	global_load_dwordx4 v[76:79], v[46:47], off offset:128
	global_load_dwordx4 v[80:83], v[48:49], off offset:128
	s_add_i32 s6, s71, s6
	v_mul_lo_u32 v52, v32, s60
	s_lshl_b32 s6, s6, 6
	s_and_b32 s7, s73, 7
	v_add3_u32 v105, 32, v52, v96
	s_or_b32 s6, s45, s6
	s_add_i32 s6, s6, s7
	s_mov_b32 s8, 0xfffffc0
	v_lshrrev_b32_e32 v50, 1, v33
	v_and_b32_e32 v51, 31, v33
	s_lshl_b32 s6, s6, 1
	s_add_i32 s9, s56, s7
	v_and_or_b32 v51, v50, s8, v51
	v_and_b32_e32 v50, 16, v50
	s_and_b32 s6, s6, 0xffffff80
	s_and_b32 s9, s9, 63
	s_ashr_i32 s7, s6, 31
	s_lshl_b32 s9, s9, 18
	v_mul_lo_u32 v51, v51, s60
	v_add3_u32 v103, 32, v51, v50
	v_add_u32_e32 v106, 0xd800, v105
	s_waitcnt vmcnt(15)
	ds_write_b128 v105, v[0:3]
	s_waitcnt vmcnt(11)
	ds_write_b128 v105, v[16:19] offset:36864
	ds_write_b128 v105, v[4:7] offset:4608
	ds_write_b128 v105, v[8:11] offset:9216
	ds_write_b128 v105, v[12:15] offset:13824
	s_waitcnt vmcnt(10)
	ds_write_b128 v105, v[20:23] offset:41472
	s_waitcnt vmcnt(9)
	ds_write_b128 v105, v[24:27] offset:46080
	s_waitcnt vmcnt(8)
	ds_write_b128 v105, v[28:31] offset:50688
	v_and_b32_e32 v0, 0x5f, v33
	v_mul_u32_u24_e32 v0, 0x48, v0
	v_lshlrev_b32_e32 v0, 1, v0
	v_add3_u32 v104, 32, v0, v50
	v_and_b32_e32 v0, 7, v33
	v_ashrrev_i32_e32 v33, 31, v32
	v_lshlrev_b32_e32 v96, 4, v0
	v_lshl_add_u64 v[0:1], v[32:33], 0, s[6:7]
	v_lshlrev_b64 v[0:1], 11, v[0:1]
	s_add_u32 s6, s30, s9
	v_lshl_add_u64 v[98:99], s[30:31], 0, v[0:1]
	v_lshlrev_b64 v[0:1], 11, v[32:33]
	s_addc_u32 s7, s31, 0
	v_lshl_add_u64 v[100:101], s[6:7], 0, v[0:1]
	v_mov_b32_e32 v0, 0
	s_mov_b32 s6, -2
	v_mov_b32_e32 v1, v0
	v_mov_b32_e32 v2, v0
	v_mov_b32_e32 v3, v0
	v_mov_b32_e32 v4, v0
	v_mov_b32_e32 v5, v0
	v_mov_b32_e32 v6, v0
	v_mov_b32_e32 v7, v0
	v_mov_b32_e32 v8, v0
	v_mov_b32_e32 v9, v0
	v_mov_b32_e32 v10, v0
	v_mov_b32_e32 v11, v0
	v_mov_b32_e32 v12, v0
	v_mov_b32_e32 v13, v0
	v_mov_b32_e32 v14, v0
	v_mov_b32_e32 v15, v0
	v_mov_b32_e32 v16, v0
	v_mov_b32_e32 v17, v0
	v_mov_b32_e32 v18, v0
	v_mov_b32_e32 v19, v0
	v_mov_b32_e32 v20, v0
	v_mov_b32_e32 v21, v0
	v_mov_b32_e32 v22, v0
	v_mov_b32_e32 v23, v0
	v_mov_b32_e32 v24, v0
	v_mov_b32_e32 v25, v0
	v_mov_b32_e32 v26, v0
	v_mov_b32_e32 v27, v0
	v_mov_b32_e32 v28, v0
	v_mov_b32_e32 v29, v0
	v_mov_b32_e32 v30, v0
	v_mov_b32_e32 v31, v0
	v_mov_b32_e32 v32, v0
	v_mov_b32_e32 v33, v0
	v_mov_b32_e32 v34, v0
	v_mov_b32_e32 v35, v0
	v_mov_b32_e32 v36, v0
	v_mov_b32_e32 v37, v0
	v_mov_b32_e32 v38, v0
	v_mov_b32_e32 v39, v0
	v_mov_b32_e32 v40, v0
	v_mov_b32_e32 v41, v0
	v_mov_b32_e32 v42, v0
	v_mov_b32_e32 v43, v0
	v_mov_b32_e32 v44, v0
	v_mov_b32_e32 v45, v0
	v_mov_b32_e32 v46, v0
	v_mov_b32_e32 v47, v0
	v_mov_b32_e32 v48, v0
	v_mov_b32_e32 v49, v0
	v_mov_b32_e32 v50, v0
	v_mov_b32_e32 v51, v0
	v_mov_b32_e32 v52, v0
	v_mov_b32_e32 v53, v0
	v_mov_b32_e32 v54, v0
	v_mov_b32_e32 v55, v0
	v_mov_b32_e32 v56, v0
	v_mov_b32_e32 v57, v0
	v_mov_b32_e32 v58, v0
	v_mov_b32_e32 v59, v0
	v_mov_b32_e32 v60, v0
	v_mov_b32_e32 v61, v0
	v_mov_b32_e32 v62, v0
	v_mov_b32_e32 v63, v0
	v_lshl_add_u64 v[116:117], v[100:101], 0, v[96:97]
	s_mov_b32 s7, 0xc793000
	v_add_co_u32_e32 v168, vcc, s7, v116
	s_mov_b32 s7, 0xc7a3000
	s_nop 0
	v_addc_co_u32_e32 v169, vcc, 0, v117, vcc
	v_add_co_u32_e32 v170, vcc, s7, v116
	s_mov_b32 s7, 0xc7b3000
	s_nop 0
	v_addc_co_u32_e32 v171, vcc, 0, v117, vcc
	v_add_co_u32_e32 v172, vcc, s7, v116
	s_mov_b32 s7, 0xc7c3000
	s_nop 0
	v_addc_co_u32_e32 v173, vcc, 0, v117, vcc
	v_add_co_u32_e32 v174, vcc, s7, v116
	v_lshl_add_u64 v[132:133], v[98:99], 0, v[96:97]
	s_nop 0
	v_addc_co_u32_e32 v175, vcc, 0, v117, vcc
	v_add_co_u32_e32 v176, vcc, s61, v132
	s_nop 1
	v_addc_co_u32_e32 v177, vcc, 0, v133, vcc
	v_add_co_u32_e32 v178, vcc, s62, v132
	s_nop 1
	v_addc_co_u32_e32 v179, vcc, 0, v133, vcc
	v_add_co_u32_e32 v180, vcc, s63, v132
	s_nop 1
	v_addc_co_u32_e32 v181, vcc, 0, v133, vcc
	v_add_co_u32_e32 v182, vcc, s65, v132
	s_nop 1
	v_addc_co_u32_e32 v183, vcc, 0, v133, vcc
	v_subrev_u32_e32 v168, s30, v168
	v_subrev_u32_e32 v170, s30, v170
	v_subrev_u32_e32 v172, s30, v172
	v_subrev_u32_e32 v174, s30, v174
	v_subrev_u32_e32 v176, s30, v176
	v_subrev_u32_e32 v178, s30, v178
	v_subrev_u32_e32 v180, s30, v180
	v_subrev_u32_e32 v182, s30, v182
	s_mov_b64 s[98:99], s[30:31]
	s_waitcnt lgkmcnt(0)
	s_barrier
.LBB0_198:
	s_setprio 1
	ds_read_b128 v[140:143], v103
	ds_read_b128 v[144:147], v104 offset:36864
	ds_read_b128 v[148:151], v103 offset:32
	ds_read_b128 v[152:155], v104 offset:36896
	ds_read_b128 v[156:159], v104 offset:41472
	ds_read_b128 v[160:163], v104 offset:41504
	s_waitcnt lgkmcnt(4)
	v_mfma_f32_32x32x16_bf16 v[48:63], v[140:143], v[144:147], v[48:63]
	global_load_dwordx4 v[108:111], v168, s[98:99] offset:3840
	global_load_dwordx4 v[112:115], v170, s[98:99] offset:3840
	s_waitcnt lgkmcnt(1)
	v_mfma_f32_32x32x16_bf16 v[32:47], v[140:143], v[156:159], v[32:47]
	global_load_dwordx4 v[116:119], v172, s[98:99] offset:3840
	global_load_dwordx4 v[120:123], v174, s[98:99] offset:3840
	ds_read_b128 v[140:143], v103 offset:4608
	ds_read_b128 v[164:167], v103 offset:4640
	s_waitcnt lgkmcnt(1)
	v_mfma_f32_32x32x16_bf16 v[16:31], v[140:143], v[144:147], v[16:31]
	global_load_dwordx4 v[124:127], v176, s[98:99] offset:3840
	global_load_dwordx4 v[128:131], v178, s[98:99] offset:3840
	v_mfma_f32_32x32x16_bf16 v[0:15], v[140:143], v[156:159], v[0:15]
	global_load_dwordx4 v[132:135], v180, s[98:99] offset:3840
	global_load_dwordx4 v[136:139], v182, s[98:99] offset:3840
	v_mfma_f32_32x32x16_bf16 v[48:63], v[148:151], v[152:155], v[48:63]
	v_mfma_f32_32x32x16_bf16 v[32:47], v[148:151], v[160:163], v[32:47]
	s_waitcnt lgkmcnt(0)
	v_mfma_f32_32x32x16_bf16 v[16:31], v[164:167], v[152:155], v[16:31]
	ds_read_b128 v[140:143], v103 offset:64
	ds_read_b128 v[144:147], v104 offset:36928
	ds_read_b128 v[148:151], v103 offset:96
	ds_read_b128 v[152:155], v104 offset:36960
	v_mfma_f32_32x32x16_bf16 v[0:15], v[164:167], v[160:163], v[0:15]
	s_waitcnt vmcnt(15)
	ds_write_b128 v105, v[68:71] offset:18432
	ds_read_b128 v[156:159], v104 offset:41536
	ds_read_b128 v[160:163], v104 offset:41568
	s_waitcnt lgkmcnt(5)
	v_mfma_f32_32x32x16_bf16 v[48:63], v[140:143], v[144:147], v[48:63]
	s_waitcnt vmcnt(13)
	ds_write_b128 v105, v[84:87] offset:23040
	s_waitcnt lgkmcnt(2)
	v_mfma_f32_32x32x16_bf16 v[32:47], v[140:143], v[156:159], v[32:47]
	s_waitcnt vmcnt(12)
	ds_write_b128 v105, v[88:91] offset:27648
	ds_read_b128 v[140:143], v103 offset:4672
	ds_read_b128 v[164:167], v103 offset:4704
	s_waitcnt lgkmcnt(1)
	v_mfma_f32_32x32x16_bf16 v[16:31], v[140:143], v[144:147], v[16:31]
	s_waitcnt vmcnt(11)
	ds_write_b128 v105, v[92:95] offset:32256
	v_mfma_f32_32x32x16_bf16 v[0:15], v[140:143], v[156:159], v[0:15]
	ds_write_b128 v105, v[64:67] offset:55296
	v_mfma_f32_32x32x16_bf16 v[48:63], v[148:151], v[152:155], v[48:63]
	s_waitcnt vmcnt(10)
	ds_write_b128 v105, v[72:75] offset:59904
	v_mfma_f32_32x32x16_bf16 v[32:47], v[148:151], v[160:163], v[32:47]
	s_waitcnt vmcnt(9)
	ds_write_b128 v105, v[76:79] offset:64512
	s_waitcnt lgkmcnt(4)
	v_mfma_f32_32x32x16_bf16 v[16:31], v[164:167], v[152:155], v[16:31]
	s_waitcnt vmcnt(8)
	ds_write_b128 v106, v[80:83] offset:13824
	v_mfma_f32_32x32x16_bf16 v[0:15], v[164:167], v[160:163], v[0:15]
	s_setprio 0
	s_waitcnt lgkmcnt(0)
	s_barrier
	s_setprio 1
	ds_read_b128 v[140:143], v103 offset:18432
	ds_read_b128 v[144:147], v104 offset:55296
	ds_read_b128 v[148:151], v103 offset:18464
	ds_read_b128 v[152:155], v104 offset:55328
	ds_read_b128 v[156:159], v104 offset:59904
	ds_read_b128 v[160:163], v104 offset:59936
	s_waitcnt lgkmcnt(4)
	v_mfma_f32_32x32x16_bf16 v[48:63], v[140:143], v[144:147], v[48:63]
	global_load_dwordx4 v[68:71], v168, s[98:99] offset:3968
	global_load_dwordx4 v[84:87], v170, s[98:99] offset:3968
	s_waitcnt lgkmcnt(1)
	v_mfma_f32_32x32x16_bf16 v[32:47], v[140:143], v[156:159], v[32:47]
	global_load_dwordx4 v[88:91], v172, s[98:99] offset:3968
	global_load_dwordx4 v[92:95], v174, s[98:99] offset:3968
	ds_read_b128 v[140:143], v103 offset:23040
	ds_read_b128 v[164:167], v103 offset:23072
	s_waitcnt lgkmcnt(1)
	v_mfma_f32_32x32x16_bf16 v[16:31], v[140:143], v[144:147], v[16:31]
	global_load_dwordx4 v[64:67], v176, s[98:99] offset:3968
	global_load_dwordx4 v[72:75], v178, s[98:99] offset:3968
	v_mfma_f32_32x32x16_bf16 v[0:15], v[140:143], v[156:159], v[0:15]
	global_load_dwordx4 v[76:79], v180, s[98:99] offset:3968
	global_load_dwordx4 v[80:83], v182, s[98:99] offset:3968
	v_mfma_f32_32x32x16_bf16 v[48:63], v[148:151], v[152:155], v[48:63]
	v_mfma_f32_32x32x16_bf16 v[32:47], v[148:151], v[160:163], v[32:47]
	s_waitcnt lgkmcnt(0)
	v_mfma_f32_32x32x16_bf16 v[16:31], v[164:167], v[152:155], v[16:31]
	ds_read_b128 v[140:143], v103 offset:18496
	ds_read_b128 v[144:147], v104 offset:55360
	ds_read_b128 v[148:151], v103 offset:18528
	ds_read_b128 v[152:155], v104 offset:55392
	v_mfma_f32_32x32x16_bf16 v[0:15], v[164:167], v[160:163], v[0:15]
	s_add_u32 s98, s98, 0x100
	s_addc_u32 s99, s99, 0
	s_add_i32 s6, s6, 2
	s_cmp_lt_u32 s6, 11
	s_waitcnt vmcnt(15)
	ds_write_b128 v105, v[108:111]
	ds_read_b128 v[156:159], v104 offset:59968
	ds_read_b128 v[160:163], v104 offset:60000
	s_waitcnt lgkmcnt(5)
	v_mfma_f32_32x32x16_bf16 v[48:63], v[140:143], v[144:147], v[48:63]
	s_waitcnt vmcnt(14)
	ds_write_b128 v105, v[112:115] offset:4608
	s_waitcnt lgkmcnt(2)
	v_mfma_f32_32x32x16_bf16 v[32:47], v[140:143], v[156:159], v[32:47]
	s_waitcnt vmcnt(13)
	ds_write_b128 v105, v[116:119] offset:9216
	ds_read_b128 v[140:143], v103 offset:23104
	ds_read_b128 v[164:167], v103 offset:23136
	s_waitcnt lgkmcnt(1)
	v_mfma_f32_32x32x16_bf16 v[16:31], v[140:143], v[144:147], v[16:31]
	s_waitcnt vmcnt(12)
	ds_write_b128 v105, v[120:123] offset:13824
	v_mfma_f32_32x32x16_bf16 v[0:15], v[140:143], v[156:159], v[0:15]
	s_waitcnt vmcnt(11)
	ds_write_b128 v105, v[124:127] offset:36864
	v_mfma_f32_32x32x16_bf16 v[48:63], v[148:151], v[152:155], v[48:63]
	s_waitcnt vmcnt(10)
	ds_write_b128 v105, v[128:131] offset:41472
	v_mfma_f32_32x32x16_bf16 v[32:47], v[148:151], v[160:163], v[32:47]
	s_waitcnt vmcnt(9)
	ds_write_b128 v105, v[132:135] offset:46080
	s_waitcnt lgkmcnt(4)
	v_mfma_f32_32x32x16_bf16 v[16:31], v[164:167], v[152:155], v[16:31]
	s_waitcnt vmcnt(8)
	ds_write_b128 v105, v[136:139] offset:50688
	v_mfma_f32_32x32x16_bf16 v[0:15], v[164:167], v[160:163], v[0:15]
	s_setprio 0
	s_waitcnt lgkmcnt(0)
	s_barrier
	s_cbranch_scc1 .LBB0_198
	s_setprio 1
	ds_read_b128 v[98:101], v103
	ds_read_b128 v[108:111], v104 offset:36864
	ds_read_b128 v[112:115], v103 offset:32
	ds_read_b128 v[116:119], v104 offset:36896
	ds_read_b128 v[120:123], v104 offset:41472
	ds_read_b128 v[124:127], v104 offset:41504
	s_waitcnt lgkmcnt(4)
	v_mfma_f32_32x32x16_bf16 v[48:63], v[98:101], v[108:111], v[48:63]
	s_waitcnt lgkmcnt(1)
	v_mfma_f32_32x32x16_bf16 v[32:47], v[98:101], v[120:123], v[32:47]
	ds_read_b128 v[98:101], v103 offset:4608
	ds_read_b128 v[128:131], v103 offset:4640
	s_waitcnt lgkmcnt(1)
	v_mfma_f32_32x32x16_bf16 v[16:31], v[98:101], v[108:111], v[16:31]
	v_mfma_f32_32x32x16_bf16 v[0:15], v[98:101], v[120:123], v[0:15]
	v_mfma_f32_32x32x16_bf16 v[48:63], v[112:115], v[116:119], v[48:63]
	v_mfma_f32_32x32x16_bf16 v[32:47], v[112:115], v[124:127], v[32:47]
	s_waitcnt lgkmcnt(0)
	v_mfma_f32_32x32x16_bf16 v[16:31], v[128:131], v[116:119], v[16:31]
	ds_read_b128 v[98:101], v103 offset:64
	ds_read_b128 v[108:111], v104 offset:36928
	ds_read_b128 v[112:115], v103 offset:96
	ds_read_b128 v[116:119], v104 offset:36960
	v_mfma_f32_32x32x16_bf16 v[0:15], v[128:131], v[124:127], v[0:15]
	s_waitcnt vmcnt(7)
	ds_write_b128 v105, v[68:71] offset:18432
	ds_read_b128 v[120:123], v104 offset:41536
	ds_read_b128 v[124:127], v104 offset:41568
	s_waitcnt lgkmcnt(5)
	v_mfma_f32_32x32x16_bf16 v[48:63], v[98:101], v[108:111], v[48:63]
	s_waitcnt vmcnt(6)
	ds_write_b128 v105, v[84:87] offset:23040
	s_waitcnt lgkmcnt(2)
	v_mfma_f32_32x32x16_bf16 v[32:47], v[98:101], v[120:123], v[32:47]
	s_waitcnt vmcnt(5)
	ds_write_b128 v105, v[88:91] offset:27648
	ds_read_b128 v[98:101], v103 offset:4672
	ds_read_b128 v[128:131], v103 offset:4704
	s_waitcnt lgkmcnt(1)
	v_mfma_f32_32x32x16_bf16 v[16:31], v[98:101], v[108:111], v[16:31]
	s_waitcnt vmcnt(4)
	ds_write_b128 v105, v[92:95] offset:32256
	v_mfma_f32_32x32x16_bf16 v[0:15], v[98:101], v[120:123], v[0:15]
	s_waitcnt vmcnt(3)
	ds_write_b128 v105, v[64:67] offset:55296
	v_mfma_f32_32x32x16_bf16 v[48:63], v[112:115], v[116:119], v[48:63]
	s_waitcnt vmcnt(2)
	ds_write_b128 v105, v[72:75] offset:59904
	v_mfma_f32_32x32x16_bf16 v[32:47], v[112:115], v[124:127], v[32:47]
	s_waitcnt vmcnt(1)
	ds_write_b128 v105, v[76:79] offset:64512
	s_waitcnt lgkmcnt(4)
	v_mfma_f32_32x32x16_bf16 v[16:31], v[128:131], v[116:119], v[16:31]
	s_waitcnt vmcnt(0)
	ds_write_b128 v106, v[80:83] offset:13824
	v_mfma_f32_32x32x16_bf16 v[0:15], v[128:131], v[124:127], v[0:15]
	s_setprio 0
	s_waitcnt lgkmcnt(0)
	s_barrier
	s_setprio 1
	ds_read_b128 v[64:67], v103 offset:18432
	ds_read_b128 v[68:71], v104 offset:55296
	ds_read_b128 v[72:75], v103 offset:18464
	ds_read_b128 v[76:79], v104 offset:55328
	ds_read_b128 v[80:83], v104 offset:59904
	ds_read_b128 v[84:87], v104 offset:59936
	s_waitcnt lgkmcnt(4)
	v_mfma_f32_32x32x16_bf16 v[48:63], v[64:67], v[68:71], v[48:63]
	s_waitcnt lgkmcnt(1)
	v_mfma_f32_32x32x16_bf16 v[32:47], v[64:67], v[80:83], v[32:47]
	ds_read_b128 v[64:67], v103 offset:23040
	ds_read_b128 v[88:91], v103 offset:23072
	s_waitcnt lgkmcnt(1)
	v_mfma_f32_32x32x16_bf16 v[16:31], v[64:67], v[68:71], v[16:31]
	v_mfma_f32_32x32x16_bf16 v[0:15], v[64:67], v[80:83], v[0:15]
	v_mfma_f32_32x32x16_bf16 v[48:63], v[72:75], v[76:79], v[48:63]
	v_mfma_f32_32x32x16_bf16 v[32:47], v[72:75], v[84:87], v[32:47]
	s_waitcnt lgkmcnt(0)
	v_mfma_f32_32x32x16_bf16 v[16:31], v[88:91], v[76:79], v[16:31]
	ds_read_b128 v[64:67], v103 offset:18496
	ds_read_b128 v[68:71], v104 offset:55360
	ds_read_b128 v[72:75], v103 offset:18528
	ds_read_b128 v[76:79], v104 offset:55392
	v_mfma_f32_32x32x16_bf16 v[0:15], v[88:91], v[84:87], v[0:15]
	ds_read_b128 v[80:83], v104 offset:59968
	ds_read_b128 v[84:87], v104 offset:60000
	s_waitcnt lgkmcnt(4)
	v_mfma_f32_32x32x16_bf16 v[48:63], v[64:67], v[68:71], v[48:63]
	s_waitcnt lgkmcnt(1)
	v_mfma_f32_32x32x16_bf16 v[32:47], v[64:67], v[80:83], v[32:47]
	ds_read_b128 v[64:67], v103 offset:23104
	ds_read_b128 v[88:91], v103 offset:23136
	s_waitcnt lgkmcnt(1)
	v_mfma_f32_32x32x16_bf16 v[16:31], v[64:67], v[68:71], v[16:31]
	v_mfma_f32_32x32x16_bf16 v[0:15], v[64:67], v[80:83], v[0:15]
	v_mfma_f32_32x32x16_bf16 v[48:63], v[72:75], v[76:79], v[48:63]
	v_mfma_f32_32x32x16_bf16 v[32:47], v[72:75], v[84:87], v[32:47]
	s_waitcnt lgkmcnt(0)
	v_mfma_f32_32x32x16_bf16 v[16:31], v[88:91], v[76:79], v[16:31]
	v_mfma_f32_32x32x16_bf16 v[0:15], v[88:91], v[84:87], v[0:15]
	s_setprio 0
	s_cmpk_gt_u32 s24, 0xfff
	s_cselect_b64 s[12:13], -1, 0
	s_cmpk_lt_u32 s24, 0x1000
	s_cselect_b64 s[48:49], -1, 0
	s_ashr_i32 s76, s2, 2
	s_cmp_lt_i32 s76, 7
	s_barrier
	s_cbranch_scc1 .LBB0_201
	s_cmp_lg_u32 s76, 7
	s_cselect_b64 s[6:7], -1, 0
	s_cbranch_execz .LBB0_202
	s_branch .LBB0_203

.LBB0_1744:
	s_cmp_eq_u32 s26, 1
	s_mov_b32 s0, 0xa393e00
	s_cselect_b32 s16, s0, 0x8b93e00
	s_cmp_lg_u32 s26, 0
	s_cselect_b64 s[50:51], -1, 0
	s_waitcnt vmcnt(6)
	v_mov_b32_e32 v33, v234
	s_and_b64 s[0:1], s[50:51], exec
	s_cselect_b32 s0, s16, 0x8393e00
	v_ashrrev_i32_e32 v32, 3, v33
	v_add_u32_e32 v0, s69, v32
	s_add_u32 s0, s30, s0
	v_ashrrev_i32_e32 v1, 31, v0
	s_addc_u32 s1, s31, 0
	v_lshlrev_b64 v[0:1], 10, v[0:1]
	v_lshlrev_b32_e32 v2, 4, v33
	v_lshl_add_u64 v[0:1], s[0:1], 0, v[0:1]
	v_and_b32_e32 v128, 0x70, v2
	s_waitcnt vmcnt(5)
	v_lshl_add_u64 v[34:35], v[0:1], 0, v[128:129]
	s_mov_b32 s27, s17
	s_waitcnt vmcnt(4)
	v_add_co_u32_e32 v38, vcc, s61, v34
	s_lshl_b64 s[72:73], s[26:27], 20
	v_add_u32_e32 v0, s22, v32
	v_addc_co_u32_e32 v39, vcc, 0, v35, vcc
	s_add_u32 s72, s33, s72
	v_ashrrev_i32_e32 v1, 31, v0
	v_add_co_u32_e32 v40, vcc, s62, v34
	s_addc_u32 s73, s52, s73
	v_lshlrev_b64 v[0:1], 10, v[0:1]
	v_addc_co_u32_e32 v41, vcc, 0, v35, vcc
	v_lshl_add_u64 v[0:1], s[72:73], 0, v[0:1]
	v_add_co_u32_e32 v42, vcc, s63, v34
	v_lshl_add_u64 v[36:37], v[0:1], 0, v[128:129]
	s_nop 0
	v_addc_co_u32_e32 v43, vcc, 0, v35, vcc
	v_add_co_u32_e32 v44, vcc, s61, v36
	s_nop 1
	v_addc_co_u32_e32 v45, vcc, 0, v37, vcc
	v_add_co_u32_e32 v46, vcc, s62, v36
	s_barrier
	s_nop 0
	v_addc_co_u32_e32 v47, vcc, 0, v37, vcc
	v_add_co_u32_e32 v48, vcc, s63, v36
	s_nop 1
	v_addc_co_u32_e32 v49, vcc, 0, v37, vcc
	global_load_dwordx4 v[0:3], v[34:35], off
	global_load_dwordx4 v[4:7], v[38:39], off
	global_load_dwordx4 v[8:11], v[40:41], off
	global_load_dwordx4 v[12:15], v[42:43], off
	global_load_dwordx4 v[16:19], v[36:37], off
	global_load_dwordx4 v[20:23], v[44:45], off
	global_load_dwordx4 v[24:27], v[46:47], off
	global_load_dwordx4 v[28:31], v[48:49], off
	global_load_dwordx4 v[64:67], v[34:35], off offset:128
	global_load_dwordx4 v[68:71], v[38:39], off offset:128
	global_load_dwordx4 v[72:75], v[40:41], off offset:128
	global_load_dwordx4 v[76:79], v[42:43], off offset:128
	global_load_dwordx4 v[80:83], v[36:37], off offset:128
	global_load_dwordx4 v[84:87], v[44:45], off offset:128
	global_load_dwordx4 v[88:91], v[46:47], off offset:128
	global_load_dwordx4 v[92:95], v[48:49], off offset:128
	v_mul_lo_u32 v53, v32, s65
	v_add3_u32 v146, 32, v53, v128
	v_lshrrev_b32_e32 v50, 1, v33
	v_and_b32_e32 v51, 31, v33
	v_and_b32_e32 v52, 0x5f, v33
	v_and_or_b32 v51, v50, s59, v51
	v_mul_u32_u24_e32 v52, 0x48, v52
	v_and_b32_e32 v50, 16, v50
	v_mul_lo_u32 v51, v51, s65
	v_lshlrev_b32_e32 v52, 1, v52
	v_add3_u32 v144, 32, v51, v50
	v_add3_u32 v145, 32, v52, v50
	v_add_u32_e32 v147, 0xd800, v146
	s_waitcnt vmcnt(15)
	ds_write_b128 v146, v[0:3]
	s_waitcnt vmcnt(14)
	ds_write_b128 v146, v[4:7] offset:4608
	s_waitcnt vmcnt(13)
	ds_write_b128 v146, v[8:11] offset:9216
	s_waitcnt vmcnt(12)
	ds_write_b128 v146, v[12:15] offset:13824
	s_waitcnt vmcnt(11)
	ds_write_b128 v146, v[16:19] offset:36864
	s_waitcnt vmcnt(10)
	ds_write_b128 v146, v[20:23] offset:41472
	s_waitcnt vmcnt(9)
	ds_write_b128 v146, v[24:27] offset:46080
	s_waitcnt vmcnt(8)
	ds_write_b128 v146, v[28:31] offset:50688
	v_and_b32_e32 v0, 7, v33
	v_ashrrev_i32_e32 v33, 31, v32
	v_lshlrev_b32_e32 v128, 4, v0
	v_lshl_add_u64 v[0:1], s[20:21], 0, v[32:33]
	v_add_u32_e32 v2, s70, v32
	v_lshlrev_b64 v[0:1], 10, v[0:1]
	v_ashrrev_i32_e32 v3, 31, v2
	v_lshl_add_u64 v[130:131], s[48:49], 0, v[0:1]
	v_lshl_add_u64 v[132:133], s[46:47], 0, v[0:1]
	v_lshl_add_u64 v[134:135], s[44:45], 0, v[0:1]
	v_lshl_add_u64 v[136:137], s[40:41], 0, v[0:1]
	v_lshlrev_b64 v[2:3], 10, v[2:3]
	v_lshl_add_u64 v[140:141], s[34:35], 0, v[0:1]
	v_mov_b32_e32 v0, 0
	v_lshl_add_u64 v[138:139], s[0:1], 0, v[2:3]
	s_mov_b32 s0, -2
	v_mov_b32_e32 v1, v0
	v_mov_b32_e32 v2, v0
	v_mov_b32_e32 v3, v0
	v_mov_b32_e32 v4, v0
	v_mov_b32_e32 v5, v0
	v_mov_b32_e32 v6, v0
	v_mov_b32_e32 v7, v0
	v_mov_b32_e32 v8, v0
	v_mov_b32_e32 v9, v0
	v_mov_b32_e32 v10, v0
	v_mov_b32_e32 v11, v0
	v_mov_b32_e32 v12, v0
	v_mov_b32_e32 v13, v0
	v_mov_b32_e32 v14, v0
	v_mov_b32_e32 v15, v0
	v_mov_b32_e32 v16, v0
	v_mov_b32_e32 v17, v0
	v_mov_b32_e32 v18, v0
	v_mov_b32_e32 v19, v0
	v_mov_b32_e32 v20, v0
	v_mov_b32_e32 v21, v0
	v_mov_b32_e32 v22, v0
	v_mov_b32_e32 v23, v0
	v_mov_b32_e32 v24, v0
	v_mov_b32_e32 v25, v0
	v_mov_b32_e32 v26, v0
	v_mov_b32_e32 v27, v0
	v_mov_b32_e32 v28, v0
	v_mov_b32_e32 v29, v0
	v_mov_b32_e32 v30, v0
	v_mov_b32_e32 v31, v0
	v_mov_b32_e32 v32, v0
	v_mov_b32_e32 v33, v0
	v_mov_b32_e32 v34, v0
	v_mov_b32_e32 v35, v0
	v_mov_b32_e32 v36, v0
	v_mov_b32_e32 v37, v0
	v_mov_b32_e32 v38, v0
	v_mov_b32_e32 v39, v0
	v_mov_b32_e32 v40, v0
	v_mov_b32_e32 v41, v0
	v_mov_b32_e32 v42, v0
	v_mov_b32_e32 v43, v0
	v_mov_b32_e32 v44, v0
	v_mov_b32_e32 v45, v0
	v_mov_b32_e32 v46, v0
	v_mov_b32_e32 v47, v0
	v_mov_b32_e32 v48, v0
	v_mov_b32_e32 v49, v0
	v_mov_b32_e32 v50, v0
	v_mov_b32_e32 v51, v0
	v_mov_b32_e32 v52, v0
	v_mov_b32_e32 v53, v0
	v_mov_b32_e32 v54, v0
	v_mov_b32_e32 v55, v0
	v_mov_b32_e32 v56, v0
	v_mov_b32_e32 v57, v0
	v_mov_b32_e32 v58, v0
	v_mov_b32_e32 v59, v0
	v_mov_b32_e32 v60, v0
	v_mov_b32_e32 v61, v0
	v_mov_b32_e32 v62, v0
	v_mov_b32_e32 v63, v0
	v_lshl_add_u64 v[160:161], v[138:139], 0, v[128:129]
	v_add_co_u32_e32 v164, vcc, s61, v160
	v_lshl_add_u64 v[162:163], v[140:141], 0, v[128:129]
	s_nop 0
	v_addc_co_u32_e32 v165, vcc, 0, v161, vcc
	v_add_co_u32_e32 v166, vcc, s62, v160
	s_nop 0
	s_nop 0
	v_addc_co_u32_e32 v167, vcc, 0, v161, vcc
	v_add_co_u32_e32 v168, vcc, s63, v160
	s_nop 1
	v_addc_co_u32_e32 v169, vcc, 0, v161, vcc
	v_lshl_add_u64 v[116:117], v[136:137], 0, v[128:129]
	v_lshl_add_u64 v[170:171], v[132:133], 0, v[128:129]
	v_lshl_add_u64 v[172:173], v[130:131], 0, v[128:129]
	s_nop 0
	v_lshl_add_u64 v[192:193], v[134:135], 0, v[128:129]
	s_nop 0
	v_subrev_u32_e32 v130, s30, v116
	v_subrev_u32_e32 v131, s30, v192
	v_subrev_u32_e32 v160, s30, v160
	v_subrev_u32_e32 v164, s30, v164
	v_subrev_u32_e32 v166, s30, v166
	v_subrev_u32_e32 v168, s30, v168
	v_subrev_u32_e32 v162, s30, v162
	v_subrev_u32_e32 v170, s30, v170
	v_subrev_u32_e32 v172, s30, v172
	s_mov_b64 s[98:99], s[30:31]
	s_waitcnt lgkmcnt(0)
	s_barrier
.LBB0_1745:
	s_setprio 1
	ds_read_b128 v[148:151], v144
	ds_read_b128 v[152:155], v145 offset:36864
	ds_read_b128 v[156:159], v145 offset:41472
	s_waitcnt lgkmcnt(1)
	v_mfma_f32_32x32x16_bf16 v[48:63], v[148:151], v[152:155], v[48:63]
	global_load_dwordx4 v[96:99], v160, s[98:99] offset:256
	global_load_dwordx4 v[100:103], v164, s[98:99] offset:256
	s_waitcnt lgkmcnt(0)
	v_mfma_f32_32x32x16_bf16 v[32:47], v[148:151], v[156:159], v[32:47]
	global_load_dwordx4 v[104:107], v166, s[98:99] offset:256
	global_load_dwordx4 v[108:111], v168, s[98:99] offset:256
	ds_read_b128 v[148:151], v144 offset:4608
	s_waitcnt lgkmcnt(0)
	v_mfma_f32_32x32x16_bf16 v[16:31], v[148:151], v[152:155], v[16:31]
	global_load_dwordx4 v[112:115], v162, s[98:99]
	global_load_dwordx4 v[116:119], v130, s[98:99]
	v_mfma_f32_32x32x16_bf16 v[0:15], v[148:151], v[156:159], v[0:15]
	global_load_dwordx4 v[120:123], v170, s[98:99]
	global_load_dwordx4 v[124:127], v172, s[98:99] offset:-128
	ds_read_b128 v[148:151], v144 offset:32
	ds_read_b128 v[152:155], v145 offset:36896
	ds_read_b128 v[156:159], v145 offset:41504
	s_waitcnt lgkmcnt(1)
	v_mfma_f32_32x32x16_bf16 v[48:63], v[148:151], v[152:155], v[48:63]
	s_waitcnt lgkmcnt(0)
	v_mfma_f32_32x32x16_bf16 v[32:47], v[148:151], v[156:159], v[32:47]
	ds_read_b128 v[148:151], v144 offset:4640
	s_waitcnt lgkmcnt(0)
	v_mfma_f32_32x32x16_bf16 v[16:31], v[148:151], v[152:155], v[16:31]
	v_mfma_f32_32x32x16_bf16 v[0:15], v[148:151], v[156:159], v[0:15]
	s_waitcnt vmcnt(15)
	ds_write_b128 v146, v[64:67] offset:18432
	ds_read_b128 v[148:151], v144 offset:64
	ds_read_b128 v[152:155], v145 offset:36928
	ds_read_b128 v[156:159], v145 offset:41536
	s_waitcnt lgkmcnt(1)
	v_mfma_f32_32x32x16_bf16 v[48:63], v[148:151], v[152:155], v[48:63]
	s_waitcnt vmcnt(14)
	ds_write_b128 v146, v[68:71] offset:23040
	s_waitcnt lgkmcnt(1)
	v_mfma_f32_32x32x16_bf16 v[32:47], v[148:151], v[156:159], v[32:47]
	s_waitcnt vmcnt(13)
	ds_write_b128 v146, v[72:75] offset:27648
	ds_read_b128 v[148:151], v144 offset:4672
	s_waitcnt lgkmcnt(0)
	v_mfma_f32_32x32x16_bf16 v[16:31], v[148:151], v[152:155], v[16:31]
	s_waitcnt vmcnt(12)
	ds_write_b128 v146, v[76:79] offset:32256
	v_mfma_f32_32x32x16_bf16 v[0:15], v[148:151], v[156:159], v[0:15]
	s_waitcnt vmcnt(11)
	ds_write_b128 v146, v[80:83] offset:55296
	ds_read_b128 v[148:151], v144 offset:96
	ds_read_b128 v[152:155], v145 offset:36960
	ds_read_b128 v[156:159], v145 offset:41568
	s_waitcnt lgkmcnt(1)
	v_mfma_f32_32x32x16_bf16 v[48:63], v[148:151], v[152:155], v[48:63]
	s_waitcnt vmcnt(10)
	ds_write_b128 v146, v[84:87] offset:59904
	s_waitcnt lgkmcnt(1)
	v_mfma_f32_32x32x16_bf16 v[32:47], v[148:151], v[156:159], v[32:47]
	s_waitcnt vmcnt(9)
	ds_write_b128 v146, v[88:91] offset:64512
	ds_read_b128 v[148:151], v144 offset:4704
	s_waitcnt lgkmcnt(0)
	v_mfma_f32_32x32x16_bf16 v[16:31], v[148:151], v[152:155], v[16:31]
	s_waitcnt vmcnt(8)
	ds_write_b128 v147, v[92:95] offset:13824
	v_mfma_f32_32x32x16_bf16 v[0:15], v[148:151], v[156:159], v[0:15]
	s_setprio 0
	s_waitcnt lgkmcnt(0)
	s_barrier
	s_setprio 1
	ds_read_b128 v[148:151], v144 offset:18432
	ds_read_b128 v[152:155], v145 offset:55296
	ds_read_b128 v[156:159], v145 offset:59904
	s_waitcnt lgkmcnt(1)
	v_mfma_f32_32x32x16_bf16 v[48:63], v[148:151], v[152:155], v[48:63]
	global_load_dwordx4 v[64:67], v160, s[98:99] offset:384
	global_load_dwordx4 v[68:71], v164, s[98:99] offset:384
	s_waitcnt lgkmcnt(0)
	v_mfma_f32_32x32x16_bf16 v[32:47], v[148:151], v[156:159], v[32:47]
	global_load_dwordx4 v[72:75], v166, s[98:99] offset:384
	global_load_dwordx4 v[76:79], v168, s[98:99] offset:384
	ds_read_b128 v[148:151], v144 offset:23040
	s_waitcnt lgkmcnt(0)
	v_mfma_f32_32x32x16_bf16 v[16:31], v[148:151], v[152:155], v[16:31]
	global_load_dwordx4 v[80:83], v162, s[98:99] offset:128
	global_load_dwordx4 v[84:87], v131, s[98:99]
	v_mfma_f32_32x32x16_bf16 v[0:15], v[148:151], v[156:159], v[0:15]
	global_load_dwordx4 v[88:91], v170, s[98:99] offset:128
	global_load_dwordx4 v[92:95], v172, s[98:99]
	ds_read_b128 v[148:151], v144 offset:18464
	ds_read_b128 v[152:155], v145 offset:55328
	ds_read_b128 v[156:159], v145 offset:59936
	s_waitcnt lgkmcnt(1)
	v_mfma_f32_32x32x16_bf16 v[48:63], v[148:151], v[152:155], v[48:63]
	s_waitcnt lgkmcnt(0)
	v_mfma_f32_32x32x16_bf16 v[32:47], v[148:151], v[156:159], v[32:47]
	ds_read_b128 v[148:151], v144 offset:23072
	s_waitcnt lgkmcnt(0)
	v_mfma_f32_32x32x16_bf16 v[16:31], v[148:151], v[152:155], v[16:31]
	v_mfma_f32_32x32x16_bf16 v[0:15], v[148:151], v[156:159], v[0:15]
	s_add_u32 s98, s98, 0x100
	s_addc_u32 s99, s99, 0
	s_add_i32 s0, s0, 2
	s_cmp_lt_u32 s0, 3
	s_waitcnt vmcnt(15)
	ds_write_b128 v146, v[96:99]
	ds_read_b128 v[148:151], v144 offset:18496
	ds_read_b128 v[152:155], v145 offset:55360
	ds_read_b128 v[156:159], v145 offset:59968
	s_waitcnt lgkmcnt(1)
	v_mfma_f32_32x32x16_bf16 v[48:63], v[148:151], v[152:155], v[48:63]
	s_waitcnt vmcnt(14)
	ds_write_b128 v146, v[100:103] offset:4608
	s_waitcnt lgkmcnt(1)
	v_mfma_f32_32x32x16_bf16 v[32:47], v[148:151], v[156:159], v[32:47]
	s_waitcnt vmcnt(13)
	ds_write_b128 v146, v[104:107] offset:9216
	ds_read_b128 v[148:151], v144 offset:23104
	s_waitcnt lgkmcnt(0)
	v_mfma_f32_32x32x16_bf16 v[16:31], v[148:151], v[152:155], v[16:31]
	s_waitcnt vmcnt(12)
	ds_write_b128 v146, v[108:111] offset:13824
	v_mfma_f32_32x32x16_bf16 v[0:15], v[148:151], v[156:159], v[0:15]
	s_waitcnt vmcnt(11)
	ds_write_b128 v146, v[112:115] offset:36864
	ds_read_b128 v[148:151], v144 offset:18528
	ds_read_b128 v[152:155], v145 offset:55392
	ds_read_b128 v[156:159], v145 offset:60000
	s_waitcnt lgkmcnt(1)
	v_mfma_f32_32x32x16_bf16 v[48:63], v[148:151], v[152:155], v[48:63]
	s_waitcnt vmcnt(10)
	ds_write_b128 v146, v[116:119] offset:41472
	s_waitcnt lgkmcnt(1)
	v_mfma_f32_32x32x16_bf16 v[32:47], v[148:151], v[156:159], v[32:47]
	s_waitcnt vmcnt(9)
	ds_write_b128 v146, v[120:123] offset:46080
	ds_read_b128 v[148:151], v144 offset:23136
	s_waitcnt lgkmcnt(0)
	v_mfma_f32_32x32x16_bf16 v[16:31], v[148:151], v[152:155], v[16:31]
	s_waitcnt vmcnt(8)
	ds_write_b128 v146, v[124:127] offset:50688
	v_mfma_f32_32x32x16_bf16 v[0:15], v[148:151], v[156:159], v[0:15]
	s_setprio 0
	s_waitcnt lgkmcnt(0)
	s_barrier
	s_cbranch_scc1 .LBB0_1745
	s_setprio 1
	ds_read_b128 v[96:99], v144
	ds_read_b128 v[100:103], v145 offset:36864
	ds_read_b128 v[104:107], v145 offset:41472
	s_waitcnt lgkmcnt(1)
	v_mfma_f32_32x32x16_bf16 v[48:63], v[96:99], v[100:103], v[48:63]
	s_waitcnt lgkmcnt(0)
	v_mfma_f32_32x32x16_bf16 v[32:47], v[96:99], v[104:107], v[32:47]
	ds_read_b128 v[96:99], v144 offset:4608
	s_waitcnt lgkmcnt(0)
	v_mfma_f32_32x32x16_bf16 v[16:31], v[96:99], v[100:103], v[16:31]
	v_mfma_f32_32x32x16_bf16 v[0:15], v[96:99], v[104:107], v[0:15]
	ds_read_b128 v[96:99], v144 offset:32
	ds_read_b128 v[100:103], v145 offset:36896
	ds_read_b128 v[104:107], v145 offset:41504
	s_waitcnt lgkmcnt(1)
	v_mfma_f32_32x32x16_bf16 v[48:63], v[96:99], v[100:103], v[48:63]
	s_waitcnt lgkmcnt(0)
	v_mfma_f32_32x32x16_bf16 v[32:47], v[96:99], v[104:107], v[32:47]
	ds_read_b128 v[96:99], v144 offset:4640
	s_waitcnt lgkmcnt(0)
	v_mfma_f32_32x32x16_bf16 v[16:31], v[96:99], v[100:103], v[16:31]
	v_mfma_f32_32x32x16_bf16 v[0:15], v[96:99], v[104:107], v[0:15]
	s_waitcnt vmcnt(7)
	ds_write_b128 v146, v[64:67] offset:18432
	ds_read_b128 v[96:99], v144 offset:64
	ds_read_b128 v[100:103], v145 offset:36928
	ds_read_b128 v[104:107], v145 offset:41536
	s_waitcnt lgkmcnt(1)
	v_mfma_f32_32x32x16_bf16 v[48:63], v[96:99], v[100:103], v[48:63]
	s_waitcnt vmcnt(6)
	ds_write_b128 v146, v[68:71] offset:23040
	s_waitcnt lgkmcnt(1)
	v_mfma_f32_32x32x16_bf16 v[32:47], v[96:99], v[104:107], v[32:47]
	s_waitcnt vmcnt(5)
	ds_write_b128 v146, v[72:75] offset:27648
	ds_read_b128 v[96:99], v144 offset:4672
	s_waitcnt lgkmcnt(0)
	v_mfma_f32_32x32x16_bf16 v[16:31], v[96:99], v[100:103], v[16:31]
	s_waitcnt vmcnt(4)
	ds_write_b128 v146, v[76:79] offset:32256
	v_mfma_f32_32x32x16_bf16 v[0:15], v[96:99], v[104:107], v[0:15]
	s_waitcnt vmcnt(3)
	ds_write_b128 v146, v[80:83] offset:55296
	ds_read_b128 v[96:99], v144 offset:96
	ds_read_b128 v[100:103], v145 offset:36960
	ds_read_b128 v[104:107], v145 offset:41568
	s_waitcnt lgkmcnt(1)
	v_mfma_f32_32x32x16_bf16 v[48:63], v[96:99], v[100:103], v[48:63]
	s_waitcnt vmcnt(2)
	ds_write_b128 v146, v[84:87] offset:59904
	s_waitcnt lgkmcnt(1)
	v_mfma_f32_32x32x16_bf16 v[32:47], v[96:99], v[104:107], v[32:47]
	s_waitcnt vmcnt(1)
	ds_write_b128 v146, v[88:91] offset:64512
	ds_read_b128 v[96:99], v144 offset:4704
	s_waitcnt lgkmcnt(0)
	v_mfma_f32_32x32x16_bf16 v[16:31], v[96:99], v[100:103], v[16:31]
	s_waitcnt vmcnt(0)
	ds_write_b128 v147, v[92:95] offset:13824
	v_mfma_f32_32x32x16_bf16 v[0:15], v[96:99], v[104:107], v[0:15]
	s_setprio 0
	s_waitcnt lgkmcnt(0)
	s_barrier
	s_setprio 1
	ds_read_b128 v[64:67], v144 offset:18432
	ds_read_b128 v[68:71], v145 offset:55296
	ds_read_b128 v[72:75], v145 offset:59904
	s_waitcnt lgkmcnt(1)
	v_mfma_f32_32x32x16_bf16 v[48:63], v[64:67], v[68:71], v[48:63]
	s_waitcnt lgkmcnt(0)
	v_mfma_f32_32x32x16_bf16 v[32:47], v[64:67], v[72:75], v[32:47]
	ds_read_b128 v[64:67], v144 offset:23040
	s_waitcnt lgkmcnt(0)
	v_mfma_f32_32x32x16_bf16 v[16:31], v[64:67], v[68:71], v[16:31]
	v_mfma_f32_32x32x16_bf16 v[0:15], v[64:67], v[72:75], v[0:15]
	ds_read_b128 v[64:67], v144 offset:18464
	ds_read_b128 v[68:71], v145 offset:55328
	ds_read_b128 v[72:75], v145 offset:59936
	s_waitcnt lgkmcnt(1)
	v_mfma_f32_32x32x16_bf16 v[48:63], v[64:67], v[68:71], v[48:63]
	s_waitcnt lgkmcnt(0)
	v_mfma_f32_32x32x16_bf16 v[32:47], v[64:67], v[72:75], v[32:47]
	ds_read_b128 v[64:67], v144 offset:23072
	s_waitcnt lgkmcnt(0)
	v_mfma_f32_32x32x16_bf16 v[16:31], v[64:67], v[68:71], v[16:31]
	v_mfma_f32_32x32x16_bf16 v[0:15], v[64:67], v[72:75], v[0:15]
	ds_read_b128 v[64:67], v144 offset:18496
	ds_read_b128 v[68:71], v145 offset:55360
	ds_read_b128 v[72:75], v145 offset:59968
	s_waitcnt lgkmcnt(1)
	v_mfma_f32_32x32x16_bf16 v[48:63], v[64:67], v[68:71], v[48:63]
	s_waitcnt lgkmcnt(0)
	v_mfma_f32_32x32x16_bf16 v[32:47], v[64:67], v[72:75], v[32:47]
	ds_read_b128 v[64:67], v144 offset:23104
	s_waitcnt lgkmcnt(0)
	v_mfma_f32_32x32x16_bf16 v[16:31], v[64:67], v[68:71], v[16:31]
	v_mfma_f32_32x32x16_bf16 v[0:15], v[64:67], v[72:75], v[0:15]
	ds_read_b128 v[64:67], v144 offset:18528
	ds_read_b128 v[68:71], v145 offset:55392
	ds_read_b128 v[72:75], v145 offset:60000
	s_waitcnt lgkmcnt(1)
	v_mfma_f32_32x32x16_bf16 v[48:63], v[64:67], v[68:71], v[48:63]
	s_waitcnt lgkmcnt(0)
	v_mfma_f32_32x32x16_bf16 v[32:47], v[64:67], v[72:75], v[32:47]
	ds_read_b128 v[64:67], v144 offset:23136
	s_waitcnt lgkmcnt(0)
	v_mfma_f32_32x32x16_bf16 v[16:31], v[64:67], v[68:71], v[16:31]
	v_mfma_f32_32x32x16_bf16 v[0:15], v[64:67], v[72:75], v[0:15]
	s_setprio 0
	s_nop 6
	v_cvt_pk_bf16_f32 v32, v32, s0
	s_nop 2
	v_cvt_pk_bf16_f32 v0, v0, s0
	s_barrier
	ds_write_b16 v143, v32 offset:64
	v_cvt_pk_bf16_f32 v32, v49, s0
	ds_write_b16 v143, v0 offset:8768
	v_cvt_pk_bf16_f32 v0, v17, s0
	ds_write_b16 v143, v32 offset:272
	v_cvt_pk_bf16_f32 v32, v33, s0
	ds_write_b16 v143, v0 offset:8976
	v_cvt_pk_bf16_f32 v0, v1, s0
	ds_write_b16 v143, v32 offset:336
	v_cvt_pk_bf16_f32 v32, v50, s0
	ds_write_b16 v143, v0 offset:9040
	v_cvt_pk_bf16_f32 v0, v18, s0
	ds_write_b16 v143, v32 offset:544
	v_cvt_pk_bf16_f32 v32, v34, s0
	ds_write_b16 v143, v0 offset:9248
	v_cvt_pk_bf16_f32 v0, v2, s0
	ds_write_b16 v143, v32 offset:608
	v_cvt_pk_bf16_f32 v32, v51, s0
	ds_write_b16 v143, v0 offset:9312
	v_cvt_pk_bf16_f32 v0, v19, s0
	ds_write_b16 v143, v32 offset:816
	v_cvt_pk_bf16_f32 v32, v35, s0
	ds_write_b16 v143, v0 offset:9520
	v_cvt_pk_bf16_f32 v0, v3, s0
	ds_write_b16 v143, v32 offset:880
	v_cvt_pk_bf16_f32 v32, v52, s0
	ds_write_b16 v143, v0 offset:9584
	v_cvt_pk_bf16_f32 v0, v20, s0
	ds_write_b16 v143, v32 offset:2176
	v_cvt_pk_bf16_f32 v32, v36, s0
	ds_write_b16 v143, v0 offset:10880
	v_cvt_pk_bf16_f32 v0, v4, s0
	ds_write_b16 v143, v32 offset:2240
	v_cvt_pk_bf16_f32 v32, v53, s0
	ds_write_b16 v143, v0 offset:10944
	v_cvt_pk_bf16_f32 v0, v21, s0
	ds_write_b16 v143, v32 offset:2448
	v_cvt_pk_bf16_f32 v32, v37, s0
	ds_write_b16 v143, v0 offset:11152
	v_cvt_pk_bf16_f32 v0, v5, s0
	ds_write_b16 v143, v32 offset:2512
	v_cvt_pk_bf16_f32 v32, v54, s0
	ds_write_b16 v143, v0 offset:11216
	v_cvt_pk_bf16_f32 v0, v22, s0
	ds_write_b16 v143, v32 offset:2720
	v_cvt_pk_bf16_f32 v32, v38, s0
	ds_write_b16 v143, v0 offset:11424
	v_cvt_pk_bf16_f32 v0, v6, s0
	ds_write_b16 v143, v32 offset:2784
	v_cvt_pk_bf16_f32 v32, v55, s0
	ds_write_b16 v143, v0 offset:11488
	v_cvt_pk_bf16_f32 v0, v23, s0
	ds_write_b16 v143, v32 offset:2992
	v_cvt_pk_bf16_f32 v32, v39, s0
	ds_write_b16 v143, v0 offset:11696
	v_cvt_pk_bf16_f32 v0, v7, s0
	ds_write_b16 v143, v32 offset:3056
	v_cvt_pk_bf16_f32 v32, v56, s0
	ds_write_b16 v143, v0 offset:11760
	v_cvt_pk_bf16_f32 v0, v24, s0
	ds_write_b16 v143, v32 offset:4352
	v_cvt_pk_bf16_f32 v32, v40, s0
	ds_write_b16 v143, v0 offset:13056
	v_cvt_pk_bf16_f32 v0, v8, s0
	ds_write_b16 v143, v32 offset:4416
	v_cvt_pk_bf16_f32 v32, v57, s0
	ds_write_b16 v143, v0 offset:13120
	v_cvt_pk_bf16_f32 v0, v25, s0
	ds_write_b16 v143, v32 offset:4624
	v_cvt_pk_bf16_f32 v32, v41, s0
	ds_write_b16 v143, v0 offset:13328
	v_cvt_pk_bf16_f32 v0, v9, s0
	ds_write_b16 v143, v32 offset:4688
	v_cvt_pk_bf16_f32 v32, v58, s0
	ds_write_b16 v143, v0 offset:13392
	v_cvt_pk_bf16_f32 v0, v26, s0
	ds_write_b16 v143, v32 offset:4896
	v_cvt_pk_bf16_f32 v32, v42, s0
	ds_write_b16 v143, v0 offset:13600
	v_cvt_pk_bf16_f32 v0, v10, s0
	ds_write_b16 v143, v32 offset:4960
	v_cvt_pk_bf16_f32 v32, v59, s0
	ds_write_b16 v143, v0 offset:13664
	v_cvt_pk_bf16_f32 v0, v27, s0
	ds_write_b16 v143, v32 offset:5168
	v_cvt_pk_bf16_f32 v32, v43, s0
	ds_write_b16 v143, v0 offset:13872
	v_cvt_pk_bf16_f32 v0, v11, s0
	ds_write_b16 v143, v32 offset:5232
	v_cvt_pk_bf16_f32 v32, v60, s0
	ds_write_b16 v143, v0 offset:13936
	v_cvt_pk_bf16_f32 v0, v28, s0
	ds_write_b16 v143, v32 offset:6528
	v_cvt_pk_bf16_f32 v32, v44, s0
	ds_write_b16 v143, v0 offset:15232
	v_cvt_pk_bf16_f32 v0, v12, s0
	ds_write_b16 v143, v32 offset:6592
	v_cvt_pk_bf16_f32 v32, v61, s0
	ds_write_b16 v143, v0 offset:15296
	v_cvt_pk_bf16_f32 v0, v29, s0
	ds_write_b16 v143, v32 offset:6800
	v_cvt_pk_bf16_f32 v32, v45, s0
	ds_write_b16 v143, v0 offset:15504
	v_cvt_pk_bf16_f32 v0, v13, s0
	ds_write_b16 v143, v32 offset:6864
	v_cvt_pk_bf16_f32 v32, v62, s0
	ds_write_b16 v143, v0 offset:15568
	v_cvt_pk_bf16_f32 v0, v30, s0
	ds_write_b16 v143, v32 offset:7072
	v_cvt_pk_bf16_f32 v32, v46, s0
	ds_write_b16 v143, v0 offset:15776
	v_cvt_pk_bf16_f32 v0, v14, s0
	ds_write_b16 v143, v32 offset:7136
	v_cvt_pk_bf16_f32 v32, v63, s0
	ds_write_b16 v143, v0 offset:15840
	v_cvt_pk_bf16_f32 v0, v31, s0
	v_cvt_pk_bf16_f32 v48, v48, s0
	ds_write_b16 v143, v32 offset:7344
	v_cvt_pk_bf16_f32 v32, v47, s0
	v_cvt_pk_bf16_f32 v16, v16, s0
	ds_write_b16 v143, v0 offset:16048
	v_cvt_pk_bf16_f32 v0, v15, s0
	v_mov_b32_e32 v15, v142
	ds_write_b16 v143, v48
	ds_write_b16 v143, v32 offset:7408
	ds_write_b16 v143, v16 offset:8704
	ds_write_b16 v143, v0 offset:16112
	s_waitcnt lgkmcnt(0)
	s_barrier
	v_mov_b64_e32 v[2:3], s[4:5]
	v_lshlrev_b32_e32 v0, 3, v15
	v_and_b32_e32 v0, 0x78, v0
	v_ashrrev_i32_e32 v1, 4, v15
	v_lshlrev_b32_e32 v128, 1, v0
	v_add_u32_e32 v0, s69, v1
	s_lshl_b32 s16, s26, 10
	v_mad_i64_i32 v[2:3], s[0:1], v0, s66, v[2:3]
	v_lshl_add_u64 v[2:3], s[16:17], 1, v[2:3]
	v_lshl_add_u64 v[2:3], s[22:23], 1, v[2:3]
	v_lshl_add_u64 v[2:3], v[2:3], 0, v[128:129]
	global_load_dwordx4 v[6:9], v[2:3], off
	v_add_u32_e32 v14, 32, v128
	v_mad_u64_u32 v[2:3], s[0:1], v1, s60, v[14:15]
	ds_read_b128 v[2:5], v2
	v_ashrrev_i32_e32 v1, 31, v0
	v_lshlrev_b64 v[0:1], 11, v[0:1]
	v_lshl_add_u64 v[0:1], s[24:25], 0, v[0:1]
	v_lshl_add_u64 v[16:17], v[0:1], 0, v[128:129]
	v_cndmask_b32_e64 v1, 0, 1, s[50:51]
	v_mov_b32_e32 v0, 0
	v_cmp_ne_u32_e64 s[0:1], 1, v1
	s_andn2_b64 vcc, exec, s[50:51]
	v_mov_b32_e32 v10, 0
	v_mov_b32_e32 v11, 0
	v_mov_b32_e32 v12, 0
	v_mov_b32_e32 v13, 0
	s_cbranch_vccnz .LBB0_1748
	global_load_dwordx4 v[10:13], v[16:17], off

.LBB0_1816:
	s_and_b32 s0, s57, 7
	s_or_b32 s1, s0, s3
	s_lshl_b32 s0, s57, 4
	v_mov_b32_e32 v0, v234
	s_waitcnt vmcnt(6)
	v_mov_b32_e32 v33, v234
	s_and_b32 s21, s0, 0xffffff80
	s_lshl_b32 s0, s1, 7
	s_nop 0
	v_ashrrev_i32_e32 v32, 3, v33
	v_add_u32_e32 v0, s0, v32
	v_ashrrev_i32_e32 v1, 31, v0
	v_lshlrev_b64 v[0:1], 11, v[0:1]
	v_lshlrev_b32_e32 v2, 4, v33
	v_lshl_add_u64 v[0:1], s[4:5], 0, v[0:1]
	v_and_b32_e32 v96, 0x70, v2
	s_waitcnt vmcnt(5)
	v_lshl_add_u64 v[34:35], v[0:1], 0, v[96:97]
	s_waitcnt vmcnt(4)
	v_add_co_u32_e32 v38, vcc, s35, v34
	v_add_u32_e32 v0, s21, v32
	s_nop 0
	v_addc_co_u32_e32 v39, vcc, 0, v35, vcc
	v_ashrrev_i32_e32 v1, 31, v0
	v_add_co_u32_e32 v40, vcc, s40, v34
	v_lshlrev_b64 v[0:1], 11, v[0:1]
	s_nop 0
	v_addc_co_u32_e32 v41, vcc, 0, v35, vcc
	v_lshl_add_u64 v[0:1], s[6:7], 0, v[0:1]
	v_add_co_u32_e32 v42, vcc, s41, v34
	v_lshl_add_u64 v[36:37], v[0:1], 0, v[96:97]
	s_nop 0
	v_addc_co_u32_e32 v43, vcc, 0, v35, vcc
	v_add_co_u32_e32 v44, vcc, s35, v36
	s_barrier
	s_nop 0
	v_addc_co_u32_e32 v45, vcc, 0, v37, vcc
	v_add_co_u32_e32 v46, vcc, s40, v36
	s_nop 1
	v_addc_co_u32_e32 v47, vcc, 0, v37, vcc
	global_load_dwordx4 v[0:3], v[34:35], off
	global_load_dwordx4 v[4:7], v[38:39], off
	global_load_dwordx4 v[8:11], v[40:41], off
	global_load_dwordx4 v[12:15], v[42:43], off
	global_load_dwordx4 v[16:19], v[36:37], off
	v_add_co_u32_e32 v48, vcc, s41, v36
	global_load_dwordx4 v[20:23], v[44:45], off
	s_waitcnt lgkmcnt(0)
	global_load_dwordx4 v[24:27], v[46:47], off
	v_addc_co_u32_e32 v49, vcc, 0, v37, vcc
	global_load_dwordx4 v[28:31], v[48:49], off
	global_load_dwordx4 v[68:71], v[34:35], off offset:128
	global_load_dwordx4 v[64:67], v[36:37], off offset:128
	global_load_dwordx4 v[84:87], v[38:39], off offset:128
	global_load_dwordx4 v[88:91], v[40:41], off offset:128
	global_load_dwordx4 v[92:95], v[42:43], off offset:128
	global_load_dwordx4 v[72:75], v[44:45], off offset:128
	global_load_dwordx4 v[76:79], v[46:47], off offset:128
	global_load_dwordx4 v[80:83], v[48:49], off offset:128
	v_and_b32_e32 v52, 0x5f, v33
	v_mul_lo_u32 v53, v32, s44
	v_lshrrev_b32_e32 v50, 1, v33
	v_and_b32_e32 v51, 31, v33
	v_mul_u32_u24_e32 v52, 0x48, v52
	v_add3_u32 v105, 32, v53, v96
	s_and_b32 s18, s24, 0xffffff80
	v_and_or_b32 v51, v50, s45, v51
	v_and_b32_e32 v50, 16, v50
	s_and_b32 s10, s17, 7
	s_ashr_i32 s19, s18, 31
	s_lshl_b32 s20, s10, 7
	v_mul_lo_u32 v51, v51, s44
	v_add3_u32 v103, 32, v51, v50
	v_add_u32_e32 v106, 0xd800, v105
	s_mov_b32 s10, -2
	v_mov_b32_e32 v34, v97
	v_mov_b32_e32 v35, v97
	v_mov_b32_e32 v36, v97
	v_mov_b32_e32 v37, v97
	v_mov_b32_e32 v38, v97
	v_mov_b32_e32 v39, v97
	v_mov_b32_e32 v40, v97
	v_mov_b32_e32 v41, v97
	v_mov_b32_e32 v42, v97
	v_mov_b32_e32 v43, v97
	v_mov_b32_e32 v44, v97
	v_mov_b32_e32 v45, v97
	v_mov_b32_e32 v46, v97
	v_mov_b32_e32 v47, v97
	v_mov_b32_e32 v48, v97
	v_mov_b32_e32 v49, v97
	v_mov_b32_e32 v51, v97
	v_mov_b32_e32 v53, v97
	v_mov_b32_e32 v54, v97
	v_mov_b32_e32 v55, v97
	v_mov_b32_e32 v56, v97
	s_waitcnt vmcnt(15)
	ds_write_b128 v105, v[0:3]
	s_waitcnt vmcnt(11)
	ds_write_b128 v105, v[16:19] offset:36864
	ds_write_b128 v105, v[4:7] offset:4608
	ds_write_b128 v105, v[8:11] offset:9216
	ds_write_b128 v105, v[12:15] offset:13824
	s_waitcnt vmcnt(10)
	ds_write_b128 v105, v[20:23] offset:41472
	s_waitcnt vmcnt(9)
	ds_write_b128 v105, v[24:27] offset:46080
	s_waitcnt vmcnt(8)
	ds_write_b128 v105, v[28:31] offset:50688
	v_lshlrev_b32_e32 v0, 1, v52
	v_add3_u32 v104, 32, v0, v50
	v_and_b32_e32 v0, 7, v33
	v_ashrrev_i32_e32 v33, 31, v32
	v_lshlrev_b32_e32 v96, 4, v0
	v_lshl_add_u64 v[0:1], v[32:33], 0, s[18:19]
	v_lshlrev_b64 v[0:1], 11, v[0:1]
	s_add_i32 s19, s20, s26
	v_lshl_add_u64 v[98:99], s[30:31], 0, v[0:1]
	v_add_u32_e32 v0, s19, v32
	v_ashrrev_i32_e32 v1, 31, v0
	v_lshlrev_b64 v[0:1], 11, v[0:1]
	v_lshl_add_u64 v[100:101], s[30:31], 0, v[0:1]
	v_mov_b32_e32 v0, v97
	v_mov_b32_e32 v1, v97
	v_mov_b32_e32 v2, v97
	v_mov_b32_e32 v3, v97
	v_mov_b32_e32 v4, v97
	v_mov_b32_e32 v5, v97
	v_mov_b32_e32 v6, v97
	v_mov_b32_e32 v7, v97
	v_mov_b32_e32 v8, v97
	v_mov_b32_e32 v9, v97
	v_mov_b32_e32 v10, v97
	v_mov_b32_e32 v11, v97
	v_mov_b32_e32 v12, v97
	v_mov_b32_e32 v13, v97
	v_mov_b32_e32 v14, v97
	v_mov_b32_e32 v15, v97
	v_mov_b32_e32 v16, v97
	v_mov_b32_e32 v17, v97
	v_mov_b32_e32 v18, v97
	v_mov_b32_e32 v19, v97
	v_mov_b32_e32 v20, v97
	v_mov_b32_e32 v21, v97
	v_mov_b32_e32 v22, v97
	v_mov_b32_e32 v23, v97
	v_mov_b32_e32 v24, v97
	v_mov_b32_e32 v25, v97
	v_mov_b32_e32 v26, v97
	v_mov_b32_e32 v27, v97
	v_mov_b32_e32 v28, v97
	v_mov_b32_e32 v29, v97
	v_mov_b32_e32 v30, v97
	v_mov_b32_e32 v31, v97
	v_mov_b32_e32 v32, v97
	v_mov_b32_e32 v33, v97
	v_mov_b32_e32 v50, v97
	v_mov_b32_e32 v52, v97
	v_mov_b32_e32 v57, v97
	v_mov_b32_e32 v58, v97
	v_mov_b32_e32 v59, v97
	v_mov_b32_e32 v60, v97
	v_mov_b32_e32 v61, v97
	v_mov_b32_e32 v62, v97
	v_mov_b32_e32 v63, v97
	v_lshl_add_u64 v[116:117], v[100:101], 0, v[96:97]
	v_add_co_u32_e32 v168, vcc, s46, v116
	v_lshl_add_u64 v[132:133], v[98:99], 0, v[96:97]
	s_nop 0
	v_addc_co_u32_e32 v169, vcc, 0, v117, vcc
	v_add_co_u32_e32 v170, vcc, s47, v116
	s_nop 1
	v_addc_co_u32_e32 v171, vcc, 0, v117, vcc
	v_add_co_u32_e32 v172, vcc, s48, v116
	s_nop 1
	v_addc_co_u32_e32 v173, vcc, 0, v117, vcc
	v_add_co_u32_e32 v174, vcc, s49, v116
	s_nop 1
	v_addc_co_u32_e32 v175, vcc, 0, v117, vcc
	v_add_co_u32_e32 v176, vcc, s50, v132
	s_nop 1
	v_addc_co_u32_e32 v177, vcc, 0, v133, vcc
	v_add_co_u32_e32 v178, vcc, s51, v132
	s_nop 1
	v_addc_co_u32_e32 v179, vcc, 0, v133, vcc
	v_add_co_u32_e32 v180, vcc, s52, v132
	s_nop 1
	v_addc_co_u32_e32 v181, vcc, 0, v133, vcc
	v_add_co_u32_e32 v182, vcc, s53, v132
	s_nop 1
	v_addc_co_u32_e32 v183, vcc, 0, v133, vcc
	v_subrev_u32_e32 v168, s30, v168
	v_subrev_u32_e32 v170, s30, v170
	v_subrev_u32_e32 v172, s30, v172
	v_subrev_u32_e32 v174, s30, v174
	v_subrev_u32_e32 v176, s30, v176
	v_subrev_u32_e32 v178, s30, v178
	v_subrev_u32_e32 v180, s30, v180
	v_subrev_u32_e32 v182, s30, v182
	s_mov_b64 s[98:99], s[30:31]
	s_waitcnt lgkmcnt(0)
	s_barrier
.LBB0_1817:
	s_setprio 1
	ds_read_b128 v[140:143], v103
	ds_read_b128 v[144:147], v104 offset:36864
	ds_read_b128 v[148:151], v103 offset:32
	ds_read_b128 v[152:155], v104 offset:36896
	ds_read_b128 v[156:159], v104 offset:41472
	ds_read_b128 v[160:163], v104 offset:41504
	s_waitcnt lgkmcnt(4)
	v_mfma_f32_32x32x16_bf16 v[48:63], v[140:143], v[144:147], v[48:63]
	global_load_dwordx4 v[108:111], v168, s[98:99] offset:3840
	global_load_dwordx4 v[112:115], v170, s[98:99] offset:3840
	s_waitcnt lgkmcnt(1)
	v_mfma_f32_32x32x16_bf16 v[32:47], v[140:143], v[156:159], v[32:47]
	global_load_dwordx4 v[116:119], v172, s[98:99] offset:3840
	global_load_dwordx4 v[120:123], v174, s[98:99] offset:3840
	ds_read_b128 v[140:143], v103 offset:4608
	ds_read_b128 v[164:167], v103 offset:4640
	s_waitcnt lgkmcnt(1)
	v_mfma_f32_32x32x16_bf16 v[16:31], v[140:143], v[144:147], v[16:31]
	global_load_dwordx4 v[124:127], v176, s[98:99] offset:3840
	global_load_dwordx4 v[128:131], v178, s[98:99] offset:3840
	v_mfma_f32_32x32x16_bf16 v[0:15], v[140:143], v[156:159], v[0:15]
	global_load_dwordx4 v[132:135], v180, s[98:99] offset:3840
	global_load_dwordx4 v[136:139], v182, s[98:99] offset:3840
	v_mfma_f32_32x32x16_bf16 v[48:63], v[148:151], v[152:155], v[48:63]
	v_mfma_f32_32x32x16_bf16 v[32:47], v[148:151], v[160:163], v[32:47]
	s_waitcnt lgkmcnt(0)
	v_mfma_f32_32x32x16_bf16 v[16:31], v[164:167], v[152:155], v[16:31]
	ds_read_b128 v[140:143], v103 offset:64
	ds_read_b128 v[144:147], v104 offset:36928
	ds_read_b128 v[148:151], v103 offset:96
	ds_read_b128 v[152:155], v104 offset:36960
	v_mfma_f32_32x32x16_bf16 v[0:15], v[164:167], v[160:163], v[0:15]
	s_waitcnt vmcnt(15)
	ds_write_b128 v105, v[68:71] offset:18432
	ds_read_b128 v[156:159], v104 offset:41536
	ds_read_b128 v[160:163], v104 offset:41568
	s_waitcnt lgkmcnt(5)
	v_mfma_f32_32x32x16_bf16 v[48:63], v[140:143], v[144:147], v[48:63]
	s_waitcnt vmcnt(13)
	ds_write_b128 v105, v[84:87] offset:23040
	s_waitcnt lgkmcnt(2)
	v_mfma_f32_32x32x16_bf16 v[32:47], v[140:143], v[156:159], v[32:47]
	s_waitcnt vmcnt(12)
	ds_write_b128 v105, v[88:91] offset:27648
	ds_read_b128 v[140:143], v103 offset:4672
	ds_read_b128 v[164:167], v103 offset:4704
	s_waitcnt lgkmcnt(1)
	v_mfma_f32_32x32x16_bf16 v[16:31], v[140:143], v[144:147], v[16:31]
	s_waitcnt vmcnt(11)
	ds_write_b128 v105, v[92:95] offset:32256
	v_mfma_f32_32x32x16_bf16 v[0:15], v[140:143], v[156:159], v[0:15]
	ds_write_b128 v105, v[64:67] offset:55296
	v_mfma_f32_32x32x16_bf16 v[48:63], v[148:151], v[152:155], v[48:63]
	s_waitcnt vmcnt(10)
	ds_write_b128 v105, v[72:75] offset:59904
	v_mfma_f32_32x32x16_bf16 v[32:47], v[148:151], v[160:163], v[32:47]
	s_waitcnt vmcnt(9)
	ds_write_b128 v105, v[76:79] offset:64512
	s_waitcnt lgkmcnt(4)
	v_mfma_f32_32x32x16_bf16 v[16:31], v[164:167], v[152:155], v[16:31]
	s_waitcnt vmcnt(8)
	ds_write_b128 v106, v[80:83] offset:13824
	v_mfma_f32_32x32x16_bf16 v[0:15], v[164:167], v[160:163], v[0:15]
	s_setprio 0
	s_waitcnt lgkmcnt(0)
	s_barrier
	s_setprio 1
	ds_read_b128 v[140:143], v103 offset:18432
	ds_read_b128 v[144:147], v104 offset:55296
	ds_read_b128 v[148:151], v103 offset:18464
	ds_read_b128 v[152:155], v104 offset:55328
	ds_read_b128 v[156:159], v104 offset:59904
	ds_read_b128 v[160:163], v104 offset:59936
	s_waitcnt lgkmcnt(4)
	v_mfma_f32_32x32x16_bf16 v[48:63], v[140:143], v[144:147], v[48:63]
	global_load_dwordx4 v[68:71], v168, s[98:99] offset:3968
	global_load_dwordx4 v[84:87], v170, s[98:99] offset:3968
	s_waitcnt lgkmcnt(1)
	v_mfma_f32_32x32x16_bf16 v[32:47], v[140:143], v[156:159], v[32:47]
	global_load_dwordx4 v[88:91], v172, s[98:99] offset:3968
	global_load_dwordx4 v[92:95], v174, s[98:99] offset:3968
	ds_read_b128 v[140:143], v103 offset:23040
	ds_read_b128 v[164:167], v103 offset:23072
	s_waitcnt lgkmcnt(1)
	v_mfma_f32_32x32x16_bf16 v[16:31], v[140:143], v[144:147], v[16:31]
	global_load_dwordx4 v[64:67], v176, s[98:99] offset:3968
	global_load_dwordx4 v[72:75], v178, s[98:99] offset:3968
	v_mfma_f32_32x32x16_bf16 v[0:15], v[140:143], v[156:159], v[0:15]
	global_load_dwordx4 v[76:79], v180, s[98:99] offset:3968
	global_load_dwordx4 v[80:83], v182, s[98:99] offset:3968
	v_mfma_f32_32x32x16_bf16 v[48:63], v[148:151], v[152:155], v[48:63]
	v_mfma_f32_32x32x16_bf16 v[32:47], v[148:151], v[160:163], v[32:47]
	s_waitcnt lgkmcnt(0)
	v_mfma_f32_32x32x16_bf16 v[16:31], v[164:167], v[152:155], v[16:31]
	ds_read_b128 v[140:143], v103 offset:18496
	ds_read_b128 v[144:147], v104 offset:55360
	ds_read_b128 v[148:151], v103 offset:18528
	ds_read_b128 v[152:155], v104 offset:55392
	v_mfma_f32_32x32x16_bf16 v[0:15], v[164:167], v[160:163], v[0:15]
	s_add_u32 s98, s98, 0x100
	s_addc_u32 s99, s99, 0
	s_add_i32 s10, s10, 2
	s_cmp_lt_u32 s10, 11
	s_waitcnt vmcnt(15)
	ds_write_b128 v105, v[108:111]
	ds_read_b128 v[156:159], v104 offset:59968
	ds_read_b128 v[160:163], v104 offset:60000
	s_waitcnt lgkmcnt(5)
	v_mfma_f32_32x32x16_bf16 v[48:63], v[140:143], v[144:147], v[48:63]
	s_waitcnt vmcnt(14)
	ds_write_b128 v105, v[112:115] offset:4608
	s_waitcnt lgkmcnt(2)
	v_mfma_f32_32x32x16_bf16 v[32:47], v[140:143], v[156:159], v[32:47]
	s_waitcnt vmcnt(13)
	ds_write_b128 v105, v[116:119] offset:9216
	ds_read_b128 v[140:143], v103 offset:23104
	ds_read_b128 v[164:167], v103 offset:23136
	s_waitcnt lgkmcnt(1)
	v_mfma_f32_32x32x16_bf16 v[16:31], v[140:143], v[144:147], v[16:31]
	s_waitcnt vmcnt(12)
	ds_write_b128 v105, v[120:123] offset:13824
	v_mfma_f32_32x32x16_bf16 v[0:15], v[140:143], v[156:159], v[0:15]
	s_waitcnt vmcnt(11)
	ds_write_b128 v105, v[124:127] offset:36864
	v_mfma_f32_32x32x16_bf16 v[48:63], v[148:151], v[152:155], v[48:63]
	s_waitcnt vmcnt(10)
	ds_write_b128 v105, v[128:131] offset:41472
	v_mfma_f32_32x32x16_bf16 v[32:47], v[148:151], v[160:163], v[32:47]
	s_waitcnt vmcnt(9)
	ds_write_b128 v105, v[132:135] offset:46080
	s_waitcnt lgkmcnt(4)
	v_mfma_f32_32x32x16_bf16 v[16:31], v[164:167], v[152:155], v[16:31]
	s_waitcnt vmcnt(8)
	ds_write_b128 v105, v[136:139] offset:50688
	v_mfma_f32_32x32x16_bf16 v[0:15], v[164:167], v[160:163], v[0:15]
	s_setprio 0
	s_waitcnt lgkmcnt(0)
	s_barrier
	s_cbranch_scc1 .LBB0_1817
	s_setprio 1
	ds_read_b128 v[98:101], v103
	ds_read_b128 v[108:111], v104 offset:36864
	ds_read_b128 v[112:115], v103 offset:32
	ds_read_b128 v[116:119], v104 offset:36896
	ds_read_b128 v[120:123], v104 offset:41472
	ds_read_b128 v[124:127], v104 offset:41504
	s_waitcnt lgkmcnt(4)
	v_mfma_f32_32x32x16_bf16 v[48:63], v[98:101], v[108:111], v[48:63]
	s_waitcnt lgkmcnt(1)
	v_mfma_f32_32x32x16_bf16 v[32:47], v[98:101], v[120:123], v[32:47]
	ds_read_b128 v[98:101], v103 offset:4608
	ds_read_b128 v[128:131], v103 offset:4640
	s_waitcnt lgkmcnt(1)
	v_mfma_f32_32x32x16_bf16 v[16:31], v[98:101], v[108:111], v[16:31]
	v_mfma_f32_32x32x16_bf16 v[0:15], v[98:101], v[120:123], v[0:15]
	v_mfma_f32_32x32x16_bf16 v[48:63], v[112:115], v[116:119], v[48:63]
	v_mfma_f32_32x32x16_bf16 v[32:47], v[112:115], v[124:127], v[32:47]
	s_waitcnt lgkmcnt(0)
	v_mfma_f32_32x32x16_bf16 v[16:31], v[128:131], v[116:119], v[16:31]
	ds_read_b128 v[98:101], v103 offset:64
	ds_read_b128 v[108:111], v104 offset:36928
	ds_read_b128 v[112:115], v103 offset:96
	ds_read_b128 v[116:119], v104 offset:36960
	v_mfma_f32_32x32x16_bf16 v[0:15], v[128:131], v[124:127], v[0:15]
	s_waitcnt vmcnt(7)
	ds_write_b128 v105, v[68:71] offset:18432
	ds_read_b128 v[120:123], v104 offset:41536
	ds_read_b128 v[124:127], v104 offset:41568
	s_waitcnt lgkmcnt(5)
	v_mfma_f32_32x32x16_bf16 v[48:63], v[98:101], v[108:111], v[48:63]
	s_waitcnt vmcnt(6)
	ds_write_b128 v105, v[84:87] offset:23040
	s_waitcnt lgkmcnt(2)
	v_mfma_f32_32x32x16_bf16 v[32:47], v[98:101], v[120:123], v[32:47]
	s_waitcnt vmcnt(5)
	ds_write_b128 v105, v[88:91] offset:27648
	ds_read_b128 v[98:101], v103 offset:4672
	ds_read_b128 v[128:131], v103 offset:4704
	s_waitcnt lgkmcnt(1)
	v_mfma_f32_32x32x16_bf16 v[16:31], v[98:101], v[108:111], v[16:31]
	s_waitcnt vmcnt(4)
	ds_write_b128 v105, v[92:95] offset:32256
	v_mfma_f32_32x32x16_bf16 v[0:15], v[98:101], v[120:123], v[0:15]
	s_waitcnt vmcnt(3)
	ds_write_b128 v105, v[64:67] offset:55296
	s_waitcnt lgkmcnt(2)
	v_mfma_f32_32x32x16_bf16 v[16:31], v[128:131], v[116:119], v[16:31]
	s_waitcnt vmcnt(2)
	ds_write_b128 v105, v[72:75] offset:59904
	v_mfma_f32_32x32x16_bf16 v[0:15], v[128:131], v[124:127], v[0:15]
	s_waitcnt vmcnt(1)
	ds_write_b128 v105, v[76:79] offset:64512
	v_mfma_f32_32x32x16_bf16 v[48:63], v[112:115], v[116:119], v[48:63]
	s_waitcnt vmcnt(0)
	ds_write_b128 v106, v[80:83] offset:13824
	v_mfma_f32_32x32x16_bf16 v[32:47], v[112:115], v[124:127], v[32:47]
	s_setprio 0
	s_waitcnt lgkmcnt(0)
	s_barrier
	s_setprio 1
	ds_read_b128 v[64:67], v103 offset:18432
	ds_read_b128 v[68:71], v104 offset:55296
	ds_read_b128 v[72:75], v103 offset:18464
	ds_read_b128 v[76:79], v104 offset:55328
	ds_read_b128 v[80:83], v104 offset:59904
	ds_read_b128 v[84:87], v104 offset:59936
	s_waitcnt lgkmcnt(4)
	v_mfma_f32_32x32x16_bf16 v[48:63], v[64:67], v[68:71], v[48:63]
	s_waitcnt lgkmcnt(1)
	v_mfma_f32_32x32x16_bf16 v[32:47], v[64:67], v[80:83], v[32:47]
	ds_read_b128 v[64:67], v103 offset:23040
	ds_read_b128 v[88:91], v103 offset:23072
	s_waitcnt lgkmcnt(1)
	v_mfma_f32_32x32x16_bf16 v[16:31], v[64:67], v[68:71], v[16:31]
	v_mfma_f32_32x32x16_bf16 v[0:15], v[64:67], v[80:83], v[0:15]
	v_mfma_f32_32x32x16_bf16 v[48:63], v[72:75], v[76:79], v[48:63]
	v_mfma_f32_32x32x16_bf16 v[32:47], v[72:75], v[84:87], v[32:47]
	s_waitcnt lgkmcnt(0)
	v_mfma_f32_32x32x16_bf16 v[16:31], v[88:91], v[76:79], v[16:31]
	ds_read_b128 v[64:67], v103 offset:18496
	ds_read_b128 v[68:71], v104 offset:55360
	ds_read_b128 v[72:75], v103 offset:18528
	ds_read_b128 v[76:79], v104 offset:55392
	v_mfma_f32_32x32x16_bf16 v[0:15], v[88:91], v[84:87], v[0:15]
	ds_read_b128 v[80:83], v104 offset:59968
	ds_read_b128 v[84:87], v104 offset:60000
	s_waitcnt lgkmcnt(4)
	v_mfma_f32_32x32x16_bf16 v[48:63], v[64:67], v[68:71], v[48:63]
	s_waitcnt lgkmcnt(1)
	v_mfma_f32_32x32x16_bf16 v[32:47], v[64:67], v[80:83], v[32:47]
	ds_read_b128 v[64:67], v103 offset:23104
	ds_read_b128 v[88:91], v103 offset:23136
	s_waitcnt lgkmcnt(1)
	v_mfma_f32_32x32x16_bf16 v[16:31], v[64:67], v[68:71], v[16:31]
	v_mfma_f32_32x32x16_bf16 v[0:15], v[64:67], v[80:83], v[0:15]
	s_waitcnt lgkmcnt(0)
	v_mfma_f32_32x32x16_bf16 v[16:31], v[88:91], v[76:79], v[16:31]
	v_mfma_f32_32x32x16_bf16 v[0:15], v[88:91], v[84:87], v[0:15]
	v_mfma_f32_32x32x16_bf16 v[48:63], v[72:75], v[76:79], v[48:63]
	v_mfma_f32_32x32x16_bf16 v[32:47], v[72:75], v[84:87], v[32:47]
	s_setprio 0
	s_addk_i32 s0, 0xf000
	s_lshr_b32 s10, s0, 10
	s_mulk_i32 s10, 0x1800
	s_addk_i32 s10, 0x1800
	s_and_b64 s[22:23], s[8:9], exec
	s_cselect_b32 s10, 0, s10
	v_mov_b32_e32 v68, v234
	s_barrier
	s_lshl_b64 s[22:23], s[10:11], 2
	s_add_u32 s22, s30, s22
	v_and_b32_e32 v69, 0x5f, v68
	v_or_b32_e32 v64, s21, v69
	s_addc_u32 s23, s31, s23
	v_ashrrev_i32_e32 v65, 31, v64
	v_lshl_add_u64 v[64:65], v[64:65], 2, s[22:23]
	v_lshl_add_u64 v[66:67], v[64:65], 0, s[14:15]
	v_add_co_u32_e32 v64, vcc, s54, v64
	v_lshlrev_b32_e32 v69, 2, v69
	s_nop 0
	v_addc_co_u32_e32 v65, vcc, 0, v65, vcc
	global_load_dword v64, v[64:65], off
	s_nop 0
	global_load_dword v65, v[66:67], off offset:128
	v_lshrrev_b32_e32 v67, 3, v68
	v_lshrrev_b32_e32 v66, 1, v68
	v_and_b32_e32 v67, 4, v67
	v_and_or_b32 v66, v66, s45, v67
	v_mul_lo_u32 v66, v66, s55
	v_add3_u32 v66, 32, v69, v66
	v_add_u32_e32 v67, 0x400, v66
	v_add_u32_e32 v69, 0x1000, v66
	v_add_u32_e32 v70, 0x1400, v66
	v_add_u32_e32 v71, 0x2000, v66
	v_add_u32_e32 v72, 0x2400, v66
	v_add_u32_e32 v73, 0x3000, v66
	v_add_u32_e32 v74, 0x3200, v66
	v_add_u32_e32 v75, 0x3400, v66
	v_add_u32_e32 v76, 0x3600, v66
	v_add_u32_e32 v77, 0x4000, v66
	v_readlane_b32 s80, v251, 39
	v_readlane_b32 s81, v251, 40
	s_lshl_b32 s1, s1, 19
	v_readlane_b32 s82, v251, 41
	v_readlane_b32 s83, v251, 42
	s_mov_b64 s[36:37], s[80:81]
	s_add_u32 s10, s36, s1
	s_mov_b32 s1, s11
	s_mov_b64 s[38:39], s[82:83]
	s_addc_u32 s21, s37, 0
	s_lshl_b64 s[0:1], s[0:1], 12
	s_add_u32 s22, s38, s0
	s_addc_u32 s23, s39, s1
	s_and_b64 s[0:1], s[8:9], exec
	s_cselect_b32 s23, s21, s23
	s_cselect_b32 s22, s10, s22
	s_add_i32 s10, s20, s27
	v_readlane_b32 s84, v251, 43
	v_readlane_b32 s85, v251, 44
	v_readlane_b32 s86, v251, 45
	v_readlane_b32 s87, v251, 46
	v_readlane_b32 s88, v251, 47
	v_readlane_b32 s89, v251, 48
	v_readlane_b32 s90, v251, 49
	v_readlane_b32 s91, v251, 50
	v_readlane_b32 s92, v251, 51
	v_readlane_b32 s93, v251, 52
	v_readlane_b32 s94, v251, 53
	v_readlane_b32 s95, v251, 54
	s_waitcnt vmcnt(1)
	v_mul_f32_e32 v48, v48, v64
	s_waitcnt vmcnt(0)
	v_mul_f32_e32 v32, v32, v65
	v_mul_f32_e32 v16, v16, v64
	v_mul_f32_e32 v0, v0, v65
	v_mul_f32_e32 v49, v49, v64
	v_mul_f32_e32 v33, v33, v65
	v_mul_f32_e32 v50, v50, v64
	v_mul_f32_e32 v34, v34, v65
	v_mul_f32_e32 v51, v51, v64
	v_mul_f32_e32 v35, v35, v65
	v_mul_f32_e32 v52, v52, v64
	v_mul_f32_e32 v36, v36, v65
	v_mul_f32_e32 v53, v53, v64
	v_mul_f32_e32 v37, v37, v65
	v_mul_f32_e32 v54, v54, v64
	v_mul_f32_e32 v38, v38, v65
	v_mul_f32_e32 v55, v55, v64
	v_mul_f32_e32 v39, v39, v65
	v_mul_f32_e32 v56, v56, v64
	v_mul_f32_e32 v40, v40, v65
	v_mul_f32_e32 v57, v57, v64
	v_mul_f32_e32 v41, v41, v65
	v_mul_f32_e32 v58, v58, v64
	v_mul_f32_e32 v42, v42, v65
	v_mul_f32_e32 v59, v59, v64
	v_mul_f32_e32 v43, v43, v65
	v_mul_f32_e32 v60, v60, v64
	v_mul_f32_e32 v44, v44, v65
	v_mul_f32_e32 v61, v61, v64
	v_mul_f32_e32 v45, v45, v65
	v_mul_f32_e32 v62, v62, v64
	v_mul_f32_e32 v46, v46, v65
	v_mul_f32_e32 v63, v63, v64
	v_mul_f32_e32 v47, v47, v65
	ds_write2_b32 v66, v48, v32 offset1:32
	ds_write2_b32 v66, v49, v33 offset0:132 offset1:164
	ds_write2_b32 v67, v50, v34 offset0:8 offset1:40
	ds_write2_b32 v67, v51, v35 offset0:140 offset1:172
	ds_write2_b32 v69, v52, v36 offset0:32 offset1:64
	ds_write2_b32 v69, v53, v37 offset0:164 offset1:196
	ds_write2_b32 v70, v54, v38 offset0:40 offset1:72
	ds_write2_b32 v70, v55, v39 offset0:172 offset1:204
	ds_write2_b32 v71, v56, v40 offset0:64 offset1:96
	ds_write2_b32 v71, v57, v41 offset0:196 offset1:228
	ds_write2_b32 v72, v58, v42 offset0:72 offset1:104
	ds_write2_b32 v72, v59, v43 offset0:204 offset1:236
	ds_write2_b32 v73, v60, v44 offset0:96 offset1:128
	ds_write2_b32 v74, v61, v45 offset0:100 offset1:132
	ds_write2_b32 v75, v62, v46 offset0:104 offset1:136
	ds_write2_b32 v76, v63, v47 offset0:108 offset1:140
	ds_write2_b32 v77, v16, v0 offset0:128 offset1:160
	v_mul_f32_e32 v0, v17, v64
	v_mul_f32_e32 v1, v1, v65
	v_add_u32_e32 v16, 0x4400, v66
	ds_write2_b32 v16, v0, v1 offset0:4 offset1:36
	v_mul_f32_e32 v0, v18, v64
	v_mul_f32_e32 v1, v2, v65
	ds_write2_b32 v16, v0, v1 offset0:136 offset1:168
	v_mul_f32_e32 v0, v19, v64
	v_mul_f32_e32 v1, v3, v65
	v_add_u32_e32 v2, 0x4800, v66
	ds_write2_b32 v2, v0, v1 offset0:12 offset1:44
	v_mul_f32_e32 v0, v20, v64
	v_mul_f32_e32 v1, v4, v65
	v_add_u32_e32 v2, 0x5000, v66
	ds_write2_b32 v2, v0, v1 offset0:160 offset1:192
	v_mul_f32_e32 v0, v21, v64
	v_mul_f32_e32 v1, v5, v65
	v_add_u32_e32 v2, 0x5400, v66
	ds_write2_b32 v2, v0, v1 offset0:36 offset1:68
	v_mul_f32_e32 v0, v22, v64
	v_mul_f32_e32 v1, v6, v65
	ds_write2_b32 v2, v0, v1 offset0:168 offset1:200
	v_mul_f32_e32 v0, v23, v64
	v_mul_f32_e32 v1, v7, v65
	v_add_u32_e32 v2, 0x5800, v66
	ds_write2_b32 v2, v0, v1 offset0:44 offset1:76
	v_mul_f32_e32 v0, v24, v64
	v_mul_f32_e32 v1, v8, v65
	v_add_u32_e32 v2, 0x6000, v66
	ds_write2_b32 v2, v0, v1 offset0:192 offset1:224
	v_mul_f32_e32 v0, v25, v64
	v_mul_f32_e32 v1, v9, v65
	v_add_u32_e32 v2, 0x6400, v66
	ds_write2_b32 v2, v0, v1 offset0:68 offset1:100
	v_mul_f32_e32 v0, v26, v64
	v_mul_f32_e32 v1, v10, v65
	ds_write2_b32 v2, v0, v1 offset0:200 offset1:232
	v_mul_f32_e32 v0, v27, v64
	v_mul_f32_e32 v1, v11, v65
	v_add_u32_e32 v2, 0x6800, v66
	ds_write2_b32 v2, v0, v1 offset0:76 offset1:108
	v_mul_f32_e32 v0, v28, v64
	v_mul_f32_e32 v1, v12, v65
	v_add_u32_e32 v2, 0x7200, v66
	ds_write2_b32 v2, v0, v1 offset0:96 offset1:128
	v_mul_f32_e32 v0, v29, v64
	v_mul_f32_e32 v1, v13, v65
	v_add_u32_e32 v2, 0x7400, v66
	ds_write2_b32 v2, v0, v1 offset0:100 offset1:132
	v_mul_f32_e32 v0, v30, v64
	v_mul_f32_e32 v1, v14, v65
	v_add_u32_e32 v2, 0x7600, v66
	ds_write2_b32 v2, v0, v1 offset0:104 offset1:136
	v_mul_f32_e32 v0, v31, v64
	v_mul_f32_e32 v1, v15, v65
	v_add_u32_e32 v2, 0x7800, v66
	ds_write2_b32 v2, v0, v1 offset0:108 offset1:140
	v_and_b32_e32 v0, 64, v102
	v_add_u32_e32 v0, 64, v0
	v_xor_b32_e32 v1, 1, v102
	v_cmp_lt_i32_e32 vcc, v1, v0
	v_and_b32_e32 v4, 31, v68
	v_lshl_add_u32 v2, v4, 2, s18
	v_cndmask_b32_e32 v1, v102, v1, vcc
	v_lshlrev_b32_e32 v20, 2, v1
	v_xor_b32_e32 v1, 2, v102
	v_cmp_lt_i32_e32 vcc, v1, v0
	v_ashrrev_i32_e32 v14, 5, v68
	v_ashrrev_i32_e32 v3, 31, v2
	v_cndmask_b32_e32 v1, v102, v1, vcc
	v_lshlrev_b32_e32 v21, 2, v1
	v_xor_b32_e32 v1, 4, v102
	v_cmp_lt_i32_e32 vcc, v1, v0
	v_cmp_eq_u32_e64 s[0:1], 0, v4
	v_lshlrev_b64 v[16:17], 2, v[2:3]
	v_cndmask_b32_e32 v1, v102, v1, vcc
	v_lshlrev_b32_e32 v22, 2, v1
	v_xor_b32_e32 v1, 8, v102
	v_cmp_lt_i32_e32 vcc, v1, v0
	v_lshlrev_b32_e32 v3, 4, v4
	v_add_u32_e32 v4, s10, v14
	v_cndmask_b32_e32 v1, v102, v1, vcc
	v_lshlrev_b32_e32 v23, 2, v1
	v_xor_b32_e32 v1, 16, v102
	s_add_i32 s10, s20, s33
	s_add_i32 s20, s20, s34
	v_cmp_lt_i32_e32 vcc, v1, v0
	v_add_u32_e32 v8, s10, v14
	v_add_u32_e32 v12, s20, v14
	v_add_u32_e32 v18, s19, v14
	v_cndmask_b32_e32 v0, v102, v1, vcc
	v_ashrrev_i32_e32 v15, 31, v14
	v_mul_lo_u32 v2, v14, s55
	v_ashrrev_i32_e32 v5, 31, v4
	v_ashrrev_i32_e32 v9, 31, v8
	v_ashrrev_i32_e32 v13, 31, v12
	v_ashrrev_i32_e32 v19, 31, v18
	v_lshlrev_b32_e32 v24, 2, v0
	v_lshlrev_b64 v[0:1], 12, v[14:15]
	v_add3_u32 v25, v2, v3, 32
	v_lshlrev_b32_e32 v2, 1, v4
	v_lshlrev_b64 v[4:5], 12, v[4:5]
	v_lshlrev_b32_e32 v6, 1, v8
	v_lshlrev_b64 v[8:9], 12, v[8:9]
	v_lshlrev_b32_e32 v10, 1, v12
	v_lshlrev_b64 v[12:13], 12, v[12:13]
	v_lshlrev_b64 v[14:15], 12, v[18:19]
	v_lshl_add_u64 v[0:1], v[0:1], 0, v[16:17]
	v_lshl_add_u64 v[4:5], v[4:5], 0, v[16:17]
	v_lshl_add_u64 v[8:9], v[8:9], 0, v[16:17]
	v_lshl_add_u64 v[12:13], v[12:13], 0, v[16:17]
	v_lshl_add_u64 v[14:15], v[14:15], 0, v[16:17]
	v_lshlrev_b32_e32 v16, 1, v18
	v_ashrrev_i32_e32 v3, 31, v2
	v_ashrrev_i32_e32 v7, 31, v6
	v_ashrrev_i32_e32 v11, 31, v10
	v_ashrrev_i32_e32 v17, 31, v16
	v_lshl_add_u64 v[0:1], s[22:23], 0, v[0:1]
	v_lshlrev_b64 v[2:3], 2, v[2:3]
	v_lshl_add_u64 v[4:5], s[30:31], 0, v[4:5]
	v_lshlrev_b64 v[6:7], 2, v[6:7]
	v_lshl_add_u64 v[8:9], s[30:31], 0, v[8:9]
	v_lshlrev_b64 v[10:11], 2, v[10:11]
	v_lshl_add_u64 v[12:13], s[30:31], 0, v[12:13]
	v_lshl_add_u64 v[14:15], s[30:31], 0, v[14:15]
	v_lshlrev_b64 v[16:17], 2, v[16:17]
	s_mov_b64 s[18:19], 0
	s_mov_b64 s[20:21], s[30:31]
	s_waitcnt lgkmcnt(0)
	s_barrier
	s_branch .LBB0_1820

.LBB0_1938:
	s_ashr_i32 s41, s40, 3
	s_add_i32 s10, s41, s38
	s_cmp_gt_i32 s10, 43
	s_cbranch_scc1 .LBB0_1937
	s_and_b32 s11, s40, 7
	v_mov_b32_e32 v102, v234
	s_waitcnt vmcnt(6)
	v_mov_b32_e32 v33, v234
	s_or_b32 s11, s11, s15
	s_lshl_b32 s10, s10, 7
	v_ashrrev_i32_e32 v32, 3, v33
	v_lshl_add_u32 v0, s11, 7, v32
	v_ashrrev_i32_e32 v1, 31, v0
	v_lshlrev_b64 v[0:1], 11, v[0:1]
	v_lshlrev_b32_e32 v2, 4, v33
	v_lshl_add_u64 v[0:1], s[4:5], 0, v[0:1]
	v_and_b32_e32 v96, 0x70, v2
	s_waitcnt vmcnt(5)
	v_lshl_add_u64 v[34:35], v[0:1], 0, v[96:97]
	s_waitcnt vmcnt(4)
	v_add_co_u32_e32 v38, vcc, s18, v34
	v_add_u32_e32 v0, s10, v32
	s_nop 0
	v_addc_co_u32_e32 v39, vcc, 0, v35, vcc
	v_ashrrev_i32_e32 v1, 31, v0
	v_add_co_u32_e32 v40, vcc, s19, v34
	v_lshlrev_b64 v[0:1], 11, v[0:1]
	s_nop 0
	v_addc_co_u32_e32 v41, vcc, 0, v35, vcc
	v_lshl_add_u64 v[0:1], s[6:7], 0, v[0:1]
	v_add_co_u32_e32 v42, vcc, s20, v34
	v_lshl_add_u64 v[36:37], v[0:1], 0, v[96:97]
	s_nop 0
	v_addc_co_u32_e32 v43, vcc, 0, v35, vcc
	v_add_co_u32_e32 v44, vcc, s18, v36
	s_waitcnt lgkmcnt(0)
	s_nop 0
	v_addc_co_u32_e32 v45, vcc, 0, v37, vcc
	v_add_co_u32_e32 v46, vcc, s19, v36
	s_barrier
	s_nop 0
	v_addc_co_u32_e32 v47, vcc, 0, v37, vcc
	v_add_co_u32_e32 v48, vcc, s20, v36
	global_load_dwordx4 v[0:3], v[34:35], off
	global_load_dwordx4 v[4:7], v[38:39], off
	global_load_dwordx4 v[8:11], v[40:41], off
	global_load_dwordx4 v[12:15], v[42:43], off
	global_load_dwordx4 v[16:19], v[36:37], off
	v_addc_co_u32_e32 v49, vcc, 0, v37, vcc
	global_load_dwordx4 v[20:23], v[44:45], off
	global_load_dwordx4 v[24:27], v[46:47], off
	global_load_dwordx4 v[28:31], v[48:49], off
	global_load_dwordx4 v[68:71], v[34:35], off offset:128
	global_load_dwordx4 v[64:67], v[36:37], off offset:128
	global_load_dwordx4 v[84:87], v[38:39], off offset:128
	global_load_dwordx4 v[88:91], v[40:41], off offset:128
	global_load_dwordx4 v[92:95], v[42:43], off offset:128
	global_load_dwordx4 v[72:75], v[44:45], off offset:128
	global_load_dwordx4 v[76:79], v[46:47], off offset:128
	global_load_dwordx4 v[80:83], v[48:49], off offset:128
	s_and_b32 s44, s39, 7
	s_add_i32 s41, s16, s41
	s_lshl_b32 s46, s44, 7
	v_lshrrev_b32_e32 v50, 1, v33
	v_and_b32_e32 v51, 31, v33
	v_and_b32_e32 v52, 0x5f, v33
	v_and_b32_e32 v33, 7, v33
	v_mul_lo_u32 v53, v32, s21
	s_lshl_b32 s44, s41, 7
	v_add3_u32 v105, 32, v53, v96
	v_lshlrev_b32_e32 v96, 4, v33
	v_ashrrev_i32_e32 v33, 31, v32
	s_ashr_i32 s45, s44, 31
	s_add_i32 s46, s46, s17
	v_and_or_b32 v51, v50, s22, v51
	v_mul_u32_u24_e32 v52, 0x48, v52
	v_and_b32_e32 v50, 16, v50
	v_mul_lo_u32 v51, v51, s21
	v_lshlrev_b32_e32 v52, 1, v52
	v_add3_u32 v103, 32, v51, v50
	v_add3_u32 v104, 32, v52, v50
	v_add_u32_e32 v106, 0xd800, v105
	s_mov_b32 s41, -2
	s_waitcnt vmcnt(15)
	ds_write_b128 v105, v[0:3]
	s_waitcnt vmcnt(11)
	ds_write_b128 v105, v[16:19] offset:36864
	ds_write_b128 v105, v[4:7] offset:4608
	ds_write_b128 v105, v[8:11] offset:9216
	ds_write_b128 v105, v[12:15] offset:13824
	s_waitcnt vmcnt(10)
	ds_write_b128 v105, v[20:23] offset:41472
	s_waitcnt vmcnt(9)
	ds_write_b128 v105, v[24:27] offset:46080
	s_waitcnt vmcnt(8)
	ds_write_b128 v105, v[28:31] offset:50688
	v_lshl_add_u64 v[0:1], v[32:33], 0, s[44:45]
	v_lshlrev_b64 v[0:1], 11, v[0:1]
	v_lshl_add_u64 v[98:99], s[30:31], 0, v[0:1]
	v_add_u32_e32 v0, s46, v32
	v_ashrrev_i32_e32 v1, 31, v0
	v_lshlrev_b64 v[0:1], 11, v[0:1]
	v_lshl_add_u64 v[100:101], s[30:31], 0, v[0:1]
	v_mov_b32_e32 v0, 0
	v_mov_b32_e32 v1, v0
	v_mov_b32_e32 v2, v0
	v_mov_b32_e32 v3, v0
	v_mov_b32_e32 v4, v0
	v_mov_b32_e32 v5, v0
	v_mov_b32_e32 v6, v0
	v_mov_b32_e32 v7, v0
	v_mov_b32_e32 v8, v0
	v_mov_b32_e32 v9, v0
	v_mov_b32_e32 v10, v0
	v_mov_b32_e32 v11, v0
	v_mov_b32_e32 v12, v0
	v_mov_b32_e32 v13, v0
	v_mov_b32_e32 v14, v0
	v_mov_b32_e32 v15, v0
	v_mov_b32_e32 v16, v0
	v_mov_b32_e32 v17, v0
	v_mov_b32_e32 v18, v0
	v_mov_b32_e32 v19, v0
	v_mov_b32_e32 v20, v0
	v_mov_b32_e32 v21, v0
	v_mov_b32_e32 v22, v0
	v_mov_b32_e32 v23, v0
	v_mov_b32_e32 v24, v0
	v_mov_b32_e32 v25, v0
	v_mov_b32_e32 v26, v0
	v_mov_b32_e32 v27, v0
	v_mov_b32_e32 v28, v0
	v_mov_b32_e32 v29, v0
	v_mov_b32_e32 v30, v0
	v_mov_b32_e32 v31, v0
	v_mov_b32_e32 v32, v0
	v_mov_b32_e32 v33, v0
	v_mov_b32_e32 v34, v0
	v_mov_b32_e32 v35, v0
	v_mov_b32_e32 v36, v0
	v_mov_b32_e32 v37, v0
	v_mov_b32_e32 v38, v0
	v_mov_b32_e32 v39, v0
	v_mov_b32_e32 v40, v0
	v_mov_b32_e32 v41, v0
	v_mov_b32_e32 v42, v0
	v_mov_b32_e32 v43, v0
	v_mov_b32_e32 v44, v0
	v_mov_b32_e32 v45, v0
	v_mov_b32_e32 v46, v0
	v_mov_b32_e32 v47, v0
	v_mov_b32_e32 v48, v0
	v_mov_b32_e32 v49, v0
	v_mov_b32_e32 v50, v0
	v_mov_b32_e32 v51, v0
	v_mov_b32_e32 v52, v0
	v_mov_b32_e32 v53, v0
	v_mov_b32_e32 v54, v0
	v_mov_b32_e32 v55, v0
	v_mov_b32_e32 v56, v0
	v_mov_b32_e32 v57, v0
	v_mov_b32_e32 v58, v0
	v_mov_b32_e32 v59, v0
	v_mov_b32_e32 v60, v0
	v_mov_b32_e32 v61, v0
	v_mov_b32_e32 v62, v0
	v_mov_b32_e32 v63, v0
	v_lshl_add_u64 v[116:117], v[100:101], 0, v[96:97]
	v_add_co_u32_e32 v168, vcc, s23, v116
	v_lshl_add_u64 v[132:133], v[98:99], 0, v[96:97]
	s_nop 0
	v_addc_co_u32_e32 v169, vcc, 0, v117, vcc
	v_add_co_u32_e32 v170, vcc, s24, v116
	s_nop 1
	v_addc_co_u32_e32 v171, vcc, 0, v117, vcc
	v_add_co_u32_e32 v172, vcc, s25, v116
	s_nop 1
	v_addc_co_u32_e32 v173, vcc, 0, v117, vcc
	v_add_co_u32_e32 v174, vcc, s26, v116
	s_nop 1
	v_addc_co_u32_e32 v175, vcc, 0, v117, vcc
	v_add_co_u32_e32 v176, vcc, s27, v132
	s_nop 1
	v_addc_co_u32_e32 v177, vcc, 0, v133, vcc
	v_add_co_u32_e32 v178, vcc, s33, v132
	s_nop 1
	v_addc_co_u32_e32 v179, vcc, 0, v133, vcc
	v_add_co_u32_e32 v180, vcc, s34, v132
	s_nop 1
	v_addc_co_u32_e32 v181, vcc, 0, v133, vcc
	v_add_co_u32_e32 v182, vcc, s35, v132
	s_nop 1
	v_addc_co_u32_e32 v183, vcc, 0, v133, vcc
	v_subrev_u32_e32 v168, s30, v168
	v_subrev_u32_e32 v170, s30, v170
	v_subrev_u32_e32 v172, s30, v172
	v_subrev_u32_e32 v174, s30, v174
	v_subrev_u32_e32 v176, s30, v176
	v_subrev_u32_e32 v178, s30, v178
	v_subrev_u32_e32 v180, s30, v180
	v_subrev_u32_e32 v182, s30, v182
	s_mov_b64 s[98:99], s[30:31]
	s_waitcnt lgkmcnt(0)
	s_barrier
.LBB0_1940:
	s_setprio 1
	ds_read_b128 v[140:143], v103
	ds_read_b128 v[144:147], v104 offset:36864
	ds_read_b128 v[148:151], v103 offset:32
	ds_read_b128 v[152:155], v104 offset:36896
	ds_read_b128 v[156:159], v104 offset:41472
	ds_read_b128 v[160:163], v104 offset:41504
	s_waitcnt lgkmcnt(4)
	v_mfma_f32_32x32x16_bf16 v[48:63], v[140:143], v[144:147], v[48:63]
	global_load_dwordx4 v[108:111], v168, s[98:99] offset:3840
	global_load_dwordx4 v[112:115], v170, s[98:99] offset:3840
	s_waitcnt lgkmcnt(1)
	v_mfma_f32_32x32x16_bf16 v[32:47], v[140:143], v[156:159], v[32:47]
	global_load_dwordx4 v[116:119], v172, s[98:99] offset:3840
	global_load_dwordx4 v[120:123], v174, s[98:99] offset:3840
	ds_read_b128 v[140:143], v103 offset:4608
	ds_read_b128 v[164:167], v103 offset:4640
	s_waitcnt lgkmcnt(1)
	v_mfma_f32_32x32x16_bf16 v[16:31], v[140:143], v[144:147], v[16:31]
	global_load_dwordx4 v[124:127], v176, s[98:99] offset:3840
	global_load_dwordx4 v[128:131], v178, s[98:99] offset:3840
	v_mfma_f32_32x32x16_bf16 v[0:15], v[140:143], v[156:159], v[0:15]
	global_load_dwordx4 v[132:135], v180, s[98:99] offset:3840
	global_load_dwordx4 v[136:139], v182, s[98:99] offset:3840
	v_mfma_f32_32x32x16_bf16 v[48:63], v[148:151], v[152:155], v[48:63]
	v_mfma_f32_32x32x16_bf16 v[32:47], v[148:151], v[160:163], v[32:47]
	s_waitcnt lgkmcnt(0)
	v_mfma_f32_32x32x16_bf16 v[16:31], v[164:167], v[152:155], v[16:31]
	ds_read_b128 v[140:143], v103 offset:64
	ds_read_b128 v[144:147], v104 offset:36928
	ds_read_b128 v[148:151], v103 offset:96
	ds_read_b128 v[152:155], v104 offset:36960
	v_mfma_f32_32x32x16_bf16 v[0:15], v[164:167], v[160:163], v[0:15]
	s_waitcnt vmcnt(15)
	ds_write_b128 v105, v[68:71] offset:18432
	ds_read_b128 v[156:159], v104 offset:41536
	ds_read_b128 v[160:163], v104 offset:41568
	s_waitcnt lgkmcnt(5)
	v_mfma_f32_32x32x16_bf16 v[48:63], v[140:143], v[144:147], v[48:63]
	s_waitcnt vmcnt(13)
	ds_write_b128 v105, v[84:87] offset:23040
	s_waitcnt lgkmcnt(2)
	v_mfma_f32_32x32x16_bf16 v[32:47], v[140:143], v[156:159], v[32:47]
	s_waitcnt vmcnt(12)
	ds_write_b128 v105, v[88:91] offset:27648
	ds_read_b128 v[140:143], v103 offset:4672
	ds_read_b128 v[164:167], v103 offset:4704
	s_waitcnt lgkmcnt(1)
	v_mfma_f32_32x32x16_bf16 v[16:31], v[140:143], v[144:147], v[16:31]
	s_waitcnt vmcnt(11)
	ds_write_b128 v105, v[92:95] offset:32256
	v_mfma_f32_32x32x16_bf16 v[0:15], v[140:143], v[156:159], v[0:15]
	ds_write_b128 v105, v[64:67] offset:55296
	v_mfma_f32_32x32x16_bf16 v[48:63], v[148:151], v[152:155], v[48:63]
	s_waitcnt vmcnt(10)
	ds_write_b128 v105, v[72:75] offset:59904
	v_mfma_f32_32x32x16_bf16 v[32:47], v[148:151], v[160:163], v[32:47]
	s_waitcnt vmcnt(9)
	ds_write_b128 v105, v[76:79] offset:64512
	s_waitcnt lgkmcnt(4)
	v_mfma_f32_32x32x16_bf16 v[16:31], v[164:167], v[152:155], v[16:31]
	s_waitcnt vmcnt(8)
	ds_write_b128 v106, v[80:83] offset:13824
	v_mfma_f32_32x32x16_bf16 v[0:15], v[164:167], v[160:163], v[0:15]
	s_setprio 0
	s_waitcnt lgkmcnt(0)
	s_barrier
	s_setprio 1
	ds_read_b128 v[140:143], v103 offset:18432
	ds_read_b128 v[144:147], v104 offset:55296
	ds_read_b128 v[148:151], v103 offset:18464
	ds_read_b128 v[152:155], v104 offset:55328
	ds_read_b128 v[156:159], v104 offset:59904
	ds_read_b128 v[160:163], v104 offset:59936
	s_waitcnt lgkmcnt(4)
	v_mfma_f32_32x32x16_bf16 v[48:63], v[140:143], v[144:147], v[48:63]
	global_load_dwordx4 v[68:71], v168, s[98:99] offset:3968
	global_load_dwordx4 v[84:87], v170, s[98:99] offset:3968
	s_waitcnt lgkmcnt(1)
	v_mfma_f32_32x32x16_bf16 v[32:47], v[140:143], v[156:159], v[32:47]
	global_load_dwordx4 v[88:91], v172, s[98:99] offset:3968
	global_load_dwordx4 v[92:95], v174, s[98:99] offset:3968
	ds_read_b128 v[140:143], v103 offset:23040
	ds_read_b128 v[164:167], v103 offset:23072
	s_waitcnt lgkmcnt(1)
	v_mfma_f32_32x32x16_bf16 v[16:31], v[140:143], v[144:147], v[16:31]
	global_load_dwordx4 v[64:67], v176, s[98:99] offset:3968
	global_load_dwordx4 v[72:75], v178, s[98:99] offset:3968
	v_mfma_f32_32x32x16_bf16 v[0:15], v[140:143], v[156:159], v[0:15]
	global_load_dwordx4 v[76:79], v180, s[98:99] offset:3968
	global_load_dwordx4 v[80:83], v182, s[98:99] offset:3968
	v_mfma_f32_32x32x16_bf16 v[48:63], v[148:151], v[152:155], v[48:63]
	v_mfma_f32_32x32x16_bf16 v[32:47], v[148:151], v[160:163], v[32:47]
	s_waitcnt lgkmcnt(0)
	v_mfma_f32_32x32x16_bf16 v[16:31], v[164:167], v[152:155], v[16:31]
	ds_read_b128 v[140:143], v103 offset:18496
	ds_read_b128 v[144:147], v104 offset:55360
	ds_read_b128 v[148:151], v103 offset:18528
	ds_read_b128 v[152:155], v104 offset:55392
	v_mfma_f32_32x32x16_bf16 v[0:15], v[164:167], v[160:163], v[0:15]
	s_add_u32 s98, s98, 0x100
	s_addc_u32 s99, s99, 0
	s_add_i32 s41, s41, 2
	s_cmp_lt_u32 s41, 11
	s_waitcnt vmcnt(15)
	ds_write_b128 v105, v[108:111]
	ds_read_b128 v[156:159], v104 offset:59968
	ds_read_b128 v[160:163], v104 offset:60000
	s_waitcnt lgkmcnt(5)
	v_mfma_f32_32x32x16_bf16 v[48:63], v[140:143], v[144:147], v[48:63]
	s_waitcnt vmcnt(14)
	ds_write_b128 v105, v[112:115] offset:4608
	s_waitcnt lgkmcnt(2)
	v_mfma_f32_32x32x16_bf16 v[32:47], v[140:143], v[156:159], v[32:47]
	s_waitcnt vmcnt(13)
	ds_write_b128 v105, v[116:119] offset:9216
	ds_read_b128 v[140:143], v103 offset:23104
	ds_read_b128 v[164:167], v103 offset:23136
	s_waitcnt lgkmcnt(1)
	v_mfma_f32_32x32x16_bf16 v[16:31], v[140:143], v[144:147], v[16:31]
	s_waitcnt vmcnt(12)
	ds_write_b128 v105, v[120:123] offset:13824
	v_mfma_f32_32x32x16_bf16 v[0:15], v[140:143], v[156:159], v[0:15]
	s_waitcnt vmcnt(11)
	ds_write_b128 v105, v[124:127] offset:36864
	v_mfma_f32_32x32x16_bf16 v[48:63], v[148:151], v[152:155], v[48:63]
	s_waitcnt vmcnt(10)
	ds_write_b128 v105, v[128:131] offset:41472
	v_mfma_f32_32x32x16_bf16 v[32:47], v[148:151], v[160:163], v[32:47]
	s_waitcnt vmcnt(9)
	ds_write_b128 v105, v[132:135] offset:46080
	s_waitcnt lgkmcnt(4)
	v_mfma_f32_32x32x16_bf16 v[16:31], v[164:167], v[152:155], v[16:31]
	s_waitcnt vmcnt(8)
	ds_write_b128 v105, v[136:139] offset:50688
	v_mfma_f32_32x32x16_bf16 v[0:15], v[164:167], v[160:163], v[0:15]
	s_setprio 0
	s_waitcnt lgkmcnt(0)
	s_barrier
	s_cbranch_scc1 .LBB0_1940
	s_setprio 1
	ds_read_b128 v[98:101], v103
	ds_read_b128 v[108:111], v104 offset:36864
	ds_read_b128 v[112:115], v103 offset:32
	ds_read_b128 v[116:119], v104 offset:36896
	ds_read_b128 v[120:123], v104 offset:41472
	ds_read_b128 v[124:127], v104 offset:41504
	s_waitcnt lgkmcnt(4)
	v_mfma_f32_32x32x16_bf16 v[48:63], v[98:101], v[108:111], v[48:63]
	s_waitcnt lgkmcnt(1)
	v_mfma_f32_32x32x16_bf16 v[32:47], v[98:101], v[120:123], v[32:47]
	ds_read_b128 v[98:101], v103 offset:4608
	ds_read_b128 v[128:131], v103 offset:4640
	s_waitcnt lgkmcnt(1)
	v_mfma_f32_32x32x16_bf16 v[16:31], v[98:101], v[108:111], v[16:31]
	v_mfma_f32_32x32x16_bf16 v[0:15], v[98:101], v[120:123], v[0:15]
	v_mfma_f32_32x32x16_bf16 v[48:63], v[112:115], v[116:119], v[48:63]
	v_mfma_f32_32x32x16_bf16 v[32:47], v[112:115], v[124:127], v[32:47]
	s_waitcnt lgkmcnt(0)
	v_mfma_f32_32x32x16_bf16 v[16:31], v[128:131], v[116:119], v[16:31]
	ds_read_b128 v[98:101], v103 offset:64
	ds_read_b128 v[108:111], v104 offset:36928
	ds_read_b128 v[112:115], v103 offset:96
	ds_read_b128 v[116:119], v104 offset:36960
	v_mfma_f32_32x32x16_bf16 v[0:15], v[128:131], v[124:127], v[0:15]
	s_waitcnt vmcnt(7)
	ds_write_b128 v105, v[68:71] offset:18432
	ds_read_b128 v[120:123], v104 offset:41536
	ds_read_b128 v[124:127], v104 offset:41568
	s_waitcnt lgkmcnt(5)
	v_mfma_f32_32x32x16_bf16 v[48:63], v[98:101], v[108:111], v[48:63]
	s_waitcnt vmcnt(6)
	ds_write_b128 v105, v[84:87] offset:23040
	s_waitcnt lgkmcnt(2)
	v_mfma_f32_32x32x16_bf16 v[32:47], v[98:101], v[120:123], v[32:47]
	s_waitcnt vmcnt(5)
	ds_write_b128 v105, v[88:91] offset:27648
	ds_read_b128 v[98:101], v103 offset:4672
	ds_read_b128 v[128:131], v103 offset:4704
	s_waitcnt lgkmcnt(1)
	v_mfma_f32_32x32x16_bf16 v[16:31], v[98:101], v[108:111], v[16:31]
	s_waitcnt vmcnt(4)
	ds_write_b128 v105, v[92:95] offset:32256
	v_mfma_f32_32x32x16_bf16 v[0:15], v[98:101], v[120:123], v[0:15]
	s_waitcnt vmcnt(3)
	ds_write_b128 v105, v[64:67] offset:55296
	v_mfma_f32_32x32x16_bf16 v[48:63], v[112:115], v[116:119], v[48:63]
	s_waitcnt vmcnt(2)
	ds_write_b128 v105, v[72:75] offset:59904
	v_mfma_f32_32x32x16_bf16 v[32:47], v[112:115], v[124:127], v[32:47]
	s_waitcnt vmcnt(1)
	ds_write_b128 v105, v[76:79] offset:64512
	s_waitcnt lgkmcnt(4)
	v_mfma_f32_32x32x16_bf16 v[16:31], v[128:131], v[116:119], v[16:31]
	s_waitcnt vmcnt(0)
	ds_write_b128 v106, v[80:83] offset:13824
	v_mfma_f32_32x32x16_bf16 v[0:15], v[128:131], v[124:127], v[0:15]
	s_setprio 0
	s_waitcnt lgkmcnt(0)
	s_barrier
	s_setprio 1
	ds_read_b128 v[64:67], v103 offset:18432
	ds_read_b128 v[68:71], v104 offset:55296
	ds_read_b128 v[72:75], v103 offset:18464
	ds_read_b128 v[76:79], v104 offset:55328
	ds_read_b128 v[80:83], v104 offset:59904
	ds_read_b128 v[84:87], v104 offset:59936
	s_waitcnt lgkmcnt(4)
	v_mfma_f32_32x32x16_bf16 v[48:63], v[64:67], v[68:71], v[48:63]
	s_waitcnt lgkmcnt(1)
	v_mfma_f32_32x32x16_bf16 v[32:47], v[64:67], v[80:83], v[32:47]
	ds_read_b128 v[64:67], v103 offset:23040
	ds_read_b128 v[88:91], v103 offset:23072
	s_waitcnt lgkmcnt(1)
	v_mfma_f32_32x32x16_bf16 v[16:31], v[64:67], v[68:71], v[16:31]
	v_mfma_f32_32x32x16_bf16 v[0:15], v[64:67], v[80:83], v[0:15]
	v_mfma_f32_32x32x16_bf16 v[48:63], v[72:75], v[76:79], v[48:63]
	v_mfma_f32_32x32x16_bf16 v[32:47], v[72:75], v[84:87], v[32:47]
	s_waitcnt lgkmcnt(0)
	v_mfma_f32_32x32x16_bf16 v[16:31], v[88:91], v[76:79], v[16:31]
	ds_read_b128 v[64:67], v103 offset:18496
	ds_read_b128 v[68:71], v104 offset:55360
	ds_read_b128 v[72:75], v103 offset:18528
	ds_read_b128 v[76:79], v104 offset:55392
	v_mfma_f32_32x32x16_bf16 v[0:15], v[88:91], v[84:87], v[0:15]
	ds_read_b128 v[80:83], v104 offset:59968
	ds_read_b128 v[84:87], v104 offset:60000
	s_waitcnt lgkmcnt(4)
	v_mfma_f32_32x32x16_bf16 v[48:63], v[64:67], v[68:71], v[48:63]
	s_waitcnt lgkmcnt(1)
	v_mfma_f32_32x32x16_bf16 v[32:47], v[64:67], v[80:83], v[32:47]
	ds_read_b128 v[64:67], v103 offset:23104
	ds_read_b128 v[88:91], v103 offset:23136
	s_waitcnt lgkmcnt(1)
	v_mfma_f32_32x32x16_bf16 v[16:31], v[64:67], v[68:71], v[16:31]
	v_mfma_f32_32x32x16_bf16 v[0:15], v[64:67], v[80:83], v[0:15]
	v_mfma_f32_32x32x16_bf16 v[48:63], v[72:75], v[76:79], v[48:63]
	v_mfma_f32_32x32x16_bf16 v[32:47], v[72:75], v[84:87], v[32:47]
	s_waitcnt lgkmcnt(0)
	v_mfma_f32_32x32x16_bf16 v[16:31], v[88:91], v[76:79], v[16:31]
	v_mfma_f32_32x32x16_bf16 v[0:15], v[88:91], v[84:87], v[0:15]
	s_setprio 0
	v_lshrrev_b32_e32 v65, 3, v102
	v_lshrrev_b32_e32 v64, 1, v102
	v_and_b32_e32 v65, 4, v65
	v_and_or_b32 v64, v64, s22, v65
	v_and_b32_e32 v65, 0x5f, v102
	v_lshlrev_b32_e32 v65, 1, v65
	v_mul_lo_u32 v64, v64, s36
	v_add3_u32 v64, 32, v65, v64
	s_nop 2
	v_cvt_pk_bf16_f32 v0, v0, s0
	s_barrier
	ds_write_b16 v64, v0 offset:8768
	v_cvt_pk_bf16_f32 v0, v17, s0
	ds_write_b16 v64, v0 offset:8976
	v_cvt_pk_bf16_f32 v0, v1, s0
	ds_write_b16 v64, v0 offset:9040
	v_cvt_pk_bf16_f32 v0, v18, s0
	v_cvt_pk_bf16_f32 v32, v32, s0
	ds_write_b16 v64, v0 offset:9248
	v_cvt_pk_bf16_f32 v0, v2, s0
	ds_write_b16 v64, v32 offset:64
	v_cvt_pk_bf16_f32 v32, v49, s0
	ds_write_b16 v64, v0 offset:9312
	v_cvt_pk_bf16_f32 v0, v19, s0
	ds_write_b16 v64, v32 offset:272
	v_cvt_pk_bf16_f32 v32, v33, s0
	ds_write_b16 v64, v0 offset:9520
	v_cvt_pk_bf16_f32 v0, v3, s0
	ds_write_b16 v64, v32 offset:336
	v_cvt_pk_bf16_f32 v32, v50, s0
	ds_write_b16 v64, v0 offset:9584
	v_cvt_pk_bf16_f32 v0, v20, s0
	ds_write_b16 v64, v32 offset:544
	v_cvt_pk_bf16_f32 v32, v34, s0
	ds_write_b16 v64, v0 offset:10880
	v_cvt_pk_bf16_f32 v0, v4, s0
	ds_write_b16 v64, v32 offset:608
	v_cvt_pk_bf16_f32 v32, v51, s0
	ds_write_b16 v64, v0 offset:10944
	v_cvt_pk_bf16_f32 v0, v21, s0
	ds_write_b16 v64, v32 offset:816
	v_cvt_pk_bf16_f32 v32, v35, s0
	ds_write_b16 v64, v0 offset:11152
	v_cvt_pk_bf16_f32 v0, v5, s0
	ds_write_b16 v64, v32 offset:880
	v_cvt_pk_bf16_f32 v32, v52, s0
	ds_write_b16 v64, v0 offset:11216
	v_cvt_pk_bf16_f32 v0, v22, s0
	ds_write_b16 v64, v32 offset:2176
	v_cvt_pk_bf16_f32 v32, v36, s0
	ds_write_b16 v64, v0 offset:11424
	v_cvt_pk_bf16_f32 v0, v6, s0
	ds_write_b16 v64, v32 offset:2240
	v_cvt_pk_bf16_f32 v32, v53, s0
	ds_write_b16 v64, v0 offset:11488
	v_cvt_pk_bf16_f32 v0, v23, s0
	ds_write_b16 v64, v32 offset:2448
	v_cvt_pk_bf16_f32 v32, v37, s0
	ds_write_b16 v64, v0 offset:11696
	v_cvt_pk_bf16_f32 v0, v7, s0
	ds_write_b16 v64, v32 offset:2512
	v_cvt_pk_bf16_f32 v32, v54, s0
	ds_write_b16 v64, v0 offset:11760
	v_cvt_pk_bf16_f32 v0, v24, s0
	ds_write_b16 v64, v32 offset:2720
	v_cvt_pk_bf16_f32 v32, v38, s0
	ds_write_b16 v64, v0 offset:13056
	v_cvt_pk_bf16_f32 v0, v8, s0
	ds_write_b16 v64, v32 offset:2784
	v_cvt_pk_bf16_f32 v32, v55, s0
	ds_write_b16 v64, v0 offset:13120
	v_cvt_pk_bf16_f32 v0, v25, s0
	ds_write_b16 v64, v32 offset:2992
	v_cvt_pk_bf16_f32 v32, v39, s0
	ds_write_b16 v64, v0 offset:13328
	v_cvt_pk_bf16_f32 v0, v9, s0
	ds_write_b16 v64, v32 offset:3056
	v_cvt_pk_bf16_f32 v32, v56, s0
	ds_write_b16 v64, v0 offset:13392
	v_cvt_pk_bf16_f32 v0, v26, s0
	ds_write_b16 v64, v32 offset:4352
	v_cvt_pk_bf16_f32 v32, v40, s0
	ds_write_b16 v64, v0 offset:13600
	v_cvt_pk_bf16_f32 v0, v10, s0
	ds_write_b16 v64, v32 offset:4416
	v_cvt_pk_bf16_f32 v32, v57, s0
	ds_write_b16 v64, v0 offset:13664
	v_cvt_pk_bf16_f32 v0, v27, s0
	ds_write_b16 v64, v32 offset:4624
	v_cvt_pk_bf16_f32 v32, v41, s0
	ds_write_b16 v64, v0 offset:13872
	v_cvt_pk_bf16_f32 v0, v11, s0
	ds_write_b16 v64, v32 offset:4688
	v_cvt_pk_bf16_f32 v32, v58, s0
	ds_write_b16 v64, v0 offset:13936
	v_cvt_pk_bf16_f32 v0, v28, s0
	ds_write_b16 v64, v32 offset:4896
	v_cvt_pk_bf16_f32 v32, v42, s0
	ds_write_b16 v64, v0 offset:15232
	v_cvt_pk_bf16_f32 v0, v12, s0
	ds_write_b16 v64, v32 offset:4960
	v_cvt_pk_bf16_f32 v32, v59, s0
	ds_write_b16 v64, v0 offset:15296
	v_cvt_pk_bf16_f32 v0, v29, s0
	ds_write_b16 v64, v32 offset:5168
	v_cvt_pk_bf16_f32 v32, v43, s0
	ds_write_b16 v64, v0 offset:15504
	v_cvt_pk_bf16_f32 v0, v13, s0
	ds_write_b16 v64, v32 offset:5232
	v_cvt_pk_bf16_f32 v32, v60, s0
	ds_write_b16 v64, v0 offset:15568
	v_cvt_pk_bf16_f32 v0, v30, s0
	ds_write_b16 v64, v32 offset:6528
	v_cvt_pk_bf16_f32 v32, v44, s0
	ds_write_b16 v64, v0 offset:15776
	v_cvt_pk_bf16_f32 v0, v14, s0
	s_mul_i32 s11, s11, 0x160000
	ds_write_b16 v64, v32 offset:6592
	v_cvt_pk_bf16_f32 v32, v61, s0
	ds_write_b16 v64, v0 offset:15840
	v_cvt_pk_bf16_f32 v0, v31, s0
	s_add_u32 s41, s13, s11
	ds_write_b16 v64, v32 offset:6800
	v_cvt_pk_bf16_f32 v32, v45, s0
	ds_write_b16 v64, v0 offset:16048
	v_cvt_pk_bf16_f32 v0, v15, s0
	s_addc_u32 s44, s14, 0
	s_ashr_i32 s11, s10, 31
	ds_write_b16 v64, v32 offset:6864
	v_cvt_pk_bf16_f32 v32, v62, s0
	ds_write_b16 v64, v0 offset:16112
	s_lshl_b64 s[10:11], s[10:11], 1
	v_lshlrev_b32_e32 v0, 4, v102
	ds_write_b16 v64, v32 offset:7072
	v_cvt_pk_bf16_f32 v32, v46, s0
	s_add_u32 s10, s41, s10
	v_and_b32_e32 v96, 0xf0, v0
	ds_write_b16 v64, v32 offset:7136
	v_cvt_pk_bf16_f32 v32, v63, s0
	s_addc_u32 s11, s44, s11
	v_add_u32_e32 v8, 32, v96
	v_ashrrev_i32_e32 v9, 4, v102
	v_add_u32_e32 v4, 0x100, v102
	v_cvt_pk_bf16_f32 v48, v48, s0
	ds_write_b16 v64, v32 offset:7344
	v_cvt_pk_bf16_f32 v32, v47, s0
	v_cvt_pk_bf16_f32 v16, v16, s0
	v_lshl_add_u64 v[10:11], s[10:11], 0, v[96:97]
	v_mad_u64_u32 v[0:1], s[10:11], v9, s36, v[8:9]
	v_ashrrev_i32_e32 v14, 4, v4
	ds_write_b16 v64, v48
	ds_write_b16 v64, v32 offset:7408
	ds_write_b16 v64, v16 offset:8704
	s_waitcnt lgkmcnt(0)
	s_barrier
	ds_read_b128 v[0:3], v0
	v_mad_u64_u32 v[4:5], s[10:11], v14, s36, v[8:9]
	ds_read_b128 v[4:7], v4
	v_mad_i64_i32 v[12:13], s[10:11], v9, s37, v[10:11]
	s_waitcnt lgkmcnt(1)
	global_store_dwordx4 v[12:13], v[0:3], off
	s_nop 1
	v_mad_i64_i32 v[0:1], s[10:11], v14, s37, v[10:11]
	s_waitcnt lgkmcnt(0)
	global_store_dwordx4 v[0:1], v[4:7], off
	v_add_u32_e32 v0, 0x200, v102
	v_ashrrev_i32_e32 v9, 4, v0
	v_add_u32_e32 v4, 0x300, v102
	v_mad_u64_u32 v[0:1], s[10:11], v9, s36, v[8:9]
	v_ashrrev_i32_e32 v14, 4, v4
	ds_read_b128 v[0:3], v0
	v_mad_u64_u32 v[4:5], s[10:11], v14, s36, v[8:9]
	ds_read_b128 v[4:7], v4
	v_mad_i64_i32 v[12:13], s[10:11], v9, s37, v[10:11]
	s_waitcnt lgkmcnt(1)
	global_store_dwordx4 v[12:13], v[0:3], off
	s_nop 1
	v_mad_i64_i32 v[0:1], s[10:11], v14, s37, v[10:11]
	s_waitcnt lgkmcnt(0)
	global_store_dwordx4 v[0:1], v[4:7], off
	v_add_u32_e32 v0, 0x400, v102
	v_ashrrev_i32_e32 v9, 4, v0
	v_add_u32_e32 v4, 0x500, v102
	v_mad_u64_u32 v[0:1], s[10:11], v9, s36, v[8:9]
	v_ashrrev_i32_e32 v14, 4, v4
	ds_read_b128 v[0:3], v0
	v_mad_u64_u32 v[4:5], s[10:11], v14, s36, v[8:9]
	ds_read_b128 v[4:7], v4
	v_mad_i64_i32 v[12:13], s[10:11], v9, s37, v[10:11]
	s_waitcnt lgkmcnt(1)
	global_store_dwordx4 v[12:13], v[0:3], off
	s_nop 1
	v_mad_i64_i32 v[0:1], s[10:11], v14, s37, v[10:11]
	s_waitcnt lgkmcnt(0)
	global_store_dwordx4 v[0:1], v[4:7], off
	v_add_u32_e32 v0, 0x600, v102
	v_ashrrev_i32_e32 v9, 4, v0
	v_add_u32_e32 v4, 0x700, v102
	v_mad_u64_u32 v[0:1], s[10:11], v9, s36, v[8:9]
	v_ashrrev_i32_e32 v12, 4, v4
	ds_read_b128 v[0:3], v0
	v_mad_u64_u32 v[4:5], s[10:11], v12, s36, v[8:9]
	ds_read_b128 v[4:7], v4
	v_mad_i64_i32 v[8:9], s[10:11], v9, s37, v[10:11]
	s_waitcnt lgkmcnt(1)
	global_store_dwordx4 v[8:9], v[0:3], off
	s_nop 1
	v_mad_i64_i32 v[0:1], s[10:11], v12, s37, v[10:11]
	s_waitcnt lgkmcnt(0)
	global_store_dwordx4 v[0:1], v[4:7], off
	s_branch .LBB0_1937

.LBB0_2061:
	s_and_b32 s0, s57, 7
	s_or_b32 s1, s0, s3
	s_lshl_b32 s0, s57, 4
	v_mov_b32_e32 v0, v234
	s_waitcnt vmcnt(6)
	v_mov_b32_e32 v33, v234
	s_and_b32 s23, s0, 0xffffff80
	s_lshl_b32 s0, s1, 7
	s_waitcnt lgkmcnt(0)
	v_ashrrev_i32_e32 v32, 3, v33
	v_add_u32_e32 v0, s0, v32
	v_lshlrev_b32_e32 v2, 4, v33
	v_mad_i64_i32 v[0:1], s[20:21], v0, s38, v[96:97]
	v_and_b32_e32 v98, 0x70, v2
	s_waitcnt vmcnt(5)
	v_lshl_add_u64 v[34:35], v[0:1], 0, v[98:99]
	s_waitcnt vmcnt(4)
	v_add_co_u32_e32 v38, vcc, s39, v34
	v_add_u32_e32 v0, s23, v32
	s_nop 0
	v_addc_co_u32_e32 v39, vcc, 0, v35, vcc
	v_add_co_u32_e32 v40, vcc, s40, v34
	v_mad_i64_i32 v[0:1], s[20:21], v0, s38, v[100:101]
	s_nop 0
	v_addc_co_u32_e32 v41, vcc, 0, v35, vcc
	v_add_co_u32_e32 v42, vcc, s41, v34
	v_lshl_add_u64 v[36:37], v[0:1], 0, v[98:99]
	s_nop 0
	v_addc_co_u32_e32 v43, vcc, 0, v35, vcc
	v_add_co_u32_e32 v44, vcc, s39, v36
	s_barrier
	s_nop 0
	v_addc_co_u32_e32 v45, vcc, 0, v37, vcc
	v_add_co_u32_e32 v46, vcc, s40, v36
	s_nop 1
	v_addc_co_u32_e32 v47, vcc, 0, v37, vcc
	v_add_co_u32_e32 v48, vcc, s41, v36
	global_load_dwordx4 v[0:3], v[34:35], off
	global_load_dwordx4 v[4:7], v[38:39], off
	v_addc_co_u32_e32 v49, vcc, 0, v37, vcc
	global_load_dwordx4 v[8:11], v[40:41], off
	global_load_dwordx4 v[12:15], v[42:43], off
	global_load_dwordx4 v[16:19], v[36:37], off
	global_load_dwordx4 v[20:23], v[44:45], off
	global_load_dwordx4 v[24:27], v[46:47], off
	global_load_dwordx4 v[28:31], v[48:49], off
	global_load_dwordx4 v[68:71], v[34:35], off offset:128
	global_load_dwordx4 v[64:67], v[36:37], off offset:128
	global_load_dwordx4 v[84:87], v[38:39], off offset:128
	global_load_dwordx4 v[88:91], v[40:41], off offset:128
	global_load_dwordx4 v[92:95], v[42:43], off offset:128
	global_load_dwordx4 v[72:75], v[44:45], off offset:128
	global_load_dwordx4 v[76:79], v[46:47], off offset:128
	global_load_dwordx4 v[80:83], v[48:49], off offset:128
	v_and_b32_e32 v52, 0x5f, v33
	v_mul_lo_u32 v53, v32, s44
	v_lshrrev_b32_e32 v50, 1, v33
	v_and_b32_e32 v51, 31, v33
	v_mul_u32_u24_e32 v52, 0x48, v52
	v_add3_u32 v111, 32, v53, v98
	s_and_b32 s20, s27, 0xffffff80
	s_and_b32 s8, s26, 7
	v_and_or_b32 v51, v50, s45, v51
	v_and_b32_e32 v50, 16, v50
	s_lshl_b32 s22, s8, 7
	s_ashr_i32 s21, s20, 31
	v_mul_lo_u32 v51, v51, s44
	v_add3_u32 v109, 32, v51, v50
	v_add_u32_e32 v112, 0xd800, v111
	s_mov_b32 s8, -2
	v_mov_b32_e32 v48, v99
	v_mov_b32_e32 v49, v99
	v_mov_b32_e32 v51, v99
	v_mov_b32_e32 v53, v99
	v_mov_b32_e32 v54, v99
	v_mov_b32_e32 v55, v99
	v_mov_b32_e32 v56, v99
	v_mov_b32_e32 v57, v99
	v_mov_b32_e32 v58, v99
	v_mov_b32_e32 v59, v99
	v_mov_b32_e32 v60, v99
	v_mov_b32_e32 v61, v99
	v_mov_b32_e32 v62, v99
	v_mov_b32_e32 v63, v99
	v_mov_b32_e32 v34, v99
	v_mov_b32_e32 v35, v99
	v_mov_b32_e32 v36, v99
	v_mov_b32_e32 v37, v99
	v_mov_b32_e32 v38, v99
	v_mov_b32_e32 v39, v99
	v_mov_b32_e32 v40, v99
	s_waitcnt vmcnt(15)
	ds_write_b128 v111, v[0:3]
	s_waitcnt vmcnt(11)
	ds_write_b128 v111, v[16:19] offset:36864
	ds_write_b128 v111, v[4:7] offset:4608
	ds_write_b128 v111, v[8:11] offset:9216
	ds_write_b128 v111, v[12:15] offset:13824
	s_waitcnt vmcnt(10)
	ds_write_b128 v111, v[20:23] offset:41472
	s_waitcnt vmcnt(9)
	ds_write_b128 v111, v[24:27] offset:46080
	s_waitcnt vmcnt(8)
	ds_write_b128 v111, v[28:31] offset:50688
	v_lshlrev_b32_e32 v0, 1, v52
	v_add3_u32 v110, 32, v0, v50
	v_and_b32_e32 v0, 7, v33
	v_ashrrev_i32_e32 v33, 31, v32
	v_lshlrev_b32_e32 v98, 4, v0
	v_lshl_add_u64 v[0:1], v[32:33], 0, s[20:21]
	s_add_i32 s21, s22, s34
	v_mad_u64_u32 v[104:105], s[58:59], v0, s38, v[102:103]
	v_add_u32_e32 v0, s21, v32
	v_mad_i32_i24 v105, v1, s38, v105
	v_mad_i64_i32 v[106:107], s[58:59], v0, s38, v[102:103]
	v_mov_b32_e32 v0, v99
	v_mov_b32_e32 v1, v99
	v_mov_b32_e32 v2, v99
	v_mov_b32_e32 v3, v99
	v_mov_b32_e32 v4, v99
	v_mov_b32_e32 v5, v99
	v_mov_b32_e32 v6, v99
	v_mov_b32_e32 v7, v99
	v_mov_b32_e32 v8, v99
	v_mov_b32_e32 v9, v99
	v_mov_b32_e32 v10, v99
	v_mov_b32_e32 v11, v99
	v_mov_b32_e32 v12, v99
	v_mov_b32_e32 v13, v99
	v_mov_b32_e32 v14, v99
	v_mov_b32_e32 v15, v99
	v_mov_b32_e32 v16, v99
	v_mov_b32_e32 v17, v99
	v_mov_b32_e32 v18, v99
	v_mov_b32_e32 v19, v99
	v_mov_b32_e32 v20, v99
	v_mov_b32_e32 v21, v99
	v_mov_b32_e32 v22, v99
	v_mov_b32_e32 v23, v99
	v_mov_b32_e32 v24, v99
	v_mov_b32_e32 v25, v99
	v_mov_b32_e32 v26, v99
	v_mov_b32_e32 v27, v99
	v_mov_b32_e32 v28, v99
	v_mov_b32_e32 v29, v99
	v_mov_b32_e32 v30, v99
	v_mov_b32_e32 v31, v99
	v_mov_b32_e32 v50, v99
	v_mov_b32_e32 v52, v99
	v_mov_b32_e32 v32, v99
	v_mov_b32_e32 v33, v99
	v_mov_b32_e32 v41, v99
	v_mov_b32_e32 v42, v99
	v_mov_b32_e32 v43, v99
	v_mov_b32_e32 v44, v99
	v_mov_b32_e32 v45, v99
	v_mov_b32_e32 v46, v99
	v_mov_b32_e32 v47, v99
	v_lshl_add_u64 v[122:123], v[106:107], 0, v[98:99]
	s_mov_b32 s58, 0xab93000
	v_add_co_u32_e32 v174, vcc, s58, v122
	s_mov_b32 s58, 0xabbf000
	s_nop 0
	v_addc_co_u32_e32 v175, vcc, 0, v123, vcc
	v_add_co_u32_e32 v176, vcc, s58, v122
	s_mov_b32 s58, 0xabeb000
	s_nop 0
	v_addc_co_u32_e32 v177, vcc, 0, v123, vcc
	v_add_co_u32_e32 v178, vcc, s58, v122
	v_lshl_add_u64 v[138:139], v[104:105], 0, v[98:99]
	s_nop 0
	v_addc_co_u32_e32 v179, vcc, 0, v123, vcc
	v_add_co_u32_e32 v180, vcc, s46, v122
	s_nop 1
	v_addc_co_u32_e32 v181, vcc, 0, v123, vcc
	v_add_co_u32_e32 v182, vcc, s47, v138
	s_nop 1
	v_addc_co_u32_e32 v183, vcc, 0, v139, vcc
	v_add_co_u32_e32 v184, vcc, s48, v138
	s_nop 1
	v_addc_co_u32_e32 v185, vcc, 0, v139, vcc
	v_add_co_u32_e32 v186, vcc, s49, v138
	s_nop 1
	v_addc_co_u32_e32 v187, vcc, 0, v139, vcc
	v_add_co_u32_e32 v188, vcc, s50, v138
	s_nop 1
	v_addc_co_u32_e32 v189, vcc, 0, v139, vcc
	v_subrev_u32_e32 v174, s30, v174
	v_subrev_u32_e32 v176, s30, v176
	v_subrev_u32_e32 v178, s30, v178
	v_subrev_u32_e32 v180, s30, v180
	v_subrev_u32_e32 v182, s30, v182
	v_subrev_u32_e32 v184, s30, v184
	v_subrev_u32_e32 v186, s30, v186
	v_subrev_u32_e32 v188, s30, v188
	s_mov_b64 s[98:99], s[30:31]
	s_waitcnt lgkmcnt(0)
	s_barrier
.LBB0_2062:
	s_setprio 1
	ds_read_b128 v[146:149], v109
	ds_read_b128 v[150:153], v110 offset:36864
	ds_read_b128 v[154:157], v109 offset:32
	ds_read_b128 v[158:161], v110 offset:36896
	ds_read_b128 v[162:165], v110 offset:41472
	ds_read_b128 v[166:169], v110 offset:41504
	s_waitcnt lgkmcnt(4)
	v_mfma_f32_32x32x16_bf16 v[32:47], v[146:149], v[150:153], v[32:47]
	global_load_dwordx4 v[114:117], v174, s[98:99] offset:3840
	global_load_dwordx4 v[118:121], v176, s[98:99] offset:3840
	s_waitcnt lgkmcnt(1)
	v_mfma_f32_32x32x16_bf16 v[48:63], v[146:149], v[162:165], v[48:63]
	global_load_dwordx4 v[122:125], v178, s[98:99] offset:3840
	global_load_dwordx4 v[126:129], v180, s[98:99] offset:3840
	ds_read_b128 v[146:149], v109 offset:4608
	ds_read_b128 v[170:173], v109 offset:4640
	s_waitcnt lgkmcnt(1)
	v_mfma_f32_32x32x16_bf16 v[16:31], v[146:149], v[150:153], v[16:31]
	global_load_dwordx4 v[130:133], v182, s[98:99] offset:3840
	global_load_dwordx4 v[134:137], v184, s[98:99] offset:3840
	v_mfma_f32_32x32x16_bf16 v[0:15], v[146:149], v[162:165], v[0:15]
	global_load_dwordx4 v[138:141], v186, s[98:99] offset:3840
	global_load_dwordx4 v[142:145], v188, s[98:99] offset:3840
	v_mfma_f32_32x32x16_bf16 v[32:47], v[154:157], v[158:161], v[32:47]
	v_mfma_f32_32x32x16_bf16 v[48:63], v[154:157], v[166:169], v[48:63]
	s_waitcnt lgkmcnt(0)
	v_mfma_f32_32x32x16_bf16 v[16:31], v[170:173], v[158:161], v[16:31]
	ds_read_b128 v[146:149], v109 offset:64
	ds_read_b128 v[150:153], v110 offset:36928
	ds_read_b128 v[154:157], v109 offset:96
	ds_read_b128 v[158:161], v110 offset:36960
	v_mfma_f32_32x32x16_bf16 v[0:15], v[170:173], v[166:169], v[0:15]
	s_waitcnt vmcnt(15)
	ds_write_b128 v111, v[68:71] offset:18432
	ds_read_b128 v[162:165], v110 offset:41536
	ds_read_b128 v[166:169], v110 offset:41568
	s_waitcnt lgkmcnt(5)
	v_mfma_f32_32x32x16_bf16 v[32:47], v[146:149], v[150:153], v[32:47]
	s_waitcnt vmcnt(13)
	ds_write_b128 v111, v[84:87] offset:23040
	s_waitcnt lgkmcnt(2)
	v_mfma_f32_32x32x16_bf16 v[48:63], v[146:149], v[162:165], v[48:63]
	s_waitcnt vmcnt(12)
	ds_write_b128 v111, v[88:91] offset:27648
	ds_read_b128 v[146:149], v109 offset:4672
	ds_read_b128 v[170:173], v109 offset:4704
	s_waitcnt lgkmcnt(1)
	v_mfma_f32_32x32x16_bf16 v[16:31], v[146:149], v[150:153], v[16:31]
	s_waitcnt vmcnt(11)
	ds_write_b128 v111, v[92:95] offset:32256
	v_mfma_f32_32x32x16_bf16 v[0:15], v[146:149], v[162:165], v[0:15]
	ds_write_b128 v111, v[64:67] offset:55296
	v_mfma_f32_32x32x16_bf16 v[32:47], v[154:157], v[158:161], v[32:47]
	s_waitcnt vmcnt(10)
	ds_write_b128 v111, v[72:75] offset:59904
	v_mfma_f32_32x32x16_bf16 v[48:63], v[154:157], v[166:169], v[48:63]
	s_waitcnt vmcnt(9)
	ds_write_b128 v111, v[76:79] offset:64512
	s_waitcnt lgkmcnt(4)
	v_mfma_f32_32x32x16_bf16 v[16:31], v[170:173], v[158:161], v[16:31]
	s_waitcnt vmcnt(8)
	ds_write_b128 v112, v[80:83] offset:13824
	v_mfma_f32_32x32x16_bf16 v[0:15], v[170:173], v[166:169], v[0:15]
	s_setprio 0
	s_waitcnt lgkmcnt(0)
	s_barrier
	s_setprio 1
	ds_read_b128 v[146:149], v109 offset:18432
	ds_read_b128 v[150:153], v110 offset:55296
	ds_read_b128 v[154:157], v109 offset:18464
	ds_read_b128 v[158:161], v110 offset:55328
	ds_read_b128 v[162:165], v110 offset:59904
	ds_read_b128 v[166:169], v110 offset:59936
	s_waitcnt lgkmcnt(4)
	v_mfma_f32_32x32x16_bf16 v[32:47], v[146:149], v[150:153], v[32:47]
	global_load_dwordx4 v[68:71], v174, s[98:99] offset:3968
	global_load_dwordx4 v[84:87], v176, s[98:99] offset:3968
	s_waitcnt lgkmcnt(1)
	v_mfma_f32_32x32x16_bf16 v[48:63], v[146:149], v[162:165], v[48:63]
	global_load_dwordx4 v[88:91], v178, s[98:99] offset:3968
	global_load_dwordx4 v[92:95], v180, s[98:99] offset:3968
	ds_read_b128 v[146:149], v109 offset:23040
	ds_read_b128 v[170:173], v109 offset:23072
	s_waitcnt lgkmcnt(1)
	v_mfma_f32_32x32x16_bf16 v[16:31], v[146:149], v[150:153], v[16:31]
	global_load_dwordx4 v[64:67], v182, s[98:99] offset:3968
	global_load_dwordx4 v[72:75], v184, s[98:99] offset:3968
	v_mfma_f32_32x32x16_bf16 v[0:15], v[146:149], v[162:165], v[0:15]
	global_load_dwordx4 v[76:79], v186, s[98:99] offset:3968
	global_load_dwordx4 v[80:83], v188, s[98:99] offset:3968
	v_mfma_f32_32x32x16_bf16 v[32:47], v[154:157], v[158:161], v[32:47]
	v_mfma_f32_32x32x16_bf16 v[48:63], v[154:157], v[166:169], v[48:63]
	s_waitcnt lgkmcnt(0)
	v_mfma_f32_32x32x16_bf16 v[16:31], v[170:173], v[158:161], v[16:31]
	ds_read_b128 v[146:149], v109 offset:18496
	ds_read_b128 v[150:153], v110 offset:55360
	ds_read_b128 v[154:157], v109 offset:18528
	ds_read_b128 v[158:161], v110 offset:55392
	v_mfma_f32_32x32x16_bf16 v[0:15], v[170:173], v[166:169], v[0:15]
	s_add_u32 s98, s98, 0x100
	s_addc_u32 s99, s99, 0
	s_add_i32 s8, s8, 2
	s_cmp_lt_u32 s8, 39
	s_waitcnt vmcnt(15)
	ds_write_b128 v111, v[114:117]
	ds_read_b128 v[162:165], v110 offset:59968
	ds_read_b128 v[166:169], v110 offset:60000
	s_waitcnt lgkmcnt(5)
	v_mfma_f32_32x32x16_bf16 v[32:47], v[146:149], v[150:153], v[32:47]
	s_waitcnt vmcnt(14)
	ds_write_b128 v111, v[118:121] offset:4608
	s_waitcnt lgkmcnt(2)
	v_mfma_f32_32x32x16_bf16 v[48:63], v[146:149], v[162:165], v[48:63]
	s_waitcnt vmcnt(13)
	ds_write_b128 v111, v[122:125] offset:9216
	ds_read_b128 v[146:149], v109 offset:23104
	ds_read_b128 v[170:173], v109 offset:23136
	s_waitcnt lgkmcnt(1)
	v_mfma_f32_32x32x16_bf16 v[16:31], v[146:149], v[150:153], v[16:31]
	s_waitcnt vmcnt(12)
	ds_write_b128 v111, v[126:129] offset:13824
	v_mfma_f32_32x32x16_bf16 v[0:15], v[146:149], v[162:165], v[0:15]
	s_waitcnt vmcnt(11)
	ds_write_b128 v111, v[130:133] offset:36864
	v_mfma_f32_32x32x16_bf16 v[32:47], v[154:157], v[158:161], v[32:47]
	s_waitcnt vmcnt(10)
	ds_write_b128 v111, v[134:137] offset:41472
	v_mfma_f32_32x32x16_bf16 v[48:63], v[154:157], v[166:169], v[48:63]
	s_waitcnt vmcnt(9)
	ds_write_b128 v111, v[138:141] offset:46080
	s_waitcnt lgkmcnt(4)
	v_mfma_f32_32x32x16_bf16 v[16:31], v[170:173], v[158:161], v[16:31]
	s_waitcnt vmcnt(8)
	ds_write_b128 v111, v[142:145] offset:50688
	v_mfma_f32_32x32x16_bf16 v[0:15], v[170:173], v[166:169], v[0:15]
	s_setprio 0
	s_waitcnt lgkmcnt(0)
	s_barrier
	s_cbranch_scc1 .LBB0_2062
	s_setprio 1
	ds_read_b128 v[104:107], v109
	ds_read_b128 v[114:117], v110 offset:36864
	ds_read_b128 v[118:121], v109 offset:32
	ds_read_b128 v[122:125], v110 offset:36896
	ds_read_b128 v[126:129], v110 offset:41472
	ds_read_b128 v[130:133], v110 offset:41504
	s_waitcnt lgkmcnt(4)
	v_mfma_f32_32x32x16_bf16 v[32:47], v[104:107], v[114:117], v[32:47]
	s_waitcnt lgkmcnt(1)
	v_mfma_f32_32x32x16_bf16 v[48:63], v[104:107], v[126:129], v[48:63]
	ds_read_b128 v[104:107], v109 offset:4608
	ds_read_b128 v[134:137], v109 offset:4640
	s_waitcnt lgkmcnt(1)
	v_mfma_f32_32x32x16_bf16 v[16:31], v[104:107], v[114:117], v[16:31]
	v_mfma_f32_32x32x16_bf16 v[0:15], v[104:107], v[126:129], v[0:15]
	v_mfma_f32_32x32x16_bf16 v[32:47], v[118:121], v[122:125], v[32:47]
	v_mfma_f32_32x32x16_bf16 v[48:63], v[118:121], v[130:133], v[48:63]
	s_waitcnt lgkmcnt(0)
	v_mfma_f32_32x32x16_bf16 v[16:31], v[134:137], v[122:125], v[16:31]
	ds_read_b128 v[104:107], v109 offset:64
	ds_read_b128 v[114:117], v110 offset:36928
	ds_read_b128 v[118:121], v109 offset:96
	ds_read_b128 v[122:125], v110 offset:36960
	v_mfma_f32_32x32x16_bf16 v[0:15], v[134:137], v[130:133], v[0:15]
	s_waitcnt vmcnt(7)
	ds_write_b128 v111, v[68:71] offset:18432
	ds_read_b128 v[126:129], v110 offset:41536
	ds_read_b128 v[130:133], v110 offset:41568
	s_waitcnt lgkmcnt(5)
	v_mfma_f32_32x32x16_bf16 v[32:47], v[104:107], v[114:117], v[32:47]
	s_waitcnt vmcnt(6)
	ds_write_b128 v111, v[84:87] offset:23040
	s_waitcnt lgkmcnt(2)
	v_mfma_f32_32x32x16_bf16 v[48:63], v[104:107], v[126:129], v[48:63]
	s_waitcnt vmcnt(5)
	ds_write_b128 v111, v[88:91] offset:27648
	ds_read_b128 v[104:107], v109 offset:4672
	ds_read_b128 v[134:137], v109 offset:4704
	s_waitcnt lgkmcnt(1)
	v_mfma_f32_32x32x16_bf16 v[16:31], v[104:107], v[114:117], v[16:31]
	s_waitcnt vmcnt(4)
	ds_write_b128 v111, v[92:95] offset:32256
	v_mfma_f32_32x32x16_bf16 v[0:15], v[104:107], v[126:129], v[0:15]
	s_waitcnt vmcnt(3)
	ds_write_b128 v111, v[64:67] offset:55296
	v_mfma_f32_32x32x16_bf16 v[32:47], v[118:121], v[122:125], v[32:47]
	s_waitcnt vmcnt(2)
	ds_write_b128 v111, v[72:75] offset:59904
	s_waitcnt lgkmcnt(3)
	v_mfma_f32_32x32x16_bf16 v[16:31], v[134:137], v[122:125], v[16:31]
	s_waitcnt vmcnt(1)
	ds_write_b128 v111, v[76:79] offset:64512
	v_mfma_f32_32x32x16_bf16 v[0:15], v[134:137], v[130:133], v[0:15]
	s_waitcnt vmcnt(0)
	ds_write_b128 v112, v[80:83] offset:13824
	v_mfma_f32_32x32x16_bf16 v[48:63], v[118:121], v[130:133], v[48:63]
	s_setprio 0
	s_waitcnt lgkmcnt(0)
	s_barrier
	s_setprio 1
	ds_read_b128 v[64:67], v109 offset:18432
	ds_read_b128 v[68:71], v110 offset:55296
	ds_read_b128 v[72:75], v109 offset:18464
	ds_read_b128 v[76:79], v110 offset:55328
	ds_read_b128 v[80:83], v110 offset:59904
	ds_read_b128 v[84:87], v110 offset:59936
	s_waitcnt lgkmcnt(4)
	v_mfma_f32_32x32x16_bf16 v[32:47], v[64:67], v[68:71], v[32:47]
	s_waitcnt lgkmcnt(1)
	v_mfma_f32_32x32x16_bf16 v[48:63], v[64:67], v[80:83], v[48:63]
	ds_read_b128 v[64:67], v109 offset:23040
	ds_read_b128 v[88:91], v109 offset:23072
	s_waitcnt lgkmcnt(1)
	v_mfma_f32_32x32x16_bf16 v[16:31], v[64:67], v[68:71], v[16:31]
	v_mfma_f32_32x32x16_bf16 v[0:15], v[64:67], v[80:83], v[0:15]
	v_mfma_f32_32x32x16_bf16 v[32:47], v[72:75], v[76:79], v[32:47]
	v_mfma_f32_32x32x16_bf16 v[48:63], v[72:75], v[84:87], v[48:63]
	s_waitcnt lgkmcnt(0)
	v_mfma_f32_32x32x16_bf16 v[16:31], v[88:91], v[76:79], v[16:31]
	ds_read_b128 v[64:67], v109 offset:18496
	ds_read_b128 v[68:71], v110 offset:55360
	ds_read_b128 v[72:75], v109 offset:18528
	ds_read_b128 v[76:79], v110 offset:55392
	v_mfma_f32_32x32x16_bf16 v[0:15], v[88:91], v[84:87], v[0:15]
	ds_read_b128 v[80:83], v110 offset:59968
	ds_read_b128 v[84:87], v110 offset:60000
	s_waitcnt lgkmcnt(4)
	v_mfma_f32_32x32x16_bf16 v[32:47], v[64:67], v[68:71], v[32:47]
	s_waitcnt lgkmcnt(1)
	v_mfma_f32_32x32x16_bf16 v[48:63], v[64:67], v[80:83], v[48:63]
	ds_read_b128 v[64:67], v109 offset:23104
	ds_read_b128 v[88:91], v109 offset:23136
	s_waitcnt lgkmcnt(1)
	v_mfma_f32_32x32x16_bf16 v[16:31], v[64:67], v[68:71], v[16:31]
	v_mfma_f32_32x32x16_bf16 v[0:15], v[64:67], v[80:83], v[0:15]
	v_mfma_f32_32x32x16_bf16 v[32:47], v[72:75], v[76:79], v[32:47]
	s_waitcnt lgkmcnt(0)
	v_mfma_f32_32x32x16_bf16 v[16:31], v[88:91], v[76:79], v[16:31]
	v_mfma_f32_32x32x16_bf16 v[0:15], v[88:91], v[84:87], v[0:15]
	v_mfma_f32_32x32x16_bf16 v[48:63], v[72:75], v[84:87], v[48:63]
	s_setprio 0
	s_addk_i32 s0, 0xf000
	s_lshr_b32 s8, s0, 10
	s_mulk_i32 s8, 0x1800
	s_addk_i32 s8, 0x1800
	s_and_b64 s[58:59], s[4:5], exec
	s_cselect_b32 s8, 0, s8
	v_mov_b32_e32 v68, v234
	s_barrier
	s_lshl_b64 s[58:59], s[8:9], 2
	s_add_u32 s58, s30, s58
	v_and_b32_e32 v69, 0x5f, v68
	v_or_b32_e32 v64, s23, v69
	s_addc_u32 s59, s31, s59
	v_ashrrev_i32_e32 v65, 31, v64
	v_lshl_add_u64 v[64:65], v[64:65], 2, s[58:59]
	v_lshl_add_u64 v[66:67], v[64:65], 0, s[12:13]
	v_add_co_u32_e32 v64, vcc, s51, v64
	global_load_dword v66, v[66:67], off offset:128
	s_nop 0
	v_addc_co_u32_e32 v65, vcc, 0, v65, vcc
	global_load_dword v64, v[64:65], off
	v_lshrrev_b32_e32 v67, 3, v68
	v_lshrrev_b32_e32 v65, 1, v68
	v_and_b32_e32 v67, 4, v67
	v_and_or_b32 v65, v65, s45, v67
	v_lshlrev_b32_e32 v69, 2, v69
	v_mul_lo_u32 v65, v65, s52
	v_add3_u32 v65, 32, v69, v65
	v_add_u32_e32 v67, 0x400, v65
	v_add_u32_e32 v69, 0x1000, v65
	v_add_u32_e32 v70, 0x1400, v65
	v_add_u32_e32 v71, 0x2000, v65
	v_add_u32_e32 v72, 0x2400, v65
	v_add_u32_e32 v73, 0x3000, v65
	v_add_u32_e32 v74, 0x3200, v65
	v_add_u32_e32 v75, 0x3400, v65
	v_add_u32_e32 v76, 0x3600, v65
	v_add_u32_e32 v77, 0x4000, v65
	v_readlane_b32 s80, v250, 6
	v_readlane_b32 s81, v250, 7
	v_readlane_b32 s82, v250, 8
	v_readlane_b32 s83, v250, 9
	s_lshl_b32 s1, s1, 19
	s_add_u32 s8, s15, s1
	s_mov_b32 s1, s9
	v_readlane_b32 s84, v250, 10
	v_readlane_b32 s85, v250, 11
	v_readlane_b32 s86, v250, 12
	v_readlane_b32 s87, v250, 13
	v_readlane_b32 s88, v250, 14
	v_readlane_b32 s89, v250, 15
	v_readlane_b32 s90, v250, 16
	v_readlane_b32 s91, v250, 17
	v_readlane_b32 s92, v250, 18
	v_readlane_b32 s93, v250, 19
	v_readlane_b32 s94, v250, 20
	v_readlane_b32 s95, v250, 21
	s_waitcnt vmcnt(1)
	v_mul_f32_e32 v48, v48, v66
	v_mul_f32_e32 v0, v0, v66
	v_mul_f32_e32 v49, v49, v66
	s_waitcnt vmcnt(0)
	v_mul_f32_e32 v32, v32, v64
	v_mul_f32_e32 v50, v50, v66
	v_mul_f32_e32 v51, v51, v66
	v_mul_f32_e32 v52, v52, v66
	v_mul_f32_e32 v53, v53, v66
	v_mul_f32_e32 v54, v54, v66
	v_mul_f32_e32 v55, v55, v66
	v_mul_f32_e32 v56, v56, v66
	v_mul_f32_e32 v57, v57, v66
	v_mul_f32_e32 v58, v58, v66
	v_mul_f32_e32 v59, v59, v66
	v_mul_f32_e32 v60, v60, v66
	v_mul_f32_e32 v61, v61, v66
	v_mul_f32_e32 v62, v62, v66
	v_mul_f32_e32 v63, v63, v66
	v_mul_f32_e32 v33, v33, v64
	v_mul_f32_e32 v34, v34, v64
	v_mul_f32_e32 v35, v35, v64
	v_mul_f32_e32 v36, v36, v64
	v_mul_f32_e32 v37, v37, v64
	v_mul_f32_e32 v38, v38, v64
	v_mul_f32_e32 v39, v39, v64
	v_mul_f32_e32 v40, v40, v64
	v_mul_f32_e32 v41, v41, v64
	v_mul_f32_e32 v42, v42, v64
	v_mul_f32_e32 v43, v43, v64
	v_mul_f32_e32 v44, v44, v64
	v_mul_f32_e32 v45, v45, v64
	v_mul_f32_e32 v46, v46, v64
	v_mul_f32_e32 v47, v47, v64
	v_mul_f32_e32 v16, v16, v64
	v_mul_f32_e32 v17, v17, v64
	ds_write2_b32 v65, v32, v48 offset1:32
	ds_write2_b32 v65, v33, v49 offset0:132 offset1:164
	ds_write2_b32 v67, v34, v50 offset0:8 offset1:40
	ds_write2_b32 v67, v35, v51 offset0:140 offset1:172
	ds_write2_b32 v69, v36, v52 offset0:32 offset1:64
	ds_write2_b32 v69, v37, v53 offset0:164 offset1:196
	ds_write2_b32 v70, v38, v54 offset0:40 offset1:72
	ds_write2_b32 v70, v39, v55 offset0:172 offset1:204
	ds_write2_b32 v71, v40, v56 offset0:64 offset1:96
	ds_write2_b32 v71, v41, v57 offset0:196 offset1:228
	ds_write2_b32 v72, v42, v58 offset0:72 offset1:104
	ds_write2_b32 v72, v43, v59 offset0:204 offset1:236
	ds_write2_b32 v73, v44, v60 offset0:96 offset1:128
	ds_write2_b32 v74, v45, v61 offset0:100 offset1:132
	ds_write2_b32 v75, v46, v62 offset0:104 offset1:136
	ds_write2_b32 v76, v47, v63 offset0:108 offset1:140
	ds_write2_b32 v77, v16, v0 offset0:128 offset1:160
	v_mul_f32_e32 v0, v1, v66
	v_add_u32_e32 v1, 0x4400, v65
	ds_write2_b32 v1, v17, v0 offset0:4 offset1:36
	v_mul_f32_e32 v0, v18, v64
	v_mul_f32_e32 v2, v2, v66
	ds_write2_b32 v1, v0, v2 offset0:136 offset1:168
	v_mul_f32_e32 v0, v19, v64
	v_mul_f32_e32 v1, v3, v66
	v_add_u32_e32 v2, 0x4800, v65
	ds_write2_b32 v2, v0, v1 offset0:12 offset1:44
	v_mul_f32_e32 v0, v20, v64
	v_mul_f32_e32 v1, v4, v66
	v_add_u32_e32 v2, 0x5000, v65
	ds_write2_b32 v2, v0, v1 offset0:160 offset1:192
	v_mul_f32_e32 v0, v21, v64
	v_mul_f32_e32 v1, v5, v66
	v_add_u32_e32 v2, 0x5400, v65
	ds_write2_b32 v2, v0, v1 offset0:36 offset1:68
	v_mul_f32_e32 v0, v22, v64
	v_mul_f32_e32 v1, v6, v66
	ds_write2_b32 v2, v0, v1 offset0:168 offset1:200
	v_mul_f32_e32 v0, v23, v64
	v_mul_f32_e32 v1, v7, v66
	v_add_u32_e32 v2, 0x5800, v65
	ds_write2_b32 v2, v0, v1 offset0:44 offset1:76
	v_mul_f32_e32 v0, v24, v64
	v_mul_f32_e32 v1, v8, v66
	v_add_u32_e32 v2, 0x6000, v65
	ds_write2_b32 v2, v0, v1 offset0:192 offset1:224
	v_mul_f32_e32 v0, v25, v64
	v_mul_f32_e32 v1, v9, v66
	v_add_u32_e32 v2, 0x6400, v65
	ds_write2_b32 v2, v0, v1 offset0:68 offset1:100
	v_mul_f32_e32 v0, v26, v64
	v_mul_f32_e32 v1, v10, v66
	ds_write2_b32 v2, v0, v1 offset0:200 offset1:232
	v_mul_f32_e32 v0, v27, v64
	v_mul_f32_e32 v1, v11, v66
	v_add_u32_e32 v2, 0x6800, v65
	ds_write2_b32 v2, v0, v1 offset0:76 offset1:108
	v_mul_f32_e32 v0, v28, v64
	v_mul_f32_e32 v1, v12, v66
	v_add_u32_e32 v2, 0x7200, v65
	ds_write2_b32 v2, v0, v1 offset0:96 offset1:128
	v_mul_f32_e32 v0, v29, v64
	v_mul_f32_e32 v1, v13, v66
	v_add_u32_e32 v2, 0x7400, v65
	ds_write2_b32 v2, v0, v1 offset0:100 offset1:132
	v_mul_f32_e32 v0, v30, v64
	v_mul_f32_e32 v1, v14, v66
	v_add_u32_e32 v2, 0x7600, v65
	v_and_b32_e32 v12, 31, v68
	ds_write2_b32 v2, v0, v1 offset0:104 offset1:136
	v_mul_f32_e32 v0, v31, v64
	v_mul_f32_e32 v1, v15, v66
	v_add_u32_e32 v2, 0x7800, v65
	v_lshlrev_b32_e32 v8, 2, v12
	ds_write2_b32 v2, v0, v1 offset0:108 offset1:140
	v_or_b32_e32 v0, s23, v8
	v_ashrrev_i32_e32 v1, 31, v0
	v_lshlrev_b64 v[0:1], 2, v[0:1]
	v_lshl_add_u64 v[2:3], s[80:81], 0, v[0:1]
	v_lshl_add_u64 v[4:5], s[82:83], 0, v[0:1]
	s_waitcnt lgkmcnt(0)
	s_barrier
	global_load_dwordx4 v[0:3], v[2:3], off
	s_nop 0
	global_load_dwordx4 v[4:7], v[4:5], off
	v_and_b32_e32 v9, 64, v108
	v_add_u32_e32 v9, 64, v9
	v_xor_b32_e32 v10, 1, v108
	v_cmp_lt_i32_e32 vcc, v10, v9
	s_addc_u32 s23, s17, 0
	s_lshl_b64 s[0:1], s[0:1], 12
	v_cndmask_b32_e32 v10, v108, v10, vcc
	v_lshlrev_b32_e32 v32, 2, v10
	v_xor_b32_e32 v10, 2, v108
	v_cmp_lt_i32_e32 vcc, v10, v9
	s_add_u32 s58, s24, s0
	s_addc_u32 s59, s25, s1
	v_cndmask_b32_e32 v10, v108, v10, vcc
	v_lshlrev_b32_e32 v33, 2, v10
	v_xor_b32_e32 v10, 4, v108
	v_cmp_lt_i32_e32 vcc, v10, v9
	s_and_b64 s[0:1], s[4:5], exec
	v_ashrrev_i32_e32 v22, 5, v68
	v_cndmask_b32_e32 v10, v108, v10, vcc
	v_lshlrev_b32_e32 v34, 2, v10
	v_xor_b32_e32 v10, 8, v108
	s_cselect_b32 s59, s23, s59
	s_cselect_b32 s58, s8, s58
	v_cmp_lt_i32_e32 vcc, v10, v9
	s_add_i32 s8, s22, s35
	v_add_u32_e32 v16, s8, v22
	v_cndmask_b32_e32 v10, v108, v10, vcc
	s_add_i32 s8, s22, s36
	s_add_i32 s22, s22, s37
	v_lshlrev_b32_e32 v35, 2, v10
	v_xor_b32_e32 v10, 16, v108
	v_add_u32_e32 v20, s8, v22
	v_add_u32_e32 v24, s22, v22
	v_cmp_eq_u32_e64 s[0:1], 0, v12
	v_cmp_lt_i32_e32 vcc, v10, v9
	v_ashrrev_i32_e32 v23, 31, v22
	v_mul_lo_u32 v13, v22, s52
	v_lshlrev_b32_e32 v12, 4, v12
	v_add_u32_e32 v26, s21, v22
	v_ashrrev_i32_e32 v17, 31, v16
	v_ashrrev_i32_e32 v21, 31, v20
	v_ashrrev_i32_e32 v25, 31, v24
	v_cndmask_b32_e32 v9, v108, v10, vcc
	v_add_u32_e32 v8, s20, v8
	v_lshlrev_b64 v[10:11], 12, v[22:23]
	v_add3_u32 v37, v13, v12, 32
	v_lshlrev_b32_e32 v12, 1, v26
	v_lshlrev_b64 v[14:15], 12, v[16:17]
	v_lshlrev_b32_e32 v16, 1, v16
	v_lshlrev_b64 v[18:19], 12, v[20:21]
	v_lshlrev_b32_e32 v20, 1, v20
	v_lshlrev_b64 v[22:23], 12, v[24:25]
	v_lshlrev_b32_e32 v24, 1, v24
	v_ashrrev_i32_e32 v27, 31, v26
	v_lshlrev_b32_e32 v36, 2, v9
	v_ashrrev_i32_e32 v9, 31, v8
	v_ashrrev_i32_e32 v13, 31, v12
	v_ashrrev_i32_e32 v17, 31, v16
	v_ashrrev_i32_e32 v21, 31, v20
	v_ashrrev_i32_e32 v25, 31, v24
	v_lshlrev_b64 v[26:27], 12, v[26:27]
	v_lshlrev_b64 v[8:9], 2, v[8:9]
	v_lshl_add_u64 v[10:11], s[58:59], 0, v[10:11]
	v_lshl_add_u64 v[12:13], v[12:13], 2, s[30:31]
	v_lshl_add_u64 v[14:15], s[28:29], 0, v[14:15]
	v_lshl_add_u64 v[16:17], v[16:17], 2, s[30:31]
	v_lshl_add_u64 v[18:19], s[28:29], 0, v[18:19]
	v_lshl_add_u64 v[20:21], v[20:21], 2, s[30:31]
	v_lshl_add_u64 v[22:23], s[28:29], 0, v[22:23]
	v_lshl_add_u64 v[24:25], v[24:25], 2, s[30:31]
	v_lshl_add_u64 v[26:27], s[6:7], 0, v[26:27]
	s_mov_b64 s[20:21], 0
	s_branch .LBB0_2065

.LBB0_2185:
	s_ashr_i32 s4, s59, 3
	s_add_i32 s2, s4, s57
	s_and_b32 s5, s59, 7
	s_or_b32 s5, s5, s37
	s_lshl_b32 s39, s2, 6
	s_or_b32 s5, s5, s39
	s_lshl_b32 s60, s5, 7
	v_mov_b32_e32 v102, v234
	s_waitcnt vmcnt(6)
	v_mov_b32_e32 v33, v234
	s_and_b32 s22, s60, 0x1f80
	s_lshl_b32 s48, s5, 1
	v_ashrrev_i32_e32 v32, 3, v33
	v_add_u32_e32 v0, s22, v32
	v_ashrrev_i32_e32 v1, 31, v0
	v_lshlrev_b64 v[0:1], 11, v[0:1]
	v_lshlrev_b32_e32 v2, 4, v33
	v_lshl_add_u64 v[0:1], s[16:17], 0, v[0:1]
	v_and_b32_e32 v96, 0x70, v2
	s_waitcnt vmcnt(5)
	v_lshl_add_u64 v[34:35], v[0:1], 0, v[96:97]
	s_and_b32 s38, s48, 0xffffff80
	s_waitcnt vmcnt(4) lgkmcnt(1)
	v_add_co_u32_e32 v38, vcc, s51, v34
	v_add_u32_e32 v0, s38, v32
	s_waitcnt lgkmcnt(0)
	v_addc_co_u32_e32 v39, vcc, 0, v35, vcc
	v_ashrrev_i32_e32 v1, 31, v0
	v_add_co_u32_e32 v40, vcc, s52, v34
	v_lshlrev_b64 v[0:1], 11, v[0:1]
	s_nop 0
	v_addc_co_u32_e32 v41, vcc, 0, v35, vcc
	v_lshl_add_u64 v[0:1], s[18:19], 0, v[0:1]
	v_add_co_u32_e32 v42, vcc, s53, v34
	v_lshl_add_u64 v[36:37], v[0:1], 0, v[96:97]
	s_nop 0
	v_addc_co_u32_e32 v43, vcc, 0, v35, vcc
	v_add_co_u32_e32 v44, vcc, s51, v36
	s_nop 1
	v_addc_co_u32_e32 v45, vcc, 0, v37, vcc
	v_add_co_u32_e32 v46, vcc, s52, v36
	s_barrier
	global_load_dwordx4 v[0:3], v[34:35], off
	global_load_dwordx4 v[4:7], v[38:39], off
	global_load_dwordx4 v[8:11], v[40:41], off
	global_load_dwordx4 v[12:15], v[42:43], off
	global_load_dwordx4 v[16:19], v[36:37], off
	v_addc_co_u32_e32 v47, vcc, 0, v37, vcc
	v_add_co_u32_e32 v48, vcc, s53, v36
	global_load_dwordx4 v[20:23], v[44:45], off
	global_load_dwordx4 v[24:27], v[46:47], off
	v_addc_co_u32_e32 v49, vcc, 0, v37, vcc
	global_load_dwordx4 v[28:31], v[48:49], off
	global_load_dwordx4 v[68:71], v[34:35], off offset:128
	global_load_dwordx4 v[64:67], v[36:37], off offset:128
	global_load_dwordx4 v[84:87], v[38:39], off offset:128
	global_load_dwordx4 v[88:91], v[40:41], off offset:128
	global_load_dwordx4 v[92:95], v[42:43], off offset:128
	global_load_dwordx4 v[72:75], v[44:45], off offset:128
	global_load_dwordx4 v[76:79], v[46:47], off offset:128
	global_load_dwordx4 v[80:83], v[48:49], off offset:128
	s_add_i32 s4, s56, s4
	v_mul_lo_u32 v52, v32, s54
	s_lshl_b32 s4, s4, 6
	s_and_b32 s5, s58, 7
	v_add3_u32 v105, 32, v52, v96
	s_or_b32 s4, s37, s4
	s_add_i32 s4, s4, s5
	s_mov_b32 s6, 0xfffffc0
	v_lshrrev_b32_e32 v50, 1, v33
	v_and_b32_e32 v51, 31, v33
	s_lshl_b32 s4, s4, 1
	s_add_i32 s7, s50, s5
	v_and_or_b32 v51, v50, s6, v51
	v_and_b32_e32 v50, 16, v50
	s_and_b32 s4, s4, 0xffffff80
	s_and_b32 s7, s7, 63
	s_ashr_i32 s5, s4, 31
	s_lshl_b32 s7, s7, 18
	v_mul_lo_u32 v51, v51, s54
	v_add3_u32 v103, 32, v51, v50
	v_add_u32_e32 v106, 0xd800, v105
	s_waitcnt vmcnt(15)
	ds_write_b128 v105, v[0:3]
	s_waitcnt vmcnt(11)
	ds_write_b128 v105, v[16:19] offset:36864
	ds_write_b128 v105, v[4:7] offset:4608
	ds_write_b128 v105, v[8:11] offset:9216
	ds_write_b128 v105, v[12:15] offset:13824
	s_waitcnt vmcnt(10)
	ds_write_b128 v105, v[20:23] offset:41472
	s_waitcnt vmcnt(9)
	ds_write_b128 v105, v[24:27] offset:46080
	s_waitcnt vmcnt(8)
	ds_write_b128 v105, v[28:31] offset:50688
	v_and_b32_e32 v0, 0x5f, v33
	v_mul_u32_u24_e32 v0, 0x48, v0
	v_lshlrev_b32_e32 v0, 1, v0
	v_add3_u32 v104, 32, v0, v50
	v_and_b32_e32 v0, 7, v33
	v_ashrrev_i32_e32 v33, 31, v32
	v_lshlrev_b32_e32 v96, 4, v0
	v_lshl_add_u64 v[0:1], v[32:33], 0, s[4:5]
	v_lshlrev_b64 v[0:1], 11, v[0:1]
	s_add_u32 s4, s30, s7
	v_lshl_add_u64 v[98:99], s[30:31], 0, v[0:1]
	v_lshlrev_b64 v[0:1], 11, v[32:33]
	s_addc_u32 s5, s31, 0
	v_lshl_add_u64 v[100:101], s[4:5], 0, v[0:1]
	v_mov_b32_e32 v0, 0
	s_mov_b32 s4, -2
	v_mov_b32_e32 v1, v0
	v_mov_b32_e32 v2, v0
	v_mov_b32_e32 v3, v0
	v_mov_b32_e32 v4, v0
	v_mov_b32_e32 v5, v0
	v_mov_b32_e32 v6, v0
	v_mov_b32_e32 v7, v0
	v_mov_b32_e32 v8, v0
	v_mov_b32_e32 v9, v0
	v_mov_b32_e32 v10, v0
	v_mov_b32_e32 v11, v0
	v_mov_b32_e32 v12, v0
	v_mov_b32_e32 v13, v0
	v_mov_b32_e32 v14, v0
	v_mov_b32_e32 v15, v0
	v_mov_b32_e32 v16, v0
	v_mov_b32_e32 v17, v0
	v_mov_b32_e32 v18, v0
	v_mov_b32_e32 v19, v0
	v_mov_b32_e32 v20, v0
	v_mov_b32_e32 v21, v0
	v_mov_b32_e32 v22, v0
	v_mov_b32_e32 v23, v0
	v_mov_b32_e32 v24, v0
	v_mov_b32_e32 v25, v0
	v_mov_b32_e32 v26, v0
	v_mov_b32_e32 v27, v0
	v_mov_b32_e32 v28, v0
	v_mov_b32_e32 v29, v0
	v_mov_b32_e32 v30, v0
	v_mov_b32_e32 v31, v0
	v_mov_b32_e32 v32, v0
	v_mov_b32_e32 v33, v0
	v_mov_b32_e32 v34, v0
	v_mov_b32_e32 v35, v0
	v_mov_b32_e32 v36, v0
	v_mov_b32_e32 v37, v0
	v_mov_b32_e32 v38, v0
	v_mov_b32_e32 v39, v0
	v_mov_b32_e32 v40, v0
	v_mov_b32_e32 v41, v0
	v_mov_b32_e32 v42, v0
	v_mov_b32_e32 v43, v0
	v_mov_b32_e32 v44, v0
	v_mov_b32_e32 v45, v0
	v_mov_b32_e32 v46, v0
	v_mov_b32_e32 v47, v0
	v_mov_b32_e32 v48, v0
	v_mov_b32_e32 v49, v0
	v_mov_b32_e32 v50, v0
	v_mov_b32_e32 v51, v0
	v_mov_b32_e32 v52, v0
	v_mov_b32_e32 v53, v0
	v_mov_b32_e32 v54, v0
	v_mov_b32_e32 v55, v0
	v_mov_b32_e32 v56, v0
	v_mov_b32_e32 v57, v0
	v_mov_b32_e32 v58, v0
	v_mov_b32_e32 v59, v0
	v_mov_b32_e32 v60, v0
	v_mov_b32_e32 v61, v0
	v_mov_b32_e32 v62, v0
	v_mov_b32_e32 v63, v0
	v_lshl_add_u64 v[116:117], v[100:101], 0, v[96:97]
	s_mov_b32 s5, 0xc793000
	v_add_co_u32_e32 v168, vcc, s5, v116
	s_mov_b32 s5, 0xc7a3000
	s_nop 0
	v_addc_co_u32_e32 v169, vcc, 0, v117, vcc
	v_add_co_u32_e32 v170, vcc, s5, v116
	s_mov_b32 s5, 0xc7b3000
	s_nop 0
	v_addc_co_u32_e32 v171, vcc, 0, v117, vcc
	v_add_co_u32_e32 v172, vcc, s5, v116
	s_mov_b32 s5, 0xc7c3000
	s_nop 0
	v_addc_co_u32_e32 v173, vcc, 0, v117, vcc
	v_add_co_u32_e32 v174, vcc, s5, v116
	v_lshl_add_u64 v[132:133], v[98:99], 0, v[96:97]
	s_nop 0
	v_addc_co_u32_e32 v175, vcc, 0, v117, vcc
	s_mov_b32 s5, 0x2f93000
	v_add_co_u32_e32 v176, vcc, s5, v132
	s_mov_b32 s5, 0x2fa3000
	s_nop 0
	v_addc_co_u32_e32 v177, vcc, 0, v133, vcc
	v_add_co_u32_e32 v178, vcc, s5, v132
	s_mov_b32 s5, 0x2fb3000
	s_nop 0
	v_addc_co_u32_e32 v179, vcc, 0, v133, vcc
	v_add_co_u32_e32 v180, vcc, s5, v132
	s_mov_b32 s5, 0x2fc3000
	s_nop 0
	v_addc_co_u32_e32 v181, vcc, 0, v133, vcc
	v_add_co_u32_e32 v182, vcc, s5, v132
	s_nop 1
	v_addc_co_u32_e32 v183, vcc, 0, v133, vcc
	v_subrev_u32_e32 v168, s30, v168
	v_subrev_u32_e32 v170, s30, v170
	v_subrev_u32_e32 v172, s30, v172
	v_subrev_u32_e32 v174, s30, v174
	v_subrev_u32_e32 v176, s30, v176
	v_subrev_u32_e32 v178, s30, v178
	v_subrev_u32_e32 v180, s30, v180
	v_subrev_u32_e32 v182, s30, v182
	s_mov_b64 s[98:99], s[30:31]
	s_waitcnt lgkmcnt(0)
	s_barrier
.LBB0_2186:
	s_setprio 1
	ds_read_b128 v[140:143], v103
	ds_read_b128 v[144:147], v104 offset:36864
	ds_read_b128 v[148:151], v103 offset:32
	ds_read_b128 v[152:155], v104 offset:36896
	ds_read_b128 v[156:159], v104 offset:41472
	ds_read_b128 v[160:163], v104 offset:41504
	s_waitcnt lgkmcnt(4)
	v_mfma_f32_32x32x16_bf16 v[48:63], v[140:143], v[144:147], v[48:63]
	global_load_dwordx4 v[108:111], v168, s[98:99] offset:3840
	global_load_dwordx4 v[112:115], v170, s[98:99] offset:3840
	s_waitcnt lgkmcnt(1)
	v_mfma_f32_32x32x16_bf16 v[32:47], v[140:143], v[156:159], v[32:47]
	global_load_dwordx4 v[116:119], v172, s[98:99] offset:3840
	global_load_dwordx4 v[120:123], v174, s[98:99] offset:3840
	ds_read_b128 v[140:143], v103 offset:4608
	ds_read_b128 v[164:167], v103 offset:4640
	s_waitcnt lgkmcnt(1)
	v_mfma_f32_32x32x16_bf16 v[16:31], v[140:143], v[144:147], v[16:31]
	global_load_dwordx4 v[124:127], v176, s[98:99] offset:3840
	global_load_dwordx4 v[128:131], v178, s[98:99] offset:3840
	v_mfma_f32_32x32x16_bf16 v[0:15], v[140:143], v[156:159], v[0:15]
	global_load_dwordx4 v[132:135], v180, s[98:99] offset:3840
	global_load_dwordx4 v[136:139], v182, s[98:99] offset:3840
	v_mfma_f32_32x32x16_bf16 v[48:63], v[148:151], v[152:155], v[48:63]
	v_mfma_f32_32x32x16_bf16 v[32:47], v[148:151], v[160:163], v[32:47]
	s_waitcnt lgkmcnt(0)
	v_mfma_f32_32x32x16_bf16 v[16:31], v[164:167], v[152:155], v[16:31]
	ds_read_b128 v[140:143], v103 offset:64
	ds_read_b128 v[144:147], v104 offset:36928
	ds_read_b128 v[148:151], v103 offset:96
	ds_read_b128 v[152:155], v104 offset:36960
	v_mfma_f32_32x32x16_bf16 v[0:15], v[164:167], v[160:163], v[0:15]
	s_waitcnt vmcnt(15)
	ds_write_b128 v105, v[68:71] offset:18432
	ds_read_b128 v[156:159], v104 offset:41536
	ds_read_b128 v[160:163], v104 offset:41568
	s_waitcnt lgkmcnt(5)
	v_mfma_f32_32x32x16_bf16 v[48:63], v[140:143], v[144:147], v[48:63]
	s_waitcnt vmcnt(13)
	ds_write_b128 v105, v[84:87] offset:23040
	s_waitcnt lgkmcnt(2)
	v_mfma_f32_32x32x16_bf16 v[32:47], v[140:143], v[156:159], v[32:47]
	s_waitcnt vmcnt(12)
	ds_write_b128 v105, v[88:91] offset:27648
	ds_read_b128 v[140:143], v103 offset:4672
	ds_read_b128 v[164:167], v103 offset:4704
	s_waitcnt lgkmcnt(1)
	v_mfma_f32_32x32x16_bf16 v[16:31], v[140:143], v[144:147], v[16:31]
	s_waitcnt vmcnt(11)
	ds_write_b128 v105, v[92:95] offset:32256
	v_mfma_f32_32x32x16_bf16 v[0:15], v[140:143], v[156:159], v[0:15]
	ds_write_b128 v105, v[64:67] offset:55296
	v_mfma_f32_32x32x16_bf16 v[48:63], v[148:151], v[152:155], v[48:63]
	s_waitcnt vmcnt(10)
	ds_write_b128 v105, v[72:75] offset:59904
	v_mfma_f32_32x32x16_bf16 v[32:47], v[148:151], v[160:163], v[32:47]
	s_waitcnt vmcnt(9)
	ds_write_b128 v105, v[76:79] offset:64512
	s_waitcnt lgkmcnt(4)
	v_mfma_f32_32x32x16_bf16 v[16:31], v[164:167], v[152:155], v[16:31]
	s_waitcnt vmcnt(8)
	ds_write_b128 v106, v[80:83] offset:13824
	v_mfma_f32_32x32x16_bf16 v[0:15], v[164:167], v[160:163], v[0:15]
	s_setprio 0
	s_waitcnt lgkmcnt(0)
	s_barrier
	s_setprio 1
	ds_read_b128 v[140:143], v103 offset:18432
	ds_read_b128 v[144:147], v104 offset:55296
	ds_read_b128 v[148:151], v103 offset:18464
	ds_read_b128 v[152:155], v104 offset:55328
	ds_read_b128 v[156:159], v104 offset:59904
	ds_read_b128 v[160:163], v104 offset:59936
	s_waitcnt lgkmcnt(4)
	v_mfma_f32_32x32x16_bf16 v[48:63], v[140:143], v[144:147], v[48:63]
	global_load_dwordx4 v[68:71], v168, s[98:99] offset:3968
	global_load_dwordx4 v[84:87], v170, s[98:99] offset:3968
	s_waitcnt lgkmcnt(1)
	v_mfma_f32_32x32x16_bf16 v[32:47], v[140:143], v[156:159], v[32:47]
	global_load_dwordx4 v[88:91], v172, s[98:99] offset:3968
	global_load_dwordx4 v[92:95], v174, s[98:99] offset:3968
	ds_read_b128 v[140:143], v103 offset:23040
	ds_read_b128 v[164:167], v103 offset:23072
	s_waitcnt lgkmcnt(1)
	v_mfma_f32_32x32x16_bf16 v[16:31], v[140:143], v[144:147], v[16:31]
	global_load_dwordx4 v[64:67], v176, s[98:99] offset:3968
	global_load_dwordx4 v[72:75], v178, s[98:99] offset:3968
	v_mfma_f32_32x32x16_bf16 v[0:15], v[140:143], v[156:159], v[0:15]
	global_load_dwordx4 v[76:79], v180, s[98:99] offset:3968
	global_load_dwordx4 v[80:83], v182, s[98:99] offset:3968
	v_mfma_f32_32x32x16_bf16 v[48:63], v[148:151], v[152:155], v[48:63]
	v_mfma_f32_32x32x16_bf16 v[32:47], v[148:151], v[160:163], v[32:47]
	s_waitcnt lgkmcnt(0)
	v_mfma_f32_32x32x16_bf16 v[16:31], v[164:167], v[152:155], v[16:31]
	ds_read_b128 v[140:143], v103 offset:18496
	ds_read_b128 v[144:147], v104 offset:55360
	ds_read_b128 v[148:151], v103 offset:18528
	ds_read_b128 v[152:155], v104 offset:55392
	v_mfma_f32_32x32x16_bf16 v[0:15], v[164:167], v[160:163], v[0:15]
	s_add_u32 s98, s98, 0x100
	s_addc_u32 s99, s99, 0
	s_add_i32 s4, s4, 2
	s_cmp_lt_u32 s4, 11
	s_waitcnt vmcnt(15)
	ds_write_b128 v105, v[108:111]
	ds_read_b128 v[156:159], v104 offset:59968
	ds_read_b128 v[160:163], v104 offset:60000
	s_waitcnt lgkmcnt(5)
	v_mfma_f32_32x32x16_bf16 v[48:63], v[140:143], v[144:147], v[48:63]
	s_waitcnt vmcnt(14)
	ds_write_b128 v105, v[112:115] offset:4608
	s_waitcnt lgkmcnt(2)
	v_mfma_f32_32x32x16_bf16 v[32:47], v[140:143], v[156:159], v[32:47]
	s_waitcnt vmcnt(13)
	ds_write_b128 v105, v[116:119] offset:9216
	ds_read_b128 v[140:143], v103 offset:23104
	ds_read_b128 v[164:167], v103 offset:23136
	s_waitcnt lgkmcnt(1)
	v_mfma_f32_32x32x16_bf16 v[16:31], v[140:143], v[144:147], v[16:31]
	s_waitcnt vmcnt(12)
	ds_write_b128 v105, v[120:123] offset:13824
	v_mfma_f32_32x32x16_bf16 v[0:15], v[140:143], v[156:159], v[0:15]
	s_waitcnt vmcnt(11)
	ds_write_b128 v105, v[124:127] offset:36864
	v_mfma_f32_32x32x16_bf16 v[48:63], v[148:151], v[152:155], v[48:63]
	s_waitcnt vmcnt(10)
	ds_write_b128 v105, v[128:131] offset:41472
	v_mfma_f32_32x32x16_bf16 v[32:47], v[148:151], v[160:163], v[32:47]
	s_waitcnt vmcnt(9)
	ds_write_b128 v105, v[132:135] offset:46080
	s_waitcnt lgkmcnt(4)
	v_mfma_f32_32x32x16_bf16 v[16:31], v[164:167], v[152:155], v[16:31]
	s_waitcnt vmcnt(8)
	ds_write_b128 v105, v[136:139] offset:50688
	v_mfma_f32_32x32x16_bf16 v[0:15], v[164:167], v[160:163], v[0:15]
	s_setprio 0
	s_waitcnt lgkmcnt(0)
	s_barrier
	s_cbranch_scc1 .LBB0_2186
	s_setprio 1
	ds_read_b128 v[98:101], v103
	ds_read_b128 v[108:111], v104 offset:36864
	ds_read_b128 v[112:115], v103 offset:32
	ds_read_b128 v[116:119], v104 offset:36896
	ds_read_b128 v[120:123], v104 offset:41472
	ds_read_b128 v[124:127], v104 offset:41504
	s_waitcnt lgkmcnt(4)
	v_mfma_f32_32x32x16_bf16 v[48:63], v[98:101], v[108:111], v[48:63]
	s_waitcnt lgkmcnt(1)
	v_mfma_f32_32x32x16_bf16 v[32:47], v[98:101], v[120:123], v[32:47]
	ds_read_b128 v[98:101], v103 offset:4608
	ds_read_b128 v[128:131], v103 offset:4640
	s_waitcnt lgkmcnt(1)
	v_mfma_f32_32x32x16_bf16 v[16:31], v[98:101], v[108:111], v[16:31]
	v_mfma_f32_32x32x16_bf16 v[0:15], v[98:101], v[120:123], v[0:15]
	v_mfma_f32_32x32x16_bf16 v[48:63], v[112:115], v[116:119], v[48:63]
	v_mfma_f32_32x32x16_bf16 v[32:47], v[112:115], v[124:127], v[32:47]
	s_waitcnt lgkmcnt(0)
	v_mfma_f32_32x32x16_bf16 v[16:31], v[128:131], v[116:119], v[16:31]
	ds_read_b128 v[98:101], v103 offset:64
	ds_read_b128 v[108:111], v104 offset:36928
	ds_read_b128 v[112:115], v103 offset:96
	ds_read_b128 v[116:119], v104 offset:36960
	v_mfma_f32_32x32x16_bf16 v[0:15], v[128:131], v[124:127], v[0:15]
	s_waitcnt vmcnt(7)
	ds_write_b128 v105, v[68:71] offset:18432
	ds_read_b128 v[120:123], v104 offset:41536
	ds_read_b128 v[124:127], v104 offset:41568
	s_waitcnt lgkmcnt(5)
	v_mfma_f32_32x32x16_bf16 v[48:63], v[98:101], v[108:111], v[48:63]
	s_waitcnt vmcnt(6)
	ds_write_b128 v105, v[84:87] offset:23040
	s_waitcnt lgkmcnt(2)
	v_mfma_f32_32x32x16_bf16 v[32:47], v[98:101], v[120:123], v[32:47]
	s_waitcnt vmcnt(5)
	ds_write_b128 v105, v[88:91] offset:27648
	ds_read_b128 v[98:101], v103 offset:4672
	ds_read_b128 v[128:131], v103 offset:4704
	s_waitcnt lgkmcnt(1)
	v_mfma_f32_32x32x16_bf16 v[16:31], v[98:101], v[108:111], v[16:31]
	s_waitcnt vmcnt(4)
	ds_write_b128 v105, v[92:95] offset:32256
	v_mfma_f32_32x32x16_bf16 v[0:15], v[98:101], v[120:123], v[0:15]
	s_waitcnt vmcnt(3)
	ds_write_b128 v105, v[64:67] offset:55296
	v_mfma_f32_32x32x16_bf16 v[48:63], v[112:115], v[116:119], v[48:63]
	s_waitcnt vmcnt(2)
	ds_write_b128 v105, v[72:75] offset:59904
	v_mfma_f32_32x32x16_bf16 v[32:47], v[112:115], v[124:127], v[32:47]
	s_waitcnt vmcnt(1)
	ds_write_b128 v105, v[76:79] offset:64512
	s_waitcnt lgkmcnt(4)
	v_mfma_f32_32x32x16_bf16 v[16:31], v[128:131], v[116:119], v[16:31]
	s_waitcnt vmcnt(0)
	ds_write_b128 v106, v[80:83] offset:13824
	v_mfma_f32_32x32x16_bf16 v[0:15], v[128:131], v[124:127], v[0:15]
	s_setprio 0
	s_waitcnt lgkmcnt(0)
	s_barrier
	s_setprio 1
	ds_read_b128 v[64:67], v103 offset:18432
	ds_read_b128 v[68:71], v104 offset:55296
	ds_read_b128 v[72:75], v103 offset:18464
	ds_read_b128 v[76:79], v104 offset:55328
	ds_read_b128 v[80:83], v104 offset:59904
	ds_read_b128 v[84:87], v104 offset:59936
	s_waitcnt lgkmcnt(4)
	v_mfma_f32_32x32x16_bf16 v[48:63], v[64:67], v[68:71], v[48:63]
	s_waitcnt lgkmcnt(1)
	v_mfma_f32_32x32x16_bf16 v[32:47], v[64:67], v[80:83], v[32:47]
	ds_read_b128 v[64:67], v103 offset:23040
	ds_read_b128 v[88:91], v103 offset:23072
	s_waitcnt lgkmcnt(1)
	v_mfma_f32_32x32x16_bf16 v[16:31], v[64:67], v[68:71], v[16:31]
	v_mfma_f32_32x32x16_bf16 v[0:15], v[64:67], v[80:83], v[0:15]
	v_mfma_f32_32x32x16_bf16 v[48:63], v[72:75], v[76:79], v[48:63]
	v_mfma_f32_32x32x16_bf16 v[32:47], v[72:75], v[84:87], v[32:47]
	s_waitcnt lgkmcnt(0)
	v_mfma_f32_32x32x16_bf16 v[16:31], v[88:91], v[76:79], v[16:31]
	ds_read_b128 v[64:67], v103 offset:18496
	ds_read_b128 v[68:71], v104 offset:55360
	ds_read_b128 v[72:75], v103 offset:18528
	ds_read_b128 v[76:79], v104 offset:55392
	v_mfma_f32_32x32x16_bf16 v[0:15], v[88:91], v[84:87], v[0:15]
	ds_read_b128 v[80:83], v104 offset:59968
	ds_read_b128 v[84:87], v104 offset:60000
	s_waitcnt lgkmcnt(4)
	v_mfma_f32_32x32x16_bf16 v[48:63], v[64:67], v[68:71], v[48:63]
	s_waitcnt lgkmcnt(1)
	v_mfma_f32_32x32x16_bf16 v[32:47], v[64:67], v[80:83], v[32:47]
	ds_read_b128 v[64:67], v103 offset:23104
	ds_read_b128 v[88:91], v103 offset:23136
	s_waitcnt lgkmcnt(1)
	v_mfma_f32_32x32x16_bf16 v[16:31], v[64:67], v[68:71], v[16:31]
	v_mfma_f32_32x32x16_bf16 v[0:15], v[64:67], v[80:83], v[0:15]
	v_mfma_f32_32x32x16_bf16 v[48:63], v[72:75], v[76:79], v[48:63]
	v_mfma_f32_32x32x16_bf16 v[32:47], v[72:75], v[84:87], v[32:47]
	s_waitcnt lgkmcnt(0)
	v_mfma_f32_32x32x16_bf16 v[16:31], v[88:91], v[76:79], v[16:31]
	v_mfma_f32_32x32x16_bf16 v[0:15], v[88:91], v[84:87], v[0:15]
	s_setprio 0
	s_cmpk_gt_u32 s22, 0xfff
	s_cselect_b64 s[10:11], -1, 0
	s_cmpk_lt_u32 s22, 0x1000
	s_cselect_b64 s[40:41], -1, 0
	s_ashr_i32 s61, s2, 2
	s_cmp_lt_i32 s61, 7
	s_barrier
	s_cbranch_scc1 .LBB0_2189
	s_cmp_lg_u32 s61, 7
	s_cselect_b64 s[4:5], -1, 0
	s_cbranch_execz .LBB0_2190
	s_branch .LBB0_2191

.LBB0_3733:
	s_cmp_eq_u32 s26, 1
	s_cselect_b32 s16, s55, 0x8b93e00
	s_cmp_lg_u32 s26, 0
	s_cselect_b64 s[44:45], -1, 0
	s_waitcnt vmcnt(6)
	v_mov_b32_e32 v33, v234
	s_and_b64 s[0:1], s[44:45], exec
	s_cselect_b32 s0, s16, 0x8393e00
	v_ashrrev_i32_e32 v32, 3, v33
	v_add_u32_e32 v0, s63, v32
	s_add_u32 s0, s30, s0
	v_ashrrev_i32_e32 v1, 31, v0
	s_addc_u32 s1, s31, 0
	v_lshlrev_b64 v[0:1], 10, v[0:1]
	v_lshlrev_b32_e32 v2, 4, v33
	v_lshl_add_u64 v[0:1], s[0:1], 0, v[0:1]
	v_and_b32_e32 v96, 0x70, v2
	s_waitcnt vmcnt(5)
	v_lshl_add_u64 v[34:35], v[0:1], 0, v[96:97]
	s_mov_b32 s27, s17
	s_waitcnt vmcnt(4) lgkmcnt(1)
	v_add_co_u32_e32 v38, vcc, s56, v34
	s_lshl_b64 s[66:67], s[26:27], 20
	v_add_u32_e32 v0, s22, v32
	s_waitcnt lgkmcnt(0)
	v_addc_co_u32_e32 v39, vcc, 0, v35, vcc
	s_add_u32 s66, s33, s66
	v_ashrrev_i32_e32 v1, 31, v0
	v_add_co_u32_e32 v40, vcc, s57, v34
	s_addc_u32 s67, s46, s67
	v_lshlrev_b64 v[0:1], 10, v[0:1]
	v_addc_co_u32_e32 v41, vcc, 0, v35, vcc
	v_lshl_add_u64 v[0:1], s[66:67], 0, v[0:1]
	v_add_co_u32_e32 v42, vcc, s58, v34
	v_lshl_add_u64 v[36:37], v[0:1], 0, v[96:97]
	s_nop 0
	v_addc_co_u32_e32 v43, vcc, 0, v35, vcc
	v_add_co_u32_e32 v44, vcc, s56, v36
	s_nop 1
	v_addc_co_u32_e32 v45, vcc, 0, v37, vcc
	v_add_co_u32_e32 v46, vcc, s57, v36
	s_barrier
	s_nop 0
	v_addc_co_u32_e32 v47, vcc, 0, v37, vcc
	v_add_co_u32_e32 v48, vcc, s58, v36
	s_nop 1
	v_addc_co_u32_e32 v49, vcc, 0, v37, vcc
	global_load_dwordx4 v[0:3], v[34:35], off
	global_load_dwordx4 v[4:7], v[38:39], off
	global_load_dwordx4 v[8:11], v[40:41], off
	global_load_dwordx4 v[12:15], v[42:43], off
	global_load_dwordx4 v[16:19], v[36:37], off
	global_load_dwordx4 v[20:23], v[44:45], off
	global_load_dwordx4 v[24:27], v[46:47], off
	global_load_dwordx4 v[28:31], v[48:49], off
	global_load_dwordx4 v[64:67], v[34:35], off offset:128
	global_load_dwordx4 v[68:71], v[38:39], off offset:128
	global_load_dwordx4 v[72:75], v[40:41], off offset:128
	global_load_dwordx4 v[76:79], v[42:43], off offset:128
	global_load_dwordx4 v[80:83], v[36:37], off offset:128
	global_load_dwordx4 v[84:87], v[44:45], off offset:128
	global_load_dwordx4 v[88:91], v[46:47], off offset:128
	global_load_dwordx4 v[92:95], v[48:49], off offset:128
	v_mul_lo_u32 v53, v32, s59
	v_add3_u32 v114, 32, v53, v96
	v_lshrrev_b32_e32 v50, 1, v33
	v_and_b32_e32 v51, 31, v33
	v_and_b32_e32 v52, 0x5f, v33
	v_and_or_b32 v51, v50, s53, v51
	v_mul_u32_u24_e32 v52, 0x48, v52
	v_and_b32_e32 v50, 16, v50
	v_mul_lo_u32 v51, v51, s59
	v_lshlrev_b32_e32 v52, 1, v52
	v_add3_u32 v112, 32, v51, v50
	v_add3_u32 v113, 32, v52, v50
	v_add_u32_e32 v115, 0xd800, v114
	s_waitcnt vmcnt(15)
	ds_write_b128 v114, v[0:3]
	s_waitcnt vmcnt(14)
	ds_write_b128 v114, v[4:7] offset:4608
	s_waitcnt vmcnt(13)
	ds_write_b128 v114, v[8:11] offset:9216
	s_waitcnt vmcnt(12)
	ds_write_b128 v114, v[12:15] offset:13824
	s_waitcnt vmcnt(11)
	ds_write_b128 v114, v[16:19] offset:36864
	s_waitcnt vmcnt(10)
	ds_write_b128 v114, v[20:23] offset:41472
	s_waitcnt vmcnt(9)
	ds_write_b128 v114, v[24:27] offset:46080
	s_waitcnt vmcnt(8)
	ds_write_b128 v114, v[28:31] offset:50688
	v_and_b32_e32 v0, 7, v33
	v_ashrrev_i32_e32 v33, 31, v32
	v_lshlrev_b32_e32 v96, 4, v0
	v_lshl_add_u64 v[0:1], s[20:21], 0, v[32:33]
	v_add_u32_e32 v2, s65, v32
	v_lshlrev_b64 v[0:1], 10, v[0:1]
	v_ashrrev_i32_e32 v3, 31, v2
	v_lshl_add_u64 v[98:99], s[42:43], 0, v[0:1]
	v_lshl_add_u64 v[100:101], s[40:41], 0, v[0:1]
	v_lshl_add_u64 v[102:103], s[38:39], 0, v[0:1]
	v_lshl_add_u64 v[104:105], s[36:37], 0, v[0:1]
	v_lshlrev_b64 v[2:3], 10, v[2:3]
	v_lshl_add_u64 v[108:109], s[34:35], 0, v[0:1]
	v_mov_b32_e32 v0, 0
	v_lshl_add_u64 v[106:107], s[0:1], 0, v[2:3]
	s_mov_b32 s0, -2
	v_mov_b32_e32 v1, v0
	v_mov_b32_e32 v2, v0
	v_mov_b32_e32 v3, v0
	v_mov_b32_e32 v4, v0
	v_mov_b32_e32 v5, v0
	v_mov_b32_e32 v6, v0
	v_mov_b32_e32 v7, v0
	v_mov_b32_e32 v8, v0
	v_mov_b32_e32 v9, v0
	v_mov_b32_e32 v10, v0
	v_mov_b32_e32 v11, v0
	v_mov_b32_e32 v12, v0
	v_mov_b32_e32 v13, v0
	v_mov_b32_e32 v14, v0
	v_mov_b32_e32 v15, v0
	v_mov_b32_e32 v16, v0
	v_mov_b32_e32 v17, v0
	v_mov_b32_e32 v18, v0
	v_mov_b32_e32 v19, v0
	v_mov_b32_e32 v20, v0
	v_mov_b32_e32 v21, v0
	v_mov_b32_e32 v22, v0
	v_mov_b32_e32 v23, v0
	v_mov_b32_e32 v24, v0
	v_mov_b32_e32 v25, v0
	v_mov_b32_e32 v26, v0
	v_mov_b32_e32 v27, v0
	v_mov_b32_e32 v28, v0
	v_mov_b32_e32 v29, v0
	v_mov_b32_e32 v30, v0
	v_mov_b32_e32 v31, v0
	v_mov_b32_e32 v32, v0
	v_mov_b32_e32 v33, v0
	v_mov_b32_e32 v34, v0
	v_mov_b32_e32 v35, v0
	v_mov_b32_e32 v36, v0
	v_mov_b32_e32 v37, v0
	v_mov_b32_e32 v38, v0
	v_mov_b32_e32 v39, v0
	v_mov_b32_e32 v40, v0
	v_mov_b32_e32 v41, v0
	v_mov_b32_e32 v42, v0
	v_mov_b32_e32 v43, v0
	v_mov_b32_e32 v44, v0
	v_mov_b32_e32 v45, v0
	v_mov_b32_e32 v46, v0
	v_mov_b32_e32 v47, v0
	v_mov_b32_e32 v48, v0
	v_mov_b32_e32 v49, v0
	v_mov_b32_e32 v50, v0
	v_mov_b32_e32 v51, v0
	v_mov_b32_e32 v52, v0
	v_mov_b32_e32 v53, v0
	v_mov_b32_e32 v54, v0
	v_mov_b32_e32 v55, v0
	v_mov_b32_e32 v56, v0
	v_mov_b32_e32 v57, v0
	v_mov_b32_e32 v58, v0
	v_mov_b32_e32 v59, v0
	v_mov_b32_e32 v60, v0
	v_mov_b32_e32 v61, v0
	v_mov_b32_e32 v62, v0
	v_mov_b32_e32 v63, v0
	v_lshl_add_u64 v[176:177], v[106:107], 0, v[96:97]
	v_add_co_u32_e32 v180, vcc, s56, v176
	v_lshl_add_u64 v[178:179], v[108:109], 0, v[96:97]
	s_nop 0
	v_addc_co_u32_e32 v181, vcc, 0, v177, vcc
	v_add_co_u32_e32 v182, vcc, s57, v176
	s_nop 0
	s_nop 0
	v_addc_co_u32_e32 v183, vcc, 0, v177, vcc
	v_add_co_u32_e32 v184, vcc, s58, v176
	s_nop 1
	v_addc_co_u32_e32 v185, vcc, 0, v177, vcc
	v_lshl_add_u64 v[136:137], v[104:105], 0, v[96:97]
	v_lshl_add_u64 v[186:187], v[100:101], 0, v[96:97]
	v_lshl_add_u64 v[188:189], v[98:99], 0, v[96:97]
	s_nop 0
	v_lshl_add_u64 v[192:193], v[102:103], 0, v[96:97]
	s_nop 0
	v_subrev_u32_e32 v98, s30, v136
	v_subrev_u32_e32 v99, s30, v192
	v_subrev_u32_e32 v176, s30, v176
	v_subrev_u32_e32 v180, s30, v180
	v_subrev_u32_e32 v182, s30, v182
	v_subrev_u32_e32 v184, s30, v184
	v_subrev_u32_e32 v178, s30, v178
	v_subrev_u32_e32 v186, s30, v186
	v_subrev_u32_e32 v188, s30, v188
	s_mov_b64 s[98:99], s[30:31]
	s_waitcnt lgkmcnt(0)
	s_barrier
.LBB0_3734:
	s_setprio 1
	ds_read_b128 v[148:151], v112
	ds_read_b128 v[152:155], v113 offset:36864
	ds_read_b128 v[156:159], v112 offset:32
	ds_read_b128 v[160:163], v113 offset:36896
	ds_read_b128 v[164:167], v113 offset:41472
	ds_read_b128 v[168:171], v113 offset:41504
	s_waitcnt lgkmcnt(4)
	v_mfma_f32_32x32x16_bf16 v[48:63], v[148:151], v[152:155], v[48:63]
	global_load_dwordx4 v[116:119], v176, s[98:99] offset:256
	global_load_dwordx4 v[120:123], v180, s[98:99] offset:256
	s_waitcnt lgkmcnt(1)
	v_mfma_f32_32x32x16_bf16 v[32:47], v[148:151], v[164:167], v[32:47]
	global_load_dwordx4 v[124:127], v182, s[98:99] offset:256
	global_load_dwordx4 v[128:131], v184, s[98:99] offset:256
	ds_read_b128 v[148:151], v112 offset:4608
	ds_read_b128 v[172:175], v112 offset:4640
	s_waitcnt lgkmcnt(1)
	v_mfma_f32_32x32x16_bf16 v[16:31], v[148:151], v[152:155], v[16:31]
	global_load_dwordx4 v[132:135], v178, s[98:99]
	global_load_dwordx4 v[136:139], v98, s[98:99]
	v_mfma_f32_32x32x16_bf16 v[0:15], v[148:151], v[164:167], v[0:15]
	global_load_dwordx4 v[140:143], v186, s[98:99]
	global_load_dwordx4 v[144:147], v188, s[98:99] offset:-128
	v_mfma_f32_32x32x16_bf16 v[48:63], v[156:159], v[160:163], v[48:63]
	v_mfma_f32_32x32x16_bf16 v[32:47], v[156:159], v[168:171], v[32:47]
	s_waitcnt lgkmcnt(0)
	v_mfma_f32_32x32x16_bf16 v[16:31], v[172:175], v[160:163], v[16:31]
	ds_read_b128 v[148:151], v112 offset:64
	ds_read_b128 v[152:155], v113 offset:36928
	ds_read_b128 v[156:159], v112 offset:96
	ds_read_b128 v[160:163], v113 offset:36960
	v_mfma_f32_32x32x16_bf16 v[0:15], v[172:175], v[168:171], v[0:15]
	s_waitcnt vmcnt(15)
	ds_write_b128 v114, v[64:67] offset:18432
	ds_read_b128 v[164:167], v113 offset:41536
	ds_read_b128 v[168:171], v113 offset:41568
	s_waitcnt lgkmcnt(5)
	v_mfma_f32_32x32x16_bf16 v[48:63], v[148:151], v[152:155], v[48:63]
	s_waitcnt vmcnt(14)
	ds_write_b128 v114, v[68:71] offset:23040
	s_waitcnt lgkmcnt(2)
	v_mfma_f32_32x32x16_bf16 v[32:47], v[148:151], v[164:167], v[32:47]
	s_waitcnt vmcnt(13)
	ds_write_b128 v114, v[72:75] offset:27648
	ds_read_b128 v[148:151], v112 offset:4672
	ds_read_b128 v[172:175], v112 offset:4704
	s_waitcnt lgkmcnt(1)
	v_mfma_f32_32x32x16_bf16 v[16:31], v[148:151], v[152:155], v[16:31]
	s_waitcnt vmcnt(12)
	ds_write_b128 v114, v[76:79] offset:32256
	v_mfma_f32_32x32x16_bf16 v[0:15], v[148:151], v[164:167], v[0:15]
	s_waitcnt vmcnt(11)
	ds_write_b128 v114, v[80:83] offset:55296
	v_mfma_f32_32x32x16_bf16 v[48:63], v[156:159], v[160:163], v[48:63]
	s_waitcnt vmcnt(10)
	ds_write_b128 v114, v[84:87] offset:59904
	v_mfma_f32_32x32x16_bf16 v[32:47], v[156:159], v[168:171], v[32:47]
	s_waitcnt vmcnt(9)
	ds_write_b128 v114, v[88:91] offset:64512
	s_waitcnt lgkmcnt(4)
	v_mfma_f32_32x32x16_bf16 v[16:31], v[172:175], v[160:163], v[16:31]
	s_waitcnt vmcnt(8)
	ds_write_b128 v115, v[92:95] offset:13824
	v_mfma_f32_32x32x16_bf16 v[0:15], v[172:175], v[168:171], v[0:15]
	s_setprio 0
	s_waitcnt lgkmcnt(0)
	s_barrier
	s_setprio 1
	ds_read_b128 v[148:151], v112 offset:18432
	ds_read_b128 v[152:155], v113 offset:55296
	ds_read_b128 v[156:159], v112 offset:18464
	ds_read_b128 v[160:163], v113 offset:55328
	ds_read_b128 v[164:167], v113 offset:59904
	ds_read_b128 v[168:171], v113 offset:59936
	s_waitcnt lgkmcnt(4)
	v_mfma_f32_32x32x16_bf16 v[48:63], v[148:151], v[152:155], v[48:63]
	global_load_dwordx4 v[64:67], v176, s[98:99] offset:384
	global_load_dwordx4 v[68:71], v180, s[98:99] offset:384
	s_waitcnt lgkmcnt(1)
	v_mfma_f32_32x32x16_bf16 v[32:47], v[148:151], v[164:167], v[32:47]
	global_load_dwordx4 v[72:75], v182, s[98:99] offset:384
	global_load_dwordx4 v[76:79], v184, s[98:99] offset:384
	ds_read_b128 v[148:151], v112 offset:23040
	ds_read_b128 v[172:175], v112 offset:23072
	s_waitcnt lgkmcnt(1)
	v_mfma_f32_32x32x16_bf16 v[16:31], v[148:151], v[152:155], v[16:31]
	global_load_dwordx4 v[80:83], v178, s[98:99] offset:128
	global_load_dwordx4 v[84:87], v99, s[98:99]
	v_mfma_f32_32x32x16_bf16 v[0:15], v[148:151], v[164:167], v[0:15]
	global_load_dwordx4 v[88:91], v186, s[98:99] offset:128
	global_load_dwordx4 v[92:95], v188, s[98:99]
	v_mfma_f32_32x32x16_bf16 v[48:63], v[156:159], v[160:163], v[48:63]
	v_mfma_f32_32x32x16_bf16 v[32:47], v[156:159], v[168:171], v[32:47]
	s_waitcnt lgkmcnt(0)
	v_mfma_f32_32x32x16_bf16 v[16:31], v[172:175], v[160:163], v[16:31]
	ds_read_b128 v[148:151], v112 offset:18496
	ds_read_b128 v[152:155], v113 offset:55360
	ds_read_b128 v[156:159], v112 offset:18528
	ds_read_b128 v[160:163], v113 offset:55392
	v_mfma_f32_32x32x16_bf16 v[0:15], v[172:175], v[168:171], v[0:15]
	s_add_u32 s98, s98, 0x100
	s_addc_u32 s99, s99, 0
	s_add_i32 s0, s0, 2
	s_cmp_lt_u32 s0, 3
	s_waitcnt vmcnt(15)
	ds_write_b128 v114, v[116:119]
	ds_read_b128 v[164:167], v113 offset:59968
	ds_read_b128 v[168:171], v113 offset:60000
	s_waitcnt lgkmcnt(5)
	v_mfma_f32_32x32x16_bf16 v[48:63], v[148:151], v[152:155], v[48:63]
	s_waitcnt vmcnt(14)
	ds_write_b128 v114, v[120:123] offset:4608
	s_waitcnt lgkmcnt(2)
	v_mfma_f32_32x32x16_bf16 v[32:47], v[148:151], v[164:167], v[32:47]
	s_waitcnt vmcnt(13)
	ds_write_b128 v114, v[124:127] offset:9216
	ds_read_b128 v[148:151], v112 offset:23104
	ds_read_b128 v[172:175], v112 offset:23136
	s_waitcnt lgkmcnt(1)
	v_mfma_f32_32x32x16_bf16 v[16:31], v[148:151], v[152:155], v[16:31]
	s_waitcnt vmcnt(12)
	ds_write_b128 v114, v[128:131] offset:13824
	v_mfma_f32_32x32x16_bf16 v[0:15], v[148:151], v[164:167], v[0:15]
	s_waitcnt vmcnt(11)
	ds_write_b128 v114, v[132:135] offset:36864
	v_mfma_f32_32x32x16_bf16 v[48:63], v[156:159], v[160:163], v[48:63]
	s_waitcnt vmcnt(10)
	ds_write_b128 v114, v[136:139] offset:41472
	v_mfma_f32_32x32x16_bf16 v[32:47], v[156:159], v[168:171], v[32:47]
	s_waitcnt vmcnt(9)
	ds_write_b128 v114, v[140:143] offset:46080
	s_waitcnt lgkmcnt(4)
	v_mfma_f32_32x32x16_bf16 v[16:31], v[172:175], v[160:163], v[16:31]
	s_waitcnt vmcnt(8)
	ds_write_b128 v114, v[144:147] offset:50688
	v_mfma_f32_32x32x16_bf16 v[0:15], v[172:175], v[168:171], v[0:15]
	s_setprio 0
	s_waitcnt lgkmcnt(0)
	s_barrier
	s_cbranch_scc1 .LBB0_3734
	s_setprio 1
	ds_read_b128 v[98:101], v112
	ds_read_b128 v[102:105], v113 offset:36864
	ds_read_b128 v[106:109], v112 offset:32
	ds_read_b128 v[116:119], v113 offset:36896
	ds_read_b128 v[120:123], v113 offset:41472
	ds_read_b128 v[124:127], v113 offset:41504
	s_waitcnt lgkmcnt(4)
	v_mfma_f32_32x32x16_bf16 v[48:63], v[98:101], v[102:105], v[48:63]
	s_waitcnt lgkmcnt(1)
	v_mfma_f32_32x32x16_bf16 v[32:47], v[98:101], v[120:123], v[32:47]
	ds_read_b128 v[98:101], v112 offset:4608
	ds_read_b128 v[128:131], v112 offset:4640
	s_waitcnt lgkmcnt(1)
	v_mfma_f32_32x32x16_bf16 v[16:31], v[98:101], v[102:105], v[16:31]
	v_mfma_f32_32x32x16_bf16 v[0:15], v[98:101], v[120:123], v[0:15]
	v_mfma_f32_32x32x16_bf16 v[48:63], v[106:109], v[116:119], v[48:63]
	v_mfma_f32_32x32x16_bf16 v[32:47], v[106:109], v[124:127], v[32:47]
	s_waitcnt lgkmcnt(0)
	v_mfma_f32_32x32x16_bf16 v[16:31], v[128:131], v[116:119], v[16:31]
	ds_read_b128 v[98:101], v112 offset:64
	ds_read_b128 v[102:105], v113 offset:36928
	ds_read_b128 v[106:109], v112 offset:96
	ds_read_b128 v[116:119], v113 offset:36960
	v_mfma_f32_32x32x16_bf16 v[0:15], v[128:131], v[124:127], v[0:15]
	s_waitcnt vmcnt(7)
	ds_write_b128 v114, v[64:67] offset:18432
	ds_read_b128 v[120:123], v113 offset:41536
	ds_read_b128 v[124:127], v113 offset:41568
	s_waitcnt lgkmcnt(5)
	v_mfma_f32_32x32x16_bf16 v[48:63], v[98:101], v[102:105], v[48:63]
	s_waitcnt vmcnt(6)
	ds_write_b128 v114, v[68:71] offset:23040
	s_waitcnt lgkmcnt(2)
	v_mfma_f32_32x32x16_bf16 v[32:47], v[98:101], v[120:123], v[32:47]
	s_waitcnt vmcnt(5)
	ds_write_b128 v114, v[72:75] offset:27648
	ds_read_b128 v[98:101], v112 offset:4672
	ds_read_b128 v[128:131], v112 offset:4704
	s_waitcnt lgkmcnt(1)
	v_mfma_f32_32x32x16_bf16 v[16:31], v[98:101], v[102:105], v[16:31]
	s_waitcnt vmcnt(4)
	ds_write_b128 v114, v[76:79] offset:32256
	v_mfma_f32_32x32x16_bf16 v[0:15], v[98:101], v[120:123], v[0:15]
	s_waitcnt vmcnt(3)
	ds_write_b128 v114, v[80:83] offset:55296
	s_waitcnt lgkmcnt(2)
	v_mfma_f32_32x32x16_bf16 v[16:31], v[128:131], v[116:119], v[16:31]
	s_waitcnt vmcnt(2)
	ds_write_b128 v114, v[84:87] offset:59904
	v_mfma_f32_32x32x16_bf16 v[0:15], v[128:131], v[124:127], v[0:15]
	s_waitcnt vmcnt(1)
	ds_write_b128 v114, v[88:91] offset:64512
	v_mfma_f32_32x32x16_bf16 v[48:63], v[106:109], v[116:119], v[48:63]
	s_waitcnt vmcnt(0)
	ds_write_b128 v115, v[92:95] offset:13824
	v_mfma_f32_32x32x16_bf16 v[32:47], v[106:109], v[124:127], v[32:47]
	s_setprio 0
	s_waitcnt lgkmcnt(0)
	s_barrier
	s_setprio 1
	ds_read_b128 v[64:67], v112 offset:18432
	ds_read_b128 v[68:71], v113 offset:55296
	ds_read_b128 v[72:75], v112 offset:18464
	ds_read_b128 v[76:79], v113 offset:55328
	ds_read_b128 v[80:83], v113 offset:59904
	ds_read_b128 v[84:87], v113 offset:59936
	s_waitcnt lgkmcnt(4)
	v_mfma_f32_32x32x16_bf16 v[48:63], v[64:67], v[68:71], v[48:63]
	s_waitcnt lgkmcnt(1)
	v_mfma_f32_32x32x16_bf16 v[32:47], v[64:67], v[80:83], v[32:47]
	ds_read_b128 v[64:67], v112 offset:23040
	ds_read_b128 v[88:91], v112 offset:23072
	s_waitcnt lgkmcnt(1)
	v_mfma_f32_32x32x16_bf16 v[16:31], v[64:67], v[68:71], v[16:31]
	v_mfma_f32_32x32x16_bf16 v[0:15], v[64:67], v[80:83], v[0:15]
	v_mfma_f32_32x32x16_bf16 v[48:63], v[72:75], v[76:79], v[48:63]
	v_mfma_f32_32x32x16_bf16 v[32:47], v[72:75], v[84:87], v[32:47]
	s_waitcnt lgkmcnt(0)
	v_mfma_f32_32x32x16_bf16 v[16:31], v[88:91], v[76:79], v[16:31]
	ds_read_b128 v[64:67], v112 offset:18496
	ds_read_b128 v[68:71], v113 offset:55360
	ds_read_b128 v[72:75], v112 offset:18528
	ds_read_b128 v[76:79], v113 offset:55392
	v_mfma_f32_32x32x16_bf16 v[0:15], v[88:91], v[84:87], v[0:15]
	ds_read_b128 v[80:83], v113 offset:59968
	ds_read_b128 v[84:87], v113 offset:60000
	s_waitcnt lgkmcnt(4)
	v_mfma_f32_32x32x16_bf16 v[48:63], v[64:67], v[68:71], v[48:63]
	s_waitcnt lgkmcnt(1)
	v_mfma_f32_32x32x16_bf16 v[32:47], v[64:67], v[80:83], v[32:47]
	ds_read_b128 v[64:67], v112 offset:23104
	ds_read_b128 v[88:91], v112 offset:23136
	s_waitcnt lgkmcnt(1)
	v_mfma_f32_32x32x16_bf16 v[16:31], v[64:67], v[68:71], v[16:31]
	v_mfma_f32_32x32x16_bf16 v[0:15], v[64:67], v[80:83], v[0:15]
	s_waitcnt lgkmcnt(0)
	v_mfma_f32_32x32x16_bf16 v[16:31], v[88:91], v[76:79], v[16:31]
	v_mfma_f32_32x32x16_bf16 v[0:15], v[88:91], v[84:87], v[0:15]
	v_mfma_f32_32x32x16_bf16 v[48:63], v[72:75], v[76:79], v[48:63]
	v_mfma_f32_32x32x16_bf16 v[32:47], v[72:75], v[84:87], v[32:47]
	s_setprio 0
	s_nop 10
	v_cvt_pk_bf16_f32 v32, v32, s0
	v_cvt_pk_bf16_f32 v0, v0, s0
	s_barrier
	ds_write_b16 v111, v32 offset:64
	v_cvt_pk_bf16_f32 v32, v49, s0
	ds_write_b16 v111, v0 offset:8768
	v_cvt_pk_bf16_f32 v0, v17, s0
	ds_write_b16 v111, v32 offset:272
	v_cvt_pk_bf16_f32 v32, v33, s0
	ds_write_b16 v111, v0 offset:8976
	v_cvt_pk_bf16_f32 v0, v1, s0
	ds_write_b16 v111, v32 offset:336
	v_cvt_pk_bf16_f32 v32, v50, s0
	ds_write_b16 v111, v0 offset:9040
	v_cvt_pk_bf16_f32 v0, v18, s0
	ds_write_b16 v111, v32 offset:544
	v_cvt_pk_bf16_f32 v32, v34, s0
	ds_write_b16 v111, v0 offset:9248
	v_cvt_pk_bf16_f32 v0, v2, s0
	ds_write_b16 v111, v32 offset:608
	v_cvt_pk_bf16_f32 v32, v51, s0
	ds_write_b16 v111, v0 offset:9312
	v_cvt_pk_bf16_f32 v0, v19, s0
	ds_write_b16 v111, v32 offset:816
	v_cvt_pk_bf16_f32 v32, v35, s0
	ds_write_b16 v111, v0 offset:9520
	v_cvt_pk_bf16_f32 v0, v3, s0
	ds_write_b16 v111, v32 offset:880
	v_cvt_pk_bf16_f32 v32, v52, s0
	ds_write_b16 v111, v0 offset:9584
	v_cvt_pk_bf16_f32 v0, v20, s0
	ds_write_b16 v111, v32 offset:2176
	v_cvt_pk_bf16_f32 v32, v36, s0
	ds_write_b16 v111, v0 offset:10880
	v_cvt_pk_bf16_f32 v0, v4, s0
	ds_write_b16 v111, v32 offset:2240
	v_cvt_pk_bf16_f32 v32, v53, s0
	ds_write_b16 v111, v0 offset:10944
	v_cvt_pk_bf16_f32 v0, v21, s0
	ds_write_b16 v111, v32 offset:2448
	v_cvt_pk_bf16_f32 v32, v37, s0
	ds_write_b16 v111, v0 offset:11152
	v_cvt_pk_bf16_f32 v0, v5, s0
	ds_write_b16 v111, v32 offset:2512
	v_cvt_pk_bf16_f32 v32, v54, s0
	ds_write_b16 v111, v0 offset:11216
	v_cvt_pk_bf16_f32 v0, v22, s0
	ds_write_b16 v111, v32 offset:2720
	v_cvt_pk_bf16_f32 v32, v38, s0
	ds_write_b16 v111, v0 offset:11424
	v_cvt_pk_bf16_f32 v0, v6, s0
	ds_write_b16 v111, v32 offset:2784
	v_cvt_pk_bf16_f32 v32, v55, s0
	ds_write_b16 v111, v0 offset:11488
	v_cvt_pk_bf16_f32 v0, v23, s0
	ds_write_b16 v111, v32 offset:2992
	v_cvt_pk_bf16_f32 v32, v39, s0
	ds_write_b16 v111, v0 offset:11696
	v_cvt_pk_bf16_f32 v0, v7, s0
	ds_write_b16 v111, v32 offset:3056
	v_cvt_pk_bf16_f32 v32, v56, s0
	ds_write_b16 v111, v0 offset:11760
	v_cvt_pk_bf16_f32 v0, v24, s0
	ds_write_b16 v111, v32 offset:4352
	v_cvt_pk_bf16_f32 v32, v40, s0
	ds_write_b16 v111, v0 offset:13056
	v_cvt_pk_bf16_f32 v0, v8, s0
	ds_write_b16 v111, v32 offset:4416
	v_cvt_pk_bf16_f32 v32, v57, s0
	ds_write_b16 v111, v0 offset:13120
	v_cvt_pk_bf16_f32 v0, v25, s0
	ds_write_b16 v111, v32 offset:4624
	v_cvt_pk_bf16_f32 v32, v41, s0
	ds_write_b16 v111, v0 offset:13328
	v_cvt_pk_bf16_f32 v0, v9, s0
	ds_write_b16 v111, v32 offset:4688
	v_cvt_pk_bf16_f32 v32, v58, s0
	ds_write_b16 v111, v0 offset:13392
	v_cvt_pk_bf16_f32 v0, v26, s0
	ds_write_b16 v111, v32 offset:4896
	v_cvt_pk_bf16_f32 v32, v42, s0
	ds_write_b16 v111, v0 offset:13600
	v_cvt_pk_bf16_f32 v0, v10, s0
	ds_write_b16 v111, v32 offset:4960
	v_cvt_pk_bf16_f32 v32, v59, s0
	ds_write_b16 v111, v0 offset:13664
	v_cvt_pk_bf16_f32 v0, v27, s0
	ds_write_b16 v111, v32 offset:5168
	v_cvt_pk_bf16_f32 v32, v43, s0
	ds_write_b16 v111, v0 offset:13872
	v_cvt_pk_bf16_f32 v0, v11, s0
	ds_write_b16 v111, v32 offset:5232
	v_cvt_pk_bf16_f32 v32, v60, s0
	ds_write_b16 v111, v0 offset:13936
	v_cvt_pk_bf16_f32 v0, v28, s0
	ds_write_b16 v111, v32 offset:6528
	v_cvt_pk_bf16_f32 v32, v44, s0
	ds_write_b16 v111, v0 offset:15232
	v_cvt_pk_bf16_f32 v0, v12, s0
	ds_write_b16 v111, v32 offset:6592
	v_cvt_pk_bf16_f32 v32, v61, s0
	ds_write_b16 v111, v0 offset:15296
	v_cvt_pk_bf16_f32 v0, v29, s0
	ds_write_b16 v111, v32 offset:6800
	v_cvt_pk_bf16_f32 v32, v45, s0
	ds_write_b16 v111, v0 offset:15504
	v_cvt_pk_bf16_f32 v0, v13, s0
	ds_write_b16 v111, v32 offset:6864
	v_cvt_pk_bf16_f32 v32, v62, s0
	ds_write_b16 v111, v0 offset:15568
	v_cvt_pk_bf16_f32 v0, v30, s0
	ds_write_b16 v111, v32 offset:7072
	v_cvt_pk_bf16_f32 v32, v46, s0
	ds_write_b16 v111, v0 offset:15776
	v_cvt_pk_bf16_f32 v0, v14, s0
	ds_write_b16 v111, v32 offset:7136
	v_cvt_pk_bf16_f32 v32, v63, s0
	ds_write_b16 v111, v0 offset:15840
	v_cvt_pk_bf16_f32 v0, v31, s0
	v_cvt_pk_bf16_f32 v48, v48, s0
	ds_write_b16 v111, v32 offset:7344
	v_cvt_pk_bf16_f32 v32, v47, s0
	v_cvt_pk_bf16_f32 v16, v16, s0
	ds_write_b16 v111, v0 offset:16048
	v_cvt_pk_bf16_f32 v0, v15, s0
	v_mov_b32_e32 v15, v110
	ds_write_b16 v111, v48
	ds_write_b16 v111, v32 offset:7408
	ds_write_b16 v111, v16 offset:8704
	ds_write_b16 v111, v0 offset:16112
	s_waitcnt lgkmcnt(0)
	s_barrier
	v_mov_b64_e32 v[2:3], s[4:5]
	v_lshlrev_b32_e32 v0, 3, v15
	v_and_b32_e32 v0, 0x78, v0
	v_ashrrev_i32_e32 v1, 4, v15
	v_lshlrev_b32_e32 v96, 1, v0
	v_add_u32_e32 v0, s63, v1
	s_lshl_b32 s16, s26, 10
	v_mad_i64_i32 v[2:3], s[0:1], v0, s60, v[2:3]
	v_lshl_add_u64 v[2:3], s[16:17], 1, v[2:3]
	v_lshl_add_u64 v[2:3], s[22:23], 1, v[2:3]
	v_lshl_add_u64 v[2:3], v[2:3], 0, v[96:97]
	global_load_dwordx4 v[6:9], v[2:3], off
	v_add_u32_e32 v14, 32, v96
	v_mad_u64_u32 v[2:3], s[0:1], v1, s54, v[14:15]
	ds_read_b128 v[2:5], v2
	v_ashrrev_i32_e32 v1, 31, v0
	v_lshlrev_b64 v[0:1], 11, v[0:1]
	v_lshl_add_u64 v[0:1], s[24:25], 0, v[0:1]
	v_lshl_add_u64 v[16:17], v[0:1], 0, v[96:97]
	v_cndmask_b32_e64 v1, 0, 1, s[44:45]
	v_mov_b32_e32 v0, 0
	v_cmp_ne_u32_e64 s[0:1], 1, v1
	s_andn2_b64 vcc, exec, s[44:45]
	v_mov_b32_e32 v10, 0
	v_mov_b32_e32 v11, 0
	v_mov_b32_e32 v12, 0
	v_mov_b32_e32 v13, 0
	s_cbranch_vccnz .LBB0_3737
	global_load_dwordx4 v[10:13], v[16:17], off

.LBB0_3805:
	s_and_b32 s0, s57, 7
	s_or_b32 s1, s0, s3
	s_lshl_b32 s0, s57, 4
	v_mov_b32_e32 v0, v234
	s_waitcnt vmcnt(6)
	v_mov_b32_e32 v33, v234
	s_and_b32 s25, s0, 0xffffff80
	s_lshl_b32 s0, s1, 7
	s_waitcnt lgkmcnt(0)
	v_ashrrev_i32_e32 v32, 3, v33
	v_add_u32_e32 v0, s0, v32
	v_ashrrev_i32_e32 v1, 31, v0
	v_lshlrev_b64 v[0:1], 11, v[0:1]
	v_lshlrev_b32_e32 v2, 4, v33
	v_lshl_add_u64 v[0:1], s[4:5], 0, v[0:1]
	v_and_b32_e32 v96, 0x70, v2
	s_waitcnt vmcnt(5)
	v_lshl_add_u64 v[34:35], v[0:1], 0, v[96:97]
	s_waitcnt vmcnt(4)
	v_add_co_u32_e32 v38, vcc, s38, v34
	v_add_u32_e32 v0, s25, v32
	s_nop 0
	v_addc_co_u32_e32 v39, vcc, 0, v35, vcc
	v_ashrrev_i32_e32 v1, 31, v0
	v_add_co_u32_e32 v40, vcc, s39, v34
	v_lshlrev_b64 v[0:1], 11, v[0:1]
	s_nop 0
	v_addc_co_u32_e32 v41, vcc, 0, v35, vcc
	v_lshl_add_u64 v[0:1], s[6:7], 0, v[0:1]
	v_add_co_u32_e32 v42, vcc, s40, v34
	v_lshl_add_u64 v[36:37], v[0:1], 0, v[96:97]
	s_nop 0
	v_addc_co_u32_e32 v43, vcc, 0, v35, vcc
	v_add_co_u32_e32 v44, vcc, s38, v36
	s_barrier
	s_nop 0
	v_addc_co_u32_e32 v45, vcc, 0, v37, vcc
	v_add_co_u32_e32 v46, vcc, s39, v36
	s_nop 1
	v_addc_co_u32_e32 v47, vcc, 0, v37, vcc
	global_load_dwordx4 v[0:3], v[34:35], off
	global_load_dwordx4 v[4:7], v[38:39], off
	global_load_dwordx4 v[8:11], v[40:41], off
	global_load_dwordx4 v[12:15], v[42:43], off
	global_load_dwordx4 v[16:19], v[36:37], off
	v_add_co_u32_e32 v48, vcc, s40, v36
	global_load_dwordx4 v[20:23], v[44:45], off
	global_load_dwordx4 v[24:27], v[46:47], off
	v_addc_co_u32_e32 v49, vcc, 0, v37, vcc
	global_load_dwordx4 v[28:31], v[48:49], off
	global_load_dwordx4 v[68:71], v[34:35], off offset:128
	global_load_dwordx4 v[64:67], v[36:37], off offset:128
	global_load_dwordx4 v[84:87], v[38:39], off offset:128
	global_load_dwordx4 v[88:91], v[40:41], off offset:128
	global_load_dwordx4 v[92:95], v[42:43], off offset:128
	global_load_dwordx4 v[72:75], v[44:45], off offset:128
	global_load_dwordx4 v[76:79], v[46:47], off offset:128
	global_load_dwordx4 v[80:83], v[48:49], off offset:128
	v_and_b32_e32 v52, 0x5f, v33
	v_mul_lo_u32 v53, v32, s41
	v_lshrrev_b32_e32 v50, 1, v33
	v_and_b32_e32 v51, 31, v33
	v_mul_u32_u24_e32 v52, 0x48, v52
	v_add3_u32 v105, 32, v53, v96
	s_and_b32 s22, s27, 0xffffff80
	v_and_or_b32 v51, v50, s42, v51
	v_and_b32_e32 v50, 16, v50
	s_and_b32 s10, s26, 7
	s_ashr_i32 s23, s22, 31
	s_lshl_b32 s24, s10, 7
	v_mul_lo_u32 v51, v51, s41
	v_add3_u32 v103, 32, v51, v50
	v_add_u32_e32 v106, 0xd800, v105
	s_mov_b32 s10, -2
	v_mov_b32_e32 v34, v97
	v_mov_b32_e32 v35, v97
	v_mov_b32_e32 v36, v97
	v_mov_b32_e32 v37, v97
	v_mov_b32_e32 v38, v97
	v_mov_b32_e32 v39, v97
	v_mov_b32_e32 v40, v97
	v_mov_b32_e32 v41, v97
	v_mov_b32_e32 v42, v97
	v_mov_b32_e32 v43, v97
	v_mov_b32_e32 v44, v97
	v_mov_b32_e32 v45, v97
	v_mov_b32_e32 v46, v97
	v_mov_b32_e32 v47, v97
	v_mov_b32_e32 v48, v97
	v_mov_b32_e32 v49, v97
	v_mov_b32_e32 v51, v97
	v_mov_b32_e32 v53, v97
	v_mov_b32_e32 v54, v97
	v_mov_b32_e32 v55, v97
	v_mov_b32_e32 v56, v97
	s_waitcnt vmcnt(15)
	ds_write_b128 v105, v[0:3]
	s_waitcnt vmcnt(11)
	ds_write_b128 v105, v[16:19] offset:36864
	ds_write_b128 v105, v[4:7] offset:4608
	ds_write_b128 v105, v[8:11] offset:9216
	ds_write_b128 v105, v[12:15] offset:13824
	s_waitcnt vmcnt(10)
	ds_write_b128 v105, v[20:23] offset:41472
	s_waitcnt vmcnt(9)
	ds_write_b128 v105, v[24:27] offset:46080
	s_waitcnt vmcnt(8)
	ds_write_b128 v105, v[28:31] offset:50688
	v_lshlrev_b32_e32 v0, 1, v52
	v_add3_u32 v104, 32, v0, v50
	v_and_b32_e32 v0, 7, v33
	v_ashrrev_i32_e32 v33, 31, v32
	v_lshlrev_b32_e32 v96, 4, v0
	v_lshl_add_u64 v[0:1], v[32:33], 0, s[22:23]
	v_lshlrev_b64 v[0:1], 11, v[0:1]
	s_add_i32 s23, s24, s34
	v_lshl_add_u64 v[98:99], s[30:31], 0, v[0:1]
	v_add_u32_e32 v0, s23, v32
	v_ashrrev_i32_e32 v1, 31, v0
	v_lshlrev_b64 v[0:1], 11, v[0:1]
	v_lshl_add_u64 v[100:101], s[30:31], 0, v[0:1]
	v_mov_b32_e32 v0, v97
	v_mov_b32_e32 v1, v97
	v_mov_b32_e32 v2, v97
	v_mov_b32_e32 v3, v97
	v_mov_b32_e32 v4, v97
	v_mov_b32_e32 v5, v97
	v_mov_b32_e32 v6, v97
	v_mov_b32_e32 v7, v97
	v_mov_b32_e32 v8, v97
	v_mov_b32_e32 v9, v97
	v_mov_b32_e32 v10, v97
	v_mov_b32_e32 v11, v97
	v_mov_b32_e32 v12, v97
	v_mov_b32_e32 v13, v97
	v_mov_b32_e32 v14, v97
	v_mov_b32_e32 v15, v97
	v_mov_b32_e32 v16, v97
	v_mov_b32_e32 v17, v97
	v_mov_b32_e32 v18, v97
	v_mov_b32_e32 v19, v97
	v_mov_b32_e32 v20, v97
	v_mov_b32_e32 v21, v97
	v_mov_b32_e32 v22, v97
	v_mov_b32_e32 v23, v97
	v_mov_b32_e32 v24, v97
	v_mov_b32_e32 v25, v97
	v_mov_b32_e32 v26, v97
	v_mov_b32_e32 v27, v97
	v_mov_b32_e32 v28, v97
	v_mov_b32_e32 v29, v97
	v_mov_b32_e32 v30, v97
	v_mov_b32_e32 v31, v97
	v_mov_b32_e32 v32, v97
	v_mov_b32_e32 v33, v97
	v_mov_b32_e32 v50, v97
	v_mov_b32_e32 v52, v97
	v_mov_b32_e32 v57, v97
	v_mov_b32_e32 v58, v97
	v_mov_b32_e32 v59, v97
	v_mov_b32_e32 v60, v97
	v_mov_b32_e32 v61, v97
	v_mov_b32_e32 v62, v97
	v_mov_b32_e32 v63, v97
	v_lshl_add_u64 v[116:117], v[100:101], 0, v[96:97]
	v_add_co_u32_e32 v168, vcc, s43, v116
	v_lshl_add_u64 v[132:133], v[98:99], 0, v[96:97]
	s_nop 0
	v_addc_co_u32_e32 v169, vcc, 0, v117, vcc
	v_add_co_u32_e32 v170, vcc, s44, v116
	s_nop 1
	v_addc_co_u32_e32 v171, vcc, 0, v117, vcc
	v_add_co_u32_e32 v172, vcc, s45, v116
	s_nop 1
	v_addc_co_u32_e32 v173, vcc, 0, v117, vcc
	v_add_co_u32_e32 v174, vcc, s46, v116
	s_nop 1
	v_addc_co_u32_e32 v175, vcc, 0, v117, vcc
	v_add_co_u32_e32 v176, vcc, s47, v132
	s_nop 1
	v_addc_co_u32_e32 v177, vcc, 0, v133, vcc
	v_add_co_u32_e32 v178, vcc, s48, v132
	s_nop 1
	v_addc_co_u32_e32 v179, vcc, 0, v133, vcc
	v_add_co_u32_e32 v180, vcc, s49, v132
	s_nop 1
	v_addc_co_u32_e32 v181, vcc, 0, v133, vcc
	v_add_co_u32_e32 v182, vcc, s50, v132
	s_nop 1
	v_addc_co_u32_e32 v183, vcc, 0, v133, vcc
	v_subrev_u32_e32 v168, s30, v168
	v_subrev_u32_e32 v170, s30, v170
	v_subrev_u32_e32 v172, s30, v172
	v_subrev_u32_e32 v174, s30, v174
	v_subrev_u32_e32 v176, s30, v176
	v_subrev_u32_e32 v178, s30, v178
	v_subrev_u32_e32 v180, s30, v180
	v_subrev_u32_e32 v182, s30, v182
	s_mov_b64 s[98:99], s[30:31]
	s_waitcnt lgkmcnt(0)
	s_barrier
.LBB0_3806:
	s_setprio 1
	ds_read_b128 v[140:143], v103
	ds_read_b128 v[144:147], v104 offset:36864
	ds_read_b128 v[148:151], v103 offset:32
	ds_read_b128 v[152:155], v104 offset:36896
	ds_read_b128 v[156:159], v104 offset:41472
	ds_read_b128 v[160:163], v104 offset:41504
	s_waitcnt lgkmcnt(4)
	v_mfma_f32_32x32x16_bf16 v[48:63], v[140:143], v[144:147], v[48:63]
	global_load_dwordx4 v[108:111], v168, s[98:99] offset:3840
	global_load_dwordx4 v[112:115], v170, s[98:99] offset:3840
	s_waitcnt lgkmcnt(1)
	v_mfma_f32_32x32x16_bf16 v[32:47], v[140:143], v[156:159], v[32:47]
	global_load_dwordx4 v[116:119], v172, s[98:99] offset:3840
	global_load_dwordx4 v[120:123], v174, s[98:99] offset:3840
	ds_read_b128 v[140:143], v103 offset:4608
	ds_read_b128 v[164:167], v103 offset:4640
	s_waitcnt lgkmcnt(1)
	v_mfma_f32_32x32x16_bf16 v[16:31], v[140:143], v[144:147], v[16:31]
	global_load_dwordx4 v[124:127], v176, s[98:99] offset:3840
	global_load_dwordx4 v[128:131], v178, s[98:99] offset:3840
	v_mfma_f32_32x32x16_bf16 v[0:15], v[140:143], v[156:159], v[0:15]
	global_load_dwordx4 v[132:135], v180, s[98:99] offset:3840
	global_load_dwordx4 v[136:139], v182, s[98:99] offset:3840
	v_mfma_f32_32x32x16_bf16 v[48:63], v[148:151], v[152:155], v[48:63]
	v_mfma_f32_32x32x16_bf16 v[32:47], v[148:151], v[160:163], v[32:47]
	s_waitcnt lgkmcnt(0)
	v_mfma_f32_32x32x16_bf16 v[16:31], v[164:167], v[152:155], v[16:31]
	ds_read_b128 v[140:143], v103 offset:64
	ds_read_b128 v[144:147], v104 offset:36928
	ds_read_b128 v[148:151], v103 offset:96
	ds_read_b128 v[152:155], v104 offset:36960
	v_mfma_f32_32x32x16_bf16 v[0:15], v[164:167], v[160:163], v[0:15]
	s_waitcnt vmcnt(15)
	ds_write_b128 v105, v[68:71] offset:18432
	ds_read_b128 v[156:159], v104 offset:41536
	ds_read_b128 v[160:163], v104 offset:41568
	s_waitcnt lgkmcnt(5)
	v_mfma_f32_32x32x16_bf16 v[48:63], v[140:143], v[144:147], v[48:63]
	s_waitcnt vmcnt(13)
	ds_write_b128 v105, v[84:87] offset:23040
	s_waitcnt lgkmcnt(2)
	v_mfma_f32_32x32x16_bf16 v[32:47], v[140:143], v[156:159], v[32:47]
	s_waitcnt vmcnt(12)
	ds_write_b128 v105, v[88:91] offset:27648
	ds_read_b128 v[140:143], v103 offset:4672
	ds_read_b128 v[164:167], v103 offset:4704
	s_waitcnt lgkmcnt(1)
	v_mfma_f32_32x32x16_bf16 v[16:31], v[140:143], v[144:147], v[16:31]
	s_waitcnt vmcnt(11)
	ds_write_b128 v105, v[92:95] offset:32256
	v_mfma_f32_32x32x16_bf16 v[0:15], v[140:143], v[156:159], v[0:15]
	ds_write_b128 v105, v[64:67] offset:55296
	v_mfma_f32_32x32x16_bf16 v[48:63], v[148:151], v[152:155], v[48:63]
	s_waitcnt vmcnt(10)
	ds_write_b128 v105, v[72:75] offset:59904
	v_mfma_f32_32x32x16_bf16 v[32:47], v[148:151], v[160:163], v[32:47]
	s_waitcnt vmcnt(9)
	ds_write_b128 v105, v[76:79] offset:64512
	s_waitcnt lgkmcnt(4)
	v_mfma_f32_32x32x16_bf16 v[16:31], v[164:167], v[152:155], v[16:31]
	s_waitcnt vmcnt(8)
	ds_write_b128 v106, v[80:83] offset:13824
	v_mfma_f32_32x32x16_bf16 v[0:15], v[164:167], v[160:163], v[0:15]
	s_setprio 0
	s_waitcnt lgkmcnt(0)
	s_barrier
	s_setprio 1
	ds_read_b128 v[140:143], v103 offset:18432
	ds_read_b128 v[144:147], v104 offset:55296
	ds_read_b128 v[148:151], v103 offset:18464
	ds_read_b128 v[152:155], v104 offset:55328
	ds_read_b128 v[156:159], v104 offset:59904
	ds_read_b128 v[160:163], v104 offset:59936
	s_waitcnt lgkmcnt(4)
	v_mfma_f32_32x32x16_bf16 v[48:63], v[140:143], v[144:147], v[48:63]
	global_load_dwordx4 v[68:71], v168, s[98:99] offset:3968
	global_load_dwordx4 v[84:87], v170, s[98:99] offset:3968
	s_waitcnt lgkmcnt(1)
	v_mfma_f32_32x32x16_bf16 v[32:47], v[140:143], v[156:159], v[32:47]
	global_load_dwordx4 v[88:91], v172, s[98:99] offset:3968
	global_load_dwordx4 v[92:95], v174, s[98:99] offset:3968
	ds_read_b128 v[140:143], v103 offset:23040
	ds_read_b128 v[164:167], v103 offset:23072
	s_waitcnt lgkmcnt(1)
	v_mfma_f32_32x32x16_bf16 v[16:31], v[140:143], v[144:147], v[16:31]
	global_load_dwordx4 v[64:67], v176, s[98:99] offset:3968
	global_load_dwordx4 v[72:75], v178, s[98:99] offset:3968
	v_mfma_f32_32x32x16_bf16 v[0:15], v[140:143], v[156:159], v[0:15]
	global_load_dwordx4 v[76:79], v180, s[98:99] offset:3968
	global_load_dwordx4 v[80:83], v182, s[98:99] offset:3968
	v_mfma_f32_32x32x16_bf16 v[48:63], v[148:151], v[152:155], v[48:63]
	v_mfma_f32_32x32x16_bf16 v[32:47], v[148:151], v[160:163], v[32:47]
	s_waitcnt lgkmcnt(0)
	v_mfma_f32_32x32x16_bf16 v[16:31], v[164:167], v[152:155], v[16:31]
	ds_read_b128 v[140:143], v103 offset:18496
	ds_read_b128 v[144:147], v104 offset:55360
	ds_read_b128 v[148:151], v103 offset:18528
	ds_read_b128 v[152:155], v104 offset:55392
	v_mfma_f32_32x32x16_bf16 v[0:15], v[164:167], v[160:163], v[0:15]
	s_add_u32 s98, s98, 0x100
	s_addc_u32 s99, s99, 0
	s_add_i32 s10, s10, 2
	s_cmp_lt_u32 s10, 11
	s_waitcnt vmcnt(15)
	ds_write_b128 v105, v[108:111]
	ds_read_b128 v[156:159], v104 offset:59968
	ds_read_b128 v[160:163], v104 offset:60000
	s_waitcnt lgkmcnt(5)
	v_mfma_f32_32x32x16_bf16 v[48:63], v[140:143], v[144:147], v[48:63]
	s_waitcnt vmcnt(14)
	ds_write_b128 v105, v[112:115] offset:4608
	s_waitcnt lgkmcnt(2)
	v_mfma_f32_32x32x16_bf16 v[32:47], v[140:143], v[156:159], v[32:47]
	s_waitcnt vmcnt(13)
	ds_write_b128 v105, v[116:119] offset:9216
	ds_read_b128 v[140:143], v103 offset:23104
	ds_read_b128 v[164:167], v103 offset:23136
	s_waitcnt lgkmcnt(1)
	v_mfma_f32_32x32x16_bf16 v[16:31], v[140:143], v[144:147], v[16:31]
	s_waitcnt vmcnt(12)
	ds_write_b128 v105, v[120:123] offset:13824
	v_mfma_f32_32x32x16_bf16 v[0:15], v[140:143], v[156:159], v[0:15]
	s_waitcnt vmcnt(11)
	ds_write_b128 v105, v[124:127] offset:36864
	v_mfma_f32_32x32x16_bf16 v[48:63], v[148:151], v[152:155], v[48:63]
	s_waitcnt vmcnt(10)
	ds_write_b128 v105, v[128:131] offset:41472
	v_mfma_f32_32x32x16_bf16 v[32:47], v[148:151], v[160:163], v[32:47]
	s_waitcnt vmcnt(9)
	ds_write_b128 v105, v[132:135] offset:46080
	s_waitcnt lgkmcnt(4)
	v_mfma_f32_32x32x16_bf16 v[16:31], v[164:167], v[152:155], v[16:31]
	s_waitcnt vmcnt(8)
	ds_write_b128 v105, v[136:139] offset:50688
	v_mfma_f32_32x32x16_bf16 v[0:15], v[164:167], v[160:163], v[0:15]
	s_setprio 0
	s_waitcnt lgkmcnt(0)
	s_barrier
	s_cbranch_scc1 .LBB0_3806
	s_setprio 1
	ds_read_b128 v[98:101], v103
	ds_read_b128 v[108:111], v104 offset:36864
	ds_read_b128 v[112:115], v103 offset:32
	ds_read_b128 v[116:119], v104 offset:36896
	ds_read_b128 v[120:123], v104 offset:41472
	ds_read_b128 v[124:127], v104 offset:41504
	s_waitcnt lgkmcnt(4)
	v_mfma_f32_32x32x16_bf16 v[48:63], v[98:101], v[108:111], v[48:63]
	s_waitcnt lgkmcnt(1)
	v_mfma_f32_32x32x16_bf16 v[32:47], v[98:101], v[120:123], v[32:47]
	ds_read_b128 v[98:101], v103 offset:4608
	ds_read_b128 v[128:131], v103 offset:4640
	s_waitcnt lgkmcnt(1)
	v_mfma_f32_32x32x16_bf16 v[16:31], v[98:101], v[108:111], v[16:31]
	v_mfma_f32_32x32x16_bf16 v[0:15], v[98:101], v[120:123], v[0:15]
	v_mfma_f32_32x32x16_bf16 v[48:63], v[112:115], v[116:119], v[48:63]
	v_mfma_f32_32x32x16_bf16 v[32:47], v[112:115], v[124:127], v[32:47]
	s_waitcnt lgkmcnt(0)
	v_mfma_f32_32x32x16_bf16 v[16:31], v[128:131], v[116:119], v[16:31]
	ds_read_b128 v[98:101], v103 offset:64
	ds_read_b128 v[108:111], v104 offset:36928
	ds_read_b128 v[112:115], v103 offset:96
	ds_read_b128 v[116:119], v104 offset:36960
	v_mfma_f32_32x32x16_bf16 v[0:15], v[128:131], v[124:127], v[0:15]
	s_waitcnt vmcnt(7)
	ds_write_b128 v105, v[68:71] offset:18432
	ds_read_b128 v[120:123], v104 offset:41536
	ds_read_b128 v[124:127], v104 offset:41568
	s_waitcnt lgkmcnt(5)
	v_mfma_f32_32x32x16_bf16 v[48:63], v[98:101], v[108:111], v[48:63]
	s_waitcnt vmcnt(6)
	ds_write_b128 v105, v[84:87] offset:23040
	s_waitcnt lgkmcnt(2)
	v_mfma_f32_32x32x16_bf16 v[32:47], v[98:101], v[120:123], v[32:47]
	s_waitcnt vmcnt(5)
	ds_write_b128 v105, v[88:91] offset:27648
	ds_read_b128 v[98:101], v103 offset:4672
	ds_read_b128 v[128:131], v103 offset:4704
	s_waitcnt lgkmcnt(1)
	v_mfma_f32_32x32x16_bf16 v[16:31], v[98:101], v[108:111], v[16:31]
	s_waitcnt vmcnt(4)
	ds_write_b128 v105, v[92:95] offset:32256
	v_mfma_f32_32x32x16_bf16 v[0:15], v[98:101], v[120:123], v[0:15]
	s_waitcnt vmcnt(3)
	ds_write_b128 v105, v[64:67] offset:55296
	v_mfma_f32_32x32x16_bf16 v[32:47], v[112:115], v[124:127], v[32:47]
	s_waitcnt vmcnt(2)
	ds_write_b128 v105, v[72:75] offset:59904
	s_waitcnt lgkmcnt(3)
	v_mfma_f32_32x32x16_bf16 v[16:31], v[128:131], v[116:119], v[16:31]
	s_waitcnt vmcnt(1)
	ds_write_b128 v105, v[76:79] offset:64512
	v_mfma_f32_32x32x16_bf16 v[0:15], v[128:131], v[124:127], v[0:15]
	s_waitcnt vmcnt(0)
	ds_write_b128 v106, v[80:83] offset:13824
	v_mfma_f32_32x32x16_bf16 v[48:63], v[112:115], v[116:119], v[48:63]
	s_setprio 0
	s_waitcnt lgkmcnt(0)
	s_barrier
	s_setprio 1
	ds_read_b128 v[64:67], v103 offset:18432
	ds_read_b128 v[68:71], v104 offset:55296
	ds_read_b128 v[72:75], v103 offset:18464
	ds_read_b128 v[76:79], v104 offset:55328
	ds_read_b128 v[80:83], v104 offset:59904
	ds_read_b128 v[84:87], v104 offset:59936
	s_waitcnt lgkmcnt(4)
	v_mfma_f32_32x32x16_bf16 v[48:63], v[64:67], v[68:71], v[48:63]
	s_waitcnt lgkmcnt(1)
	v_mfma_f32_32x32x16_bf16 v[32:47], v[64:67], v[80:83], v[32:47]
	ds_read_b128 v[64:67], v103 offset:23040
	ds_read_b128 v[88:91], v103 offset:23072
	s_waitcnt lgkmcnt(1)
	v_mfma_f32_32x32x16_bf16 v[16:31], v[64:67], v[68:71], v[16:31]
	v_mfma_f32_32x32x16_bf16 v[0:15], v[64:67], v[80:83], v[0:15]
	v_mfma_f32_32x32x16_bf16 v[48:63], v[72:75], v[76:79], v[48:63]
	v_mfma_f32_32x32x16_bf16 v[32:47], v[72:75], v[84:87], v[32:47]
	s_waitcnt lgkmcnt(0)
	v_mfma_f32_32x32x16_bf16 v[16:31], v[88:91], v[76:79], v[16:31]
	ds_read_b128 v[64:67], v103 offset:18496
	ds_read_b128 v[68:71], v104 offset:55360
	ds_read_b128 v[72:75], v103 offset:18528
	ds_read_b128 v[76:79], v104 offset:55392
	v_mfma_f32_32x32x16_bf16 v[0:15], v[88:91], v[84:87], v[0:15]
	ds_read_b128 v[80:83], v104 offset:59968
	ds_read_b128 v[84:87], v104 offset:60000
	s_waitcnt lgkmcnt(4)
	v_mfma_f32_32x32x16_bf16 v[48:63], v[64:67], v[68:71], v[48:63]
	s_waitcnt lgkmcnt(1)
	v_mfma_f32_32x32x16_bf16 v[32:47], v[64:67], v[80:83], v[32:47]
	ds_read_b128 v[64:67], v103 offset:23104
	ds_read_b128 v[88:91], v103 offset:23136
	s_waitcnt lgkmcnt(1)
	v_mfma_f32_32x32x16_bf16 v[16:31], v[64:67], v[68:71], v[16:31]
	v_mfma_f32_32x32x16_bf16 v[0:15], v[64:67], v[80:83], v[0:15]
	v_mfma_f32_32x32x16_bf16 v[32:47], v[72:75], v[84:87], v[32:47]
	s_waitcnt lgkmcnt(0)
	v_mfma_f32_32x32x16_bf16 v[16:31], v[88:91], v[76:79], v[16:31]
	v_mfma_f32_32x32x16_bf16 v[0:15], v[88:91], v[84:87], v[0:15]
	v_mfma_f32_32x32x16_bf16 v[48:63], v[72:75], v[76:79], v[48:63]
	s_setprio 0
	s_addk_i32 s0, 0xf000
	s_lshr_b32 s10, s0, 10
	s_mulk_i32 s10, 0x1800
	s_add_i32 s10, s10, 0x9000
	s_and_b64 s[58:59], s[8:9], exec
	s_cselect_b32 s10, 0x7800, s10
	v_mov_b32_e32 v68, v234
	s_barrier
	s_lshl_b64 s[58:59], s[10:11], 2
	s_add_u32 s58, s30, s58
	v_and_b32_e32 v69, 0x5f, v68
	v_or_b32_e32 v64, s25, v69
	s_addc_u32 s59, s31, s59
	v_ashrrev_i32_e32 v65, 31, v64
	v_lshl_add_u64 v[64:65], v[64:65], 2, s[58:59]
	v_lshl_add_u64 v[66:67], v[64:65], 0, s[14:15]
	v_add_co_u32_e32 v64, vcc, s51, v64
	v_lshlrev_b32_e32 v69, 2, v69
	s_nop 0
	v_addc_co_u32_e32 v65, vcc, 0, v65, vcc
	global_load_dword v64, v[64:65], off
	s_nop 0
	global_load_dword v65, v[66:67], off offset:128
	v_lshrrev_b32_e32 v67, 3, v68
	v_lshrrev_b32_e32 v66, 1, v68
	v_and_b32_e32 v67, 4, v67
	v_and_or_b32 v66, v66, s42, v67
	v_mul_lo_u32 v66, v66, s52
	v_add3_u32 v66, 32, v69, v66
	v_add_u32_e32 v67, 0x400, v66
	v_add_u32_e32 v69, 0x1000, v66
	v_add_u32_e32 v70, 0x1400, v66
	v_add_u32_e32 v71, 0x2000, v66
	v_add_u32_e32 v72, 0x2400, v66
	v_add_u32_e32 v73, 0x3000, v66
	v_add_u32_e32 v74, 0x3200, v66
	v_add_u32_e32 v75, 0x3400, v66
	v_add_u32_e32 v76, 0x3600, v66
	v_add_u32_e32 v77, 0x4000, v66
	v_readlane_b32 s80, v250, 6
	v_readlane_b32 s81, v250, 7
	v_readlane_b32 s82, v250, 8
	v_readlane_b32 s83, v250, 9
	v_readlane_b32 s92, v250, 18
	v_readlane_b32 s93, v250, 19
	v_readlane_b32 s94, v250, 20
	v_readlane_b32 s95, v250, 21
	s_mov_b64 s[80:81], s[92:93]
	s_mov_b64 s[82:83], s[94:95]
	s_lshl_b32 s1, s1, 19
	s_add_u32 s10, s28, s1
	s_mov_b32 s1, s11
	v_readlane_b32 s84, v250, 10
	v_readlane_b32 s85, v250, 11
	v_readlane_b32 s86, v250, 12
	v_readlane_b32 s87, v250, 13
	v_readlane_b32 s88, v250, 14
	v_readlane_b32 s89, v250, 15
	v_readlane_b32 s90, v250, 16
	v_readlane_b32 s91, v250, 17
	s_waitcnt vmcnt(1)
	v_mul_f32_e32 v48, v48, v64
	s_waitcnt vmcnt(0)
	v_mul_f32_e32 v32, v32, v65
	v_mul_f32_e32 v16, v16, v64
	v_mul_f32_e32 v0, v0, v65
	v_mul_f32_e32 v49, v49, v64
	v_mul_f32_e32 v33, v33, v65
	v_mul_f32_e32 v50, v50, v64
	v_mul_f32_e32 v34, v34, v65
	v_mul_f32_e32 v51, v51, v64
	v_mul_f32_e32 v35, v35, v65
	v_mul_f32_e32 v52, v52, v64
	v_mul_f32_e32 v36, v36, v65
	v_mul_f32_e32 v53, v53, v64
	v_mul_f32_e32 v37, v37, v65
	v_mul_f32_e32 v54, v54, v64
	v_mul_f32_e32 v38, v38, v65
	v_mul_f32_e32 v55, v55, v64
	v_mul_f32_e32 v39, v39, v65
	v_mul_f32_e32 v56, v56, v64
	v_mul_f32_e32 v40, v40, v65
	v_mul_f32_e32 v57, v57, v64
	v_mul_f32_e32 v41, v41, v65
	v_mul_f32_e32 v58, v58, v64
	v_mul_f32_e32 v42, v42, v65
	v_mul_f32_e32 v59, v59, v64
	v_mul_f32_e32 v43, v43, v65
	v_mul_f32_e32 v60, v60, v64
	v_mul_f32_e32 v44, v44, v65
	v_mul_f32_e32 v61, v61, v64
	v_mul_f32_e32 v45, v45, v65
	v_mul_f32_e32 v62, v62, v64
	v_mul_f32_e32 v46, v46, v65
	v_mul_f32_e32 v63, v63, v64
	v_mul_f32_e32 v47, v47, v65
	ds_write2_b32 v66, v48, v32 offset1:32
	ds_write2_b32 v66, v49, v33 offset0:132 offset1:164
	ds_write2_b32 v67, v50, v34 offset0:8 offset1:40
	ds_write2_b32 v67, v51, v35 offset0:140 offset1:172
	ds_write2_b32 v69, v52, v36 offset0:32 offset1:64
	ds_write2_b32 v69, v53, v37 offset0:164 offset1:196
	ds_write2_b32 v70, v54, v38 offset0:40 offset1:72
	ds_write2_b32 v70, v55, v39 offset0:172 offset1:204
	ds_write2_b32 v71, v56, v40 offset0:64 offset1:96
	ds_write2_b32 v71, v57, v41 offset0:196 offset1:228
	ds_write2_b32 v72, v58, v42 offset0:72 offset1:104
	ds_write2_b32 v72, v59, v43 offset0:204 offset1:236
	ds_write2_b32 v73, v60, v44 offset0:96 offset1:128
	ds_write2_b32 v74, v61, v45 offset0:100 offset1:132
	ds_write2_b32 v75, v62, v46 offset0:104 offset1:136
	ds_write2_b32 v76, v63, v47 offset0:108 offset1:140
	ds_write2_b32 v77, v16, v0 offset0:128 offset1:160
	v_mul_f32_e32 v0, v17, v64
	v_mul_f32_e32 v1, v1, v65
	v_add_u32_e32 v16, 0x4400, v66
	ds_write2_b32 v16, v0, v1 offset0:4 offset1:36
	v_mul_f32_e32 v0, v18, v64
	v_mul_f32_e32 v1, v2, v65
	ds_write2_b32 v16, v0, v1 offset0:136 offset1:168
	v_mul_f32_e32 v0, v19, v64
	v_mul_f32_e32 v1, v3, v65
	v_add_u32_e32 v2, 0x4800, v66
	ds_write2_b32 v2, v0, v1 offset0:12 offset1:44
	v_mul_f32_e32 v0, v20, v64
	v_mul_f32_e32 v1, v4, v65
	v_add_u32_e32 v2, 0x5000, v66
	ds_write2_b32 v2, v0, v1 offset0:160 offset1:192
	v_mul_f32_e32 v0, v21, v64
	v_mul_f32_e32 v1, v5, v65
	v_add_u32_e32 v2, 0x5400, v66
	ds_write2_b32 v2, v0, v1 offset0:36 offset1:68
	v_mul_f32_e32 v0, v22, v64
	v_mul_f32_e32 v1, v6, v65
	ds_write2_b32 v2, v0, v1 offset0:168 offset1:200
	v_mul_f32_e32 v0, v23, v64
	v_mul_f32_e32 v1, v7, v65
	v_add_u32_e32 v2, 0x5800, v66
	ds_write2_b32 v2, v0, v1 offset0:44 offset1:76
	v_mul_f32_e32 v0, v24, v64
	v_mul_f32_e32 v1, v8, v65
	v_add_u32_e32 v2, 0x6000, v66
	ds_write2_b32 v2, v0, v1 offset0:192 offset1:224
	v_mul_f32_e32 v0, v25, v64
	v_mul_f32_e32 v1, v9, v65
	v_add_u32_e32 v2, 0x6400, v66
	ds_write2_b32 v2, v0, v1 offset0:68 offset1:100
	v_mul_f32_e32 v0, v26, v64
	v_mul_f32_e32 v1, v10, v65
	ds_write2_b32 v2, v0, v1 offset0:200 offset1:232
	v_mul_f32_e32 v0, v27, v64
	v_mul_f32_e32 v1, v11, v65
	v_add_u32_e32 v2, 0x6800, v66
	ds_write2_b32 v2, v0, v1 offset0:76 offset1:108
	v_mul_f32_e32 v0, v28, v64
	v_mul_f32_e32 v1, v12, v65
	v_add_u32_e32 v2, 0x7200, v66
	ds_write2_b32 v2, v0, v1 offset0:96 offset1:128
	v_mul_f32_e32 v0, v29, v64
	v_mul_f32_e32 v1, v13, v65
	v_add_u32_e32 v2, 0x7400, v66
	ds_write2_b32 v2, v0, v1 offset0:100 offset1:132
	v_mul_f32_e32 v0, v30, v64
	v_mul_f32_e32 v1, v14, v65
	v_add_u32_e32 v2, 0x7600, v66
	v_and_b32_e32 v12, 31, v68
	ds_write2_b32 v2, v0, v1 offset0:104 offset1:136
	v_mul_f32_e32 v0, v31, v64
	v_mul_f32_e32 v1, v15, v65
	v_add_u32_e32 v2, 0x7800, v66
	v_lshlrev_b32_e32 v10, 2, v12
	ds_write2_b32 v2, v0, v1 offset0:108 offset1:140
	v_or_b32_e32 v0, s25, v10
	v_ashrrev_i32_e32 v1, 31, v0
	v_lshlrev_b64 v[0:1], 2, v[0:1]
	v_lshl_add_u64 v[2:3], s[80:81], 0, v[0:1]
	v_lshl_add_u64 v[4:5], s[82:83], 0, v[0:1]
	s_waitcnt lgkmcnt(0)
	s_barrier
	global_load_dwordx4 v[0:3], v[2:3], off
	s_nop 0
	global_load_dwordx4 v[4:7], v[4:5], off
	v_and_b32_e32 v8, 64, v102
	v_add_u32_e32 v8, 64, v8
	v_xor_b32_e32 v9, 1, v102
	v_cmp_lt_i32_e32 vcc, v9, v8
	s_addc_u32 s25, s29, 0
	s_lshl_b64 s[0:1], s[0:1], 12
	v_cndmask_b32_e32 v9, v102, v9, vcc
	v_lshlrev_b32_e32 v30, 2, v9
	v_xor_b32_e32 v9, 2, v102
	v_cmp_lt_i32_e32 vcc, v9, v8
	s_add_u32 s58, s17, s0
	s_addc_u32 s59, s19, s1
	v_cndmask_b32_e32 v9, v102, v9, vcc
	v_lshlrev_b32_e32 v31, 2, v9
	v_xor_b32_e32 v9, 4, v102
	v_cmp_lt_i32_e32 vcc, v9, v8
	s_and_b64 s[0:1], s[8:9], exec
	v_add_u32_e32 v10, s22, v10
	v_cndmask_b32_e32 v9, v102, v9, vcc
	v_lshlrev_b32_e32 v32, 2, v9
	v_xor_b32_e32 v9, 8, v102
	v_cmp_lt_i32_e32 vcc, v9, v8
	v_ashrrev_i32_e32 v22, 5, v68
	s_cselect_b32 s59, s25, s59
	s_cselect_b32 s58, s10, s58
	v_cndmask_b32_e32 v9, v102, v9, vcc
	v_ashrrev_i32_e32 v11, 31, v10
	s_add_i32 s10, s24, s35
	v_cmp_eq_u32_e64 s[0:1], 0, v12
	v_lshlrev_b32_e32 v33, 2, v9
	v_xor_b32_e32 v9, 16, v102
	v_lshlrev_b64 v[24:25], 2, v[10:11]
	v_lshlrev_b32_e32 v11, 4, v12
	v_add_u32_e32 v12, s10, v22
	s_add_i32 s10, s24, s36
	s_add_i32 s24, s24, s37
	v_cmp_lt_i32_e32 vcc, v9, v8
	v_add_u32_e32 v16, s10, v22
	v_add_u32_e32 v20, s24, v22
	v_cndmask_b32_e32 v8, v102, v9, vcc
	v_ashrrev_i32_e32 v23, 31, v22
	v_mul_lo_u32 v10, v22, s52
	v_ashrrev_i32_e32 v13, 31, v12
	v_ashrrev_i32_e32 v17, 31, v16
	v_ashrrev_i32_e32 v21, 31, v20
	v_add_u32_e32 v26, s23, v22
	v_lshlrev_b32_e32 v34, 2, v8
	v_lshlrev_b64 v[8:9], 12, v[22:23]
	v_add3_u32 v35, v10, v11, 32
	v_lshlrev_b64 v[10:11], 12, v[12:13]
	v_lshlrev_b32_e32 v12, 1, v12
	v_lshlrev_b64 v[14:15], 12, v[16:17]
	v_lshlrev_b32_e32 v16, 1, v16
	v_lshlrev_b64 v[18:19], 12, v[20:21]
	v_lshlrev_b32_e32 v20, 1, v20
	v_lshlrev_b32_e32 v22, 1, v26
	v_ashrrev_i32_e32 v27, 31, v26
	v_lshl_add_u64 v[8:9], v[8:9], 0, v[24:25]
	v_ashrrev_i32_e32 v13, 31, v12
	v_ashrrev_i32_e32 v17, 31, v16
	v_ashrrev_i32_e32 v21, 31, v20
	v_ashrrev_i32_e32 v23, 31, v22
	v_lshlrev_b64 v[26:27], 12, v[26:27]
	v_lshl_add_u64 v[8:9], s[58:59], 0, v[8:9]
	v_lshl_add_u64 v[10:11], v[10:11], 0, v[24:25]
	v_lshlrev_b64 v[12:13], 2, v[12:13]
	v_lshl_add_u64 v[14:15], v[14:15], 0, v[24:25]
	v_lshlrev_b64 v[16:17], 2, v[16:17]
	v_lshl_add_u64 v[18:19], v[18:19], 0, v[24:25]
	v_lshlrev_b64 v[20:21], 2, v[20:21]
	v_lshlrev_b64 v[22:23], 2, v[22:23]
	v_lshl_add_u64 v[24:25], v[26:27], 0, v[24:25]
	s_mov_b64 s[22:23], 0
	s_branch .LBB0_3809

.LBB0_3927:
	s_ashr_i32 s41, s40, 3
	s_add_i32 s10, s41, s38
	s_cmp_gt_i32 s10, 43
	s_cbranch_scc1 .LBB0_3926
	s_and_b32 s11, s40, 7
	v_mov_b32_e32 v102, v234
	s_waitcnt vmcnt(6)
	v_mov_b32_e32 v33, v234
	s_or_b32 s11, s11, s15
	s_lshl_b32 s10, s10, 7
	v_ashrrev_i32_e32 v32, 3, v33
	v_lshl_add_u32 v0, s11, 7, v32
	v_ashrrev_i32_e32 v1, 31, v0
	v_lshlrev_b64 v[0:1], 11, v[0:1]
	v_lshlrev_b32_e32 v2, 4, v33
	v_lshl_add_u64 v[0:1], s[4:5], 0, v[0:1]
	v_and_b32_e32 v96, 0x70, v2
	s_waitcnt vmcnt(5)
	v_lshl_add_u64 v[34:35], v[0:1], 0, v[96:97]
	s_waitcnt vmcnt(4) lgkmcnt(1)
	v_add_co_u32_e32 v38, vcc, s18, v34
	v_add_u32_e32 v0, s10, v32
	s_waitcnt lgkmcnt(0)
	v_addc_co_u32_e32 v39, vcc, 0, v35, vcc
	v_ashrrev_i32_e32 v1, 31, v0
	v_add_co_u32_e32 v40, vcc, s19, v34
	v_lshlrev_b64 v[0:1], 11, v[0:1]
	s_nop 0
	v_addc_co_u32_e32 v41, vcc, 0, v35, vcc
	v_lshl_add_u64 v[0:1], s[6:7], 0, v[0:1]
	v_add_co_u32_e32 v42, vcc, s20, v34
	v_lshl_add_u64 v[36:37], v[0:1], 0, v[96:97]
	s_nop 0
	v_addc_co_u32_e32 v43, vcc, 0, v35, vcc
	v_add_co_u32_e32 v44, vcc, s18, v36
	s_nop 1
	v_addc_co_u32_e32 v45, vcc, 0, v37, vcc
	v_add_co_u32_e32 v46, vcc, s19, v36
	s_barrier
	s_nop 0
	v_addc_co_u32_e32 v47, vcc, 0, v37, vcc
	v_add_co_u32_e32 v48, vcc, s20, v36
	global_load_dwordx4 v[0:3], v[34:35], off
	global_load_dwordx4 v[4:7], v[38:39], off
	global_load_dwordx4 v[8:11], v[40:41], off
	global_load_dwordx4 v[12:15], v[42:43], off
	global_load_dwordx4 v[16:19], v[36:37], off
	v_addc_co_u32_e32 v49, vcc, 0, v37, vcc
	global_load_dwordx4 v[20:23], v[44:45], off
	global_load_dwordx4 v[24:27], v[46:47], off
	global_load_dwordx4 v[28:31], v[48:49], off
	global_load_dwordx4 v[68:71], v[34:35], off offset:128
	global_load_dwordx4 v[64:67], v[36:37], off offset:128
	global_load_dwordx4 v[84:87], v[38:39], off offset:128
	global_load_dwordx4 v[88:91], v[40:41], off offset:128
	global_load_dwordx4 v[92:95], v[42:43], off offset:128
	global_load_dwordx4 v[72:75], v[44:45], off offset:128
	global_load_dwordx4 v[76:79], v[46:47], off offset:128
	global_load_dwordx4 v[80:83], v[48:49], off offset:128
	s_and_b32 s42, s39, 7
	s_add_i32 s41, s16, s41
	s_lshl_b32 s44, s42, 7
	v_lshrrev_b32_e32 v50, 1, v33
	v_and_b32_e32 v51, 31, v33
	v_and_b32_e32 v52, 0x5f, v33
	v_and_b32_e32 v33, 7, v33
	v_mul_lo_u32 v53, v32, s21
	s_lshl_b32 s42, s41, 7
	v_add3_u32 v105, 32, v53, v96
	v_lshlrev_b32_e32 v96, 4, v33
	v_ashrrev_i32_e32 v33, 31, v32
	s_ashr_i32 s43, s42, 31
	s_add_i32 s44, s44, s17
	v_and_or_b32 v51, v50, s22, v51
	v_mul_u32_u24_e32 v52, 0x48, v52
	v_and_b32_e32 v50, 16, v50
	v_mul_lo_u32 v51, v51, s21
	v_lshlrev_b32_e32 v52, 1, v52
	v_add3_u32 v103, 32, v51, v50
	v_add3_u32 v104, 32, v52, v50
	v_add_u32_e32 v106, 0xd800, v105
	s_mov_b32 s41, -2
	s_waitcnt vmcnt(15)
	ds_write_b128 v105, v[0:3]
	s_waitcnt vmcnt(11)
	ds_write_b128 v105, v[16:19] offset:36864
	ds_write_b128 v105, v[4:7] offset:4608
	ds_write_b128 v105, v[8:11] offset:9216
	ds_write_b128 v105, v[12:15] offset:13824
	s_waitcnt vmcnt(10)
	ds_write_b128 v105, v[20:23] offset:41472
	s_waitcnt vmcnt(9)
	ds_write_b128 v105, v[24:27] offset:46080
	s_waitcnt vmcnt(8)
	ds_write_b128 v105, v[28:31] offset:50688
	v_lshl_add_u64 v[0:1], v[32:33], 0, s[42:43]
	v_lshlrev_b64 v[0:1], 11, v[0:1]
	v_lshl_add_u64 v[98:99], s[30:31], 0, v[0:1]
	v_add_u32_e32 v0, s44, v32
	v_ashrrev_i32_e32 v1, 31, v0
	v_lshlrev_b64 v[0:1], 11, v[0:1]
	v_lshl_add_u64 v[100:101], s[30:31], 0, v[0:1]
	v_mov_b32_e32 v0, 0
	v_mov_b32_e32 v1, v0
	v_mov_b32_e32 v2, v0
	v_mov_b32_e32 v3, v0
	v_mov_b32_e32 v4, v0
	v_mov_b32_e32 v5, v0
	v_mov_b32_e32 v6, v0
	v_mov_b32_e32 v7, v0
	v_mov_b32_e32 v8, v0
	v_mov_b32_e32 v9, v0
	v_mov_b32_e32 v10, v0
	v_mov_b32_e32 v11, v0
	v_mov_b32_e32 v12, v0
	v_mov_b32_e32 v13, v0
	v_mov_b32_e32 v14, v0
	v_mov_b32_e32 v15, v0
	v_mov_b32_e32 v16, v0
	v_mov_b32_e32 v17, v0
	v_mov_b32_e32 v18, v0
	v_mov_b32_e32 v19, v0
	v_mov_b32_e32 v20, v0
	v_mov_b32_e32 v21, v0
	v_mov_b32_e32 v22, v0
	v_mov_b32_e32 v23, v0
	v_mov_b32_e32 v24, v0
	v_mov_b32_e32 v25, v0
	v_mov_b32_e32 v26, v0
	v_mov_b32_e32 v27, v0
	v_mov_b32_e32 v28, v0
	v_mov_b32_e32 v29, v0
	v_mov_b32_e32 v30, v0
	v_mov_b32_e32 v31, v0
	v_mov_b32_e32 v32, v0
	v_mov_b32_e32 v33, v0
	v_mov_b32_e32 v34, v0
	v_mov_b32_e32 v35, v0
	v_mov_b32_e32 v36, v0
	v_mov_b32_e32 v37, v0
	v_mov_b32_e32 v38, v0
	v_mov_b32_e32 v39, v0
	v_mov_b32_e32 v40, v0
	v_mov_b32_e32 v41, v0
	v_mov_b32_e32 v42, v0
	v_mov_b32_e32 v43, v0
	v_mov_b32_e32 v44, v0
	v_mov_b32_e32 v45, v0
	v_mov_b32_e32 v46, v0
	v_mov_b32_e32 v47, v0
	v_mov_b32_e32 v48, v0
	v_mov_b32_e32 v49, v0
	v_mov_b32_e32 v50, v0
	v_mov_b32_e32 v51, v0
	v_mov_b32_e32 v52, v0
	v_mov_b32_e32 v53, v0
	v_mov_b32_e32 v54, v0
	v_mov_b32_e32 v55, v0
	v_mov_b32_e32 v56, v0
	v_mov_b32_e32 v57, v0
	v_mov_b32_e32 v58, v0
	v_mov_b32_e32 v59, v0
	v_mov_b32_e32 v60, v0
	v_mov_b32_e32 v61, v0
	v_mov_b32_e32 v62, v0
	v_mov_b32_e32 v63, v0
	v_lshl_add_u64 v[116:117], v[100:101], 0, v[96:97]
	v_add_co_u32_e32 v168, vcc, s23, v116
	v_lshl_add_u64 v[132:133], v[98:99], 0, v[96:97]
	s_nop 0
	v_addc_co_u32_e32 v169, vcc, 0, v117, vcc
	v_add_co_u32_e32 v170, vcc, s24, v116
	s_nop 1
	v_addc_co_u32_e32 v171, vcc, 0, v117, vcc
	v_add_co_u32_e32 v172, vcc, s25, v116
	s_nop 1
	v_addc_co_u32_e32 v173, vcc, 0, v117, vcc
	v_add_co_u32_e32 v174, vcc, s26, v116
	s_nop 1
	v_addc_co_u32_e32 v175, vcc, 0, v117, vcc
	v_add_co_u32_e32 v176, vcc, s27, v132
	s_nop 1
	v_addc_co_u32_e32 v177, vcc, 0, v133, vcc
	v_add_co_u32_e32 v178, vcc, s33, v132
	s_nop 1
	v_addc_co_u32_e32 v179, vcc, 0, v133, vcc
	v_add_co_u32_e32 v180, vcc, s34, v132
	s_nop 1
	v_addc_co_u32_e32 v181, vcc, 0, v133, vcc
	v_add_co_u32_e32 v182, vcc, s35, v132
	s_nop 1
	v_addc_co_u32_e32 v183, vcc, 0, v133, vcc
	v_subrev_u32_e32 v168, s30, v168
	v_subrev_u32_e32 v170, s30, v170
	v_subrev_u32_e32 v172, s30, v172
	v_subrev_u32_e32 v174, s30, v174
	v_subrev_u32_e32 v176, s30, v176
	v_subrev_u32_e32 v178, s30, v178
	v_subrev_u32_e32 v180, s30, v180
	v_subrev_u32_e32 v182, s30, v182
	s_mov_b64 s[98:99], s[30:31]
	s_waitcnt lgkmcnt(0)
	s_barrier
.LBB0_3929:
	s_setprio 1
	ds_read_b128 v[140:143], v103
	ds_read_b128 v[144:147], v104 offset:36864
	ds_read_b128 v[148:151], v103 offset:32
	ds_read_b128 v[152:155], v104 offset:36896
	ds_read_b128 v[156:159], v104 offset:41472
	ds_read_b128 v[160:163], v104 offset:41504
	s_waitcnt lgkmcnt(4)
	v_mfma_f32_32x32x16_bf16 v[48:63], v[140:143], v[144:147], v[48:63]
	global_load_dwordx4 v[108:111], v168, s[98:99] offset:3840
	global_load_dwordx4 v[112:115], v170, s[98:99] offset:3840
	s_waitcnt lgkmcnt(1)
	v_mfma_f32_32x32x16_bf16 v[32:47], v[140:143], v[156:159], v[32:47]
	global_load_dwordx4 v[116:119], v172, s[98:99] offset:3840
	global_load_dwordx4 v[120:123], v174, s[98:99] offset:3840
	ds_read_b128 v[140:143], v103 offset:4608
	ds_read_b128 v[164:167], v103 offset:4640
	s_waitcnt lgkmcnt(1)
	v_mfma_f32_32x32x16_bf16 v[16:31], v[140:143], v[144:147], v[16:31]
	global_load_dwordx4 v[124:127], v176, s[98:99] offset:3840
	global_load_dwordx4 v[128:131], v178, s[98:99] offset:3840
	v_mfma_f32_32x32x16_bf16 v[0:15], v[140:143], v[156:159], v[0:15]
	global_load_dwordx4 v[132:135], v180, s[98:99] offset:3840
	global_load_dwordx4 v[136:139], v182, s[98:99] offset:3840
	v_mfma_f32_32x32x16_bf16 v[48:63], v[148:151], v[152:155], v[48:63]
	v_mfma_f32_32x32x16_bf16 v[32:47], v[148:151], v[160:163], v[32:47]
	s_waitcnt lgkmcnt(0)
	v_mfma_f32_32x32x16_bf16 v[16:31], v[164:167], v[152:155], v[16:31]
	ds_read_b128 v[140:143], v103 offset:64
	ds_read_b128 v[144:147], v104 offset:36928
	ds_read_b128 v[148:151], v103 offset:96
	ds_read_b128 v[152:155], v104 offset:36960
	v_mfma_f32_32x32x16_bf16 v[0:15], v[164:167], v[160:163], v[0:15]
	s_waitcnt vmcnt(15)
	ds_write_b128 v105, v[68:71] offset:18432
	ds_read_b128 v[156:159], v104 offset:41536
	ds_read_b128 v[160:163], v104 offset:41568
	s_waitcnt lgkmcnt(5)
	v_mfma_f32_32x32x16_bf16 v[48:63], v[140:143], v[144:147], v[48:63]
	s_waitcnt vmcnt(13)
	ds_write_b128 v105, v[84:87] offset:23040
	s_waitcnt lgkmcnt(2)
	v_mfma_f32_32x32x16_bf16 v[32:47], v[140:143], v[156:159], v[32:47]
	s_waitcnt vmcnt(12)
	ds_write_b128 v105, v[88:91] offset:27648
	ds_read_b128 v[140:143], v103 offset:4672
	ds_read_b128 v[164:167], v103 offset:4704
	s_waitcnt lgkmcnt(1)
	v_mfma_f32_32x32x16_bf16 v[16:31], v[140:143], v[144:147], v[16:31]
	s_waitcnt vmcnt(11)
	ds_write_b128 v105, v[92:95] offset:32256
	v_mfma_f32_32x32x16_bf16 v[0:15], v[140:143], v[156:159], v[0:15]
	ds_write_b128 v105, v[64:67] offset:55296
	v_mfma_f32_32x32x16_bf16 v[48:63], v[148:151], v[152:155], v[48:63]
	s_waitcnt vmcnt(10)
	ds_write_b128 v105, v[72:75] offset:59904
	v_mfma_f32_32x32x16_bf16 v[32:47], v[148:151], v[160:163], v[32:47]
	s_waitcnt vmcnt(9)
	ds_write_b128 v105, v[76:79] offset:64512
	s_waitcnt lgkmcnt(4)
	v_mfma_f32_32x32x16_bf16 v[16:31], v[164:167], v[152:155], v[16:31]
	s_waitcnt vmcnt(8)
	ds_write_b128 v106, v[80:83] offset:13824
	v_mfma_f32_32x32x16_bf16 v[0:15], v[164:167], v[160:163], v[0:15]
	s_setprio 0
	s_waitcnt lgkmcnt(0)
	s_barrier
	s_setprio 1
	ds_read_b128 v[140:143], v103 offset:18432
	ds_read_b128 v[144:147], v104 offset:55296
	ds_read_b128 v[148:151], v103 offset:18464
	ds_read_b128 v[152:155], v104 offset:55328
	ds_read_b128 v[156:159], v104 offset:59904
	ds_read_b128 v[160:163], v104 offset:59936
	s_waitcnt lgkmcnt(4)
	v_mfma_f32_32x32x16_bf16 v[48:63], v[140:143], v[144:147], v[48:63]
	global_load_dwordx4 v[68:71], v168, s[98:99] offset:3968
	global_load_dwordx4 v[84:87], v170, s[98:99] offset:3968
	s_waitcnt lgkmcnt(1)
	v_mfma_f32_32x32x16_bf16 v[32:47], v[140:143], v[156:159], v[32:47]
	global_load_dwordx4 v[88:91], v172, s[98:99] offset:3968
	global_load_dwordx4 v[92:95], v174, s[98:99] offset:3968
	ds_read_b128 v[140:143], v103 offset:23040
	ds_read_b128 v[164:167], v103 offset:23072
	s_waitcnt lgkmcnt(1)
	v_mfma_f32_32x32x16_bf16 v[16:31], v[140:143], v[144:147], v[16:31]
	global_load_dwordx4 v[64:67], v176, s[98:99] offset:3968
	global_load_dwordx4 v[72:75], v178, s[98:99] offset:3968
	v_mfma_f32_32x32x16_bf16 v[0:15], v[140:143], v[156:159], v[0:15]
	global_load_dwordx4 v[76:79], v180, s[98:99] offset:3968
	global_load_dwordx4 v[80:83], v182, s[98:99] offset:3968
	v_mfma_f32_32x32x16_bf16 v[48:63], v[148:151], v[152:155], v[48:63]
	v_mfma_f32_32x32x16_bf16 v[32:47], v[148:151], v[160:163], v[32:47]
	s_waitcnt lgkmcnt(0)
	v_mfma_f32_32x32x16_bf16 v[16:31], v[164:167], v[152:155], v[16:31]
	ds_read_b128 v[140:143], v103 offset:18496
	ds_read_b128 v[144:147], v104 offset:55360
	ds_read_b128 v[148:151], v103 offset:18528
	ds_read_b128 v[152:155], v104 offset:55392
	v_mfma_f32_32x32x16_bf16 v[0:15], v[164:167], v[160:163], v[0:15]
	s_add_u32 s98, s98, 0x100
	s_addc_u32 s99, s99, 0
	s_add_i32 s41, s41, 2
	s_cmp_lt_u32 s41, 11
	s_waitcnt vmcnt(15)
	ds_write_b128 v105, v[108:111]
	ds_read_b128 v[156:159], v104 offset:59968
	ds_read_b128 v[160:163], v104 offset:60000
	s_waitcnt lgkmcnt(5)
	v_mfma_f32_32x32x16_bf16 v[48:63], v[140:143], v[144:147], v[48:63]
	s_waitcnt vmcnt(14)
	ds_write_b128 v105, v[112:115] offset:4608
	s_waitcnt lgkmcnt(2)
	v_mfma_f32_32x32x16_bf16 v[32:47], v[140:143], v[156:159], v[32:47]
	s_waitcnt vmcnt(13)
	ds_write_b128 v105, v[116:119] offset:9216
	ds_read_b128 v[140:143], v103 offset:23104
	ds_read_b128 v[164:167], v103 offset:23136
	s_waitcnt lgkmcnt(1)
	v_mfma_f32_32x32x16_bf16 v[16:31], v[140:143], v[144:147], v[16:31]
	s_waitcnt vmcnt(12)
	ds_write_b128 v105, v[120:123] offset:13824
	v_mfma_f32_32x32x16_bf16 v[0:15], v[140:143], v[156:159], v[0:15]
	s_waitcnt vmcnt(11)
	ds_write_b128 v105, v[124:127] offset:36864
	v_mfma_f32_32x32x16_bf16 v[48:63], v[148:151], v[152:155], v[48:63]
	s_waitcnt vmcnt(10)
	ds_write_b128 v105, v[128:131] offset:41472
	v_mfma_f32_32x32x16_bf16 v[32:47], v[148:151], v[160:163], v[32:47]
	s_waitcnt vmcnt(9)
	ds_write_b128 v105, v[132:135] offset:46080
	s_waitcnt lgkmcnt(4)
	v_mfma_f32_32x32x16_bf16 v[16:31], v[164:167], v[152:155], v[16:31]
	s_waitcnt vmcnt(8)
	ds_write_b128 v105, v[136:139] offset:50688
	v_mfma_f32_32x32x16_bf16 v[0:15], v[164:167], v[160:163], v[0:15]
	s_setprio 0
	s_waitcnt lgkmcnt(0)
	s_barrier
	s_cbranch_scc1 .LBB0_3929
	s_setprio 1
	ds_read_b128 v[98:101], v103
	ds_read_b128 v[108:111], v104 offset:36864
	ds_read_b128 v[112:115], v103 offset:32
	ds_read_b128 v[116:119], v104 offset:36896
	ds_read_b128 v[120:123], v104 offset:41472
	ds_read_b128 v[124:127], v104 offset:41504
	s_waitcnt lgkmcnt(4)
	v_mfma_f32_32x32x16_bf16 v[48:63], v[98:101], v[108:111], v[48:63]
	s_waitcnt lgkmcnt(1)
	v_mfma_f32_32x32x16_bf16 v[32:47], v[98:101], v[120:123], v[32:47]
	ds_read_b128 v[98:101], v103 offset:4608
	ds_read_b128 v[128:131], v103 offset:4640
	s_waitcnt lgkmcnt(1)
	v_mfma_f32_32x32x16_bf16 v[16:31], v[98:101], v[108:111], v[16:31]
	v_mfma_f32_32x32x16_bf16 v[0:15], v[98:101], v[120:123], v[0:15]
	v_mfma_f32_32x32x16_bf16 v[48:63], v[112:115], v[116:119], v[48:63]
	v_mfma_f32_32x32x16_bf16 v[32:47], v[112:115], v[124:127], v[32:47]
	s_waitcnt lgkmcnt(0)
	v_mfma_f32_32x32x16_bf16 v[16:31], v[128:131], v[116:119], v[16:31]
	ds_read_b128 v[98:101], v103 offset:64
	ds_read_b128 v[108:111], v104 offset:36928
	ds_read_b128 v[112:115], v103 offset:96
	ds_read_b128 v[116:119], v104 offset:36960
	v_mfma_f32_32x32x16_bf16 v[0:15], v[128:131], v[124:127], v[0:15]
	s_waitcnt vmcnt(7)
	ds_write_b128 v105, v[68:71] offset:18432
	ds_read_b128 v[120:123], v104 offset:41536
	ds_read_b128 v[124:127], v104 offset:41568
	s_waitcnt lgkmcnt(5)
	v_mfma_f32_32x32x16_bf16 v[48:63], v[98:101], v[108:111], v[48:63]
	s_waitcnt vmcnt(6)
	ds_write_b128 v105, v[84:87] offset:23040
	s_waitcnt lgkmcnt(2)
	v_mfma_f32_32x32x16_bf16 v[32:47], v[98:101], v[120:123], v[32:47]
	s_waitcnt vmcnt(5)
	ds_write_b128 v105, v[88:91] offset:27648
	ds_read_b128 v[98:101], v103 offset:4672
	ds_read_b128 v[128:131], v103 offset:4704
	s_waitcnt lgkmcnt(1)
	v_mfma_f32_32x32x16_bf16 v[16:31], v[98:101], v[108:111], v[16:31]
	s_waitcnt vmcnt(4)
	ds_write_b128 v105, v[92:95] offset:32256
	v_mfma_f32_32x32x16_bf16 v[0:15], v[98:101], v[120:123], v[0:15]
	s_waitcnt vmcnt(3)
	ds_write_b128 v105, v[64:67] offset:55296
	v_mfma_f32_32x32x16_bf16 v[48:63], v[112:115], v[116:119], v[48:63]
	s_waitcnt vmcnt(2)
	ds_write_b128 v105, v[72:75] offset:59904
	v_mfma_f32_32x32x16_bf16 v[32:47], v[112:115], v[124:127], v[32:47]
	s_waitcnt vmcnt(1)
	ds_write_b128 v105, v[76:79] offset:64512
	s_waitcnt lgkmcnt(4)
	v_mfma_f32_32x32x16_bf16 v[16:31], v[128:131], v[116:119], v[16:31]
	s_waitcnt vmcnt(0)
	ds_write_b128 v106, v[80:83] offset:13824
	v_mfma_f32_32x32x16_bf16 v[0:15], v[128:131], v[124:127], v[0:15]
	s_setprio 0
	s_waitcnt lgkmcnt(0)
	s_barrier
	s_setprio 1
	ds_read_b128 v[64:67], v103 offset:18432
	ds_read_b128 v[68:71], v104 offset:55296
	ds_read_b128 v[72:75], v103 offset:18464
	ds_read_b128 v[76:79], v104 offset:55328
	ds_read_b128 v[80:83], v104 offset:59904
	ds_read_b128 v[84:87], v104 offset:59936
	s_waitcnt lgkmcnt(4)
	v_mfma_f32_32x32x16_bf16 v[48:63], v[64:67], v[68:71], v[48:63]
	s_waitcnt lgkmcnt(1)
	v_mfma_f32_32x32x16_bf16 v[32:47], v[64:67], v[80:83], v[32:47]
	ds_read_b128 v[64:67], v103 offset:23040
	ds_read_b128 v[88:91], v103 offset:23072
	s_waitcnt lgkmcnt(1)
	v_mfma_f32_32x32x16_bf16 v[16:31], v[64:67], v[68:71], v[16:31]
	v_mfma_f32_32x32x16_bf16 v[0:15], v[64:67], v[80:83], v[0:15]
	v_mfma_f32_32x32x16_bf16 v[48:63], v[72:75], v[76:79], v[48:63]
	v_mfma_f32_32x32x16_bf16 v[32:47], v[72:75], v[84:87], v[32:47]
	s_waitcnt lgkmcnt(0)
	v_mfma_f32_32x32x16_bf16 v[16:31], v[88:91], v[76:79], v[16:31]
	ds_read_b128 v[64:67], v103 offset:18496
	ds_read_b128 v[68:71], v104 offset:55360
	ds_read_b128 v[72:75], v103 offset:18528
	ds_read_b128 v[76:79], v104 offset:55392
	v_mfma_f32_32x32x16_bf16 v[0:15], v[88:91], v[84:87], v[0:15]
	ds_read_b128 v[80:83], v104 offset:59968
	ds_read_b128 v[84:87], v104 offset:60000
	s_waitcnt lgkmcnt(4)
	v_mfma_f32_32x32x16_bf16 v[48:63], v[64:67], v[68:71], v[48:63]
	s_waitcnt lgkmcnt(1)
	v_mfma_f32_32x32x16_bf16 v[32:47], v[64:67], v[80:83], v[32:47]
	ds_read_b128 v[64:67], v103 offset:23104
	ds_read_b128 v[88:91], v103 offset:23136
	s_waitcnt lgkmcnt(1)
	v_mfma_f32_32x32x16_bf16 v[16:31], v[64:67], v[68:71], v[16:31]
	v_mfma_f32_32x32x16_bf16 v[0:15], v[64:67], v[80:83], v[0:15]
	v_mfma_f32_32x32x16_bf16 v[48:63], v[72:75], v[76:79], v[48:63]
	v_mfma_f32_32x32x16_bf16 v[32:47], v[72:75], v[84:87], v[32:47]
	s_waitcnt lgkmcnt(0)
	v_mfma_f32_32x32x16_bf16 v[16:31], v[88:91], v[76:79], v[16:31]
	v_mfma_f32_32x32x16_bf16 v[0:15], v[88:91], v[84:87], v[0:15]
	s_setprio 0
	v_lshrrev_b32_e32 v65, 3, v102
	v_lshrrev_b32_e32 v64, 1, v102
	v_and_b32_e32 v65, 4, v65
	v_and_or_b32 v64, v64, s22, v65
	v_and_b32_e32 v65, 0x5f, v102
	v_lshlrev_b32_e32 v65, 1, v65
	v_mul_lo_u32 v64, v64, s36
	v_add3_u32 v64, 32, v65, v64
	s_nop 2
	v_cvt_pk_bf16_f32 v0, v0, s0
	s_barrier
	ds_write_b16 v64, v0 offset:8768
	v_cvt_pk_bf16_f32 v0, v17, s0
	ds_write_b16 v64, v0 offset:8976
	v_cvt_pk_bf16_f32 v0, v1, s0
	ds_write_b16 v64, v0 offset:9040
	v_cvt_pk_bf16_f32 v0, v18, s0
	v_cvt_pk_bf16_f32 v32, v32, s0
	ds_write_b16 v64, v0 offset:9248
	v_cvt_pk_bf16_f32 v0, v2, s0
	ds_write_b16 v64, v32 offset:64
	v_cvt_pk_bf16_f32 v32, v49, s0
	ds_write_b16 v64, v0 offset:9312
	v_cvt_pk_bf16_f32 v0, v19, s0
	ds_write_b16 v64, v32 offset:272
	v_cvt_pk_bf16_f32 v32, v33, s0
	ds_write_b16 v64, v0 offset:9520
	v_cvt_pk_bf16_f32 v0, v3, s0
	ds_write_b16 v64, v32 offset:336
	v_cvt_pk_bf16_f32 v32, v50, s0
	ds_write_b16 v64, v0 offset:9584
	v_cvt_pk_bf16_f32 v0, v20, s0
	ds_write_b16 v64, v32 offset:544
	v_cvt_pk_bf16_f32 v32, v34, s0
	ds_write_b16 v64, v0 offset:10880
	v_cvt_pk_bf16_f32 v0, v4, s0
	ds_write_b16 v64, v32 offset:608
	v_cvt_pk_bf16_f32 v32, v51, s0
	ds_write_b16 v64, v0 offset:10944
	v_cvt_pk_bf16_f32 v0, v21, s0
	ds_write_b16 v64, v32 offset:816
	v_cvt_pk_bf16_f32 v32, v35, s0
	ds_write_b16 v64, v0 offset:11152
	v_cvt_pk_bf16_f32 v0, v5, s0
	ds_write_b16 v64, v32 offset:880
	v_cvt_pk_bf16_f32 v32, v52, s0
	ds_write_b16 v64, v0 offset:11216
	v_cvt_pk_bf16_f32 v0, v22, s0
	ds_write_b16 v64, v32 offset:2176
	v_cvt_pk_bf16_f32 v32, v36, s0
	ds_write_b16 v64, v0 offset:11424
	v_cvt_pk_bf16_f32 v0, v6, s0
	ds_write_b16 v64, v32 offset:2240
	v_cvt_pk_bf16_f32 v32, v53, s0
	ds_write_b16 v64, v0 offset:11488
	v_cvt_pk_bf16_f32 v0, v23, s0
	ds_write_b16 v64, v32 offset:2448
	v_cvt_pk_bf16_f32 v32, v37, s0
	ds_write_b16 v64, v0 offset:11696
	v_cvt_pk_bf16_f32 v0, v7, s0
	ds_write_b16 v64, v32 offset:2512
	v_cvt_pk_bf16_f32 v32, v54, s0
	ds_write_b16 v64, v0 offset:11760
	v_cvt_pk_bf16_f32 v0, v24, s0
	ds_write_b16 v64, v32 offset:2720
	v_cvt_pk_bf16_f32 v32, v38, s0
	ds_write_b16 v64, v0 offset:13056
	v_cvt_pk_bf16_f32 v0, v8, s0
	ds_write_b16 v64, v32 offset:2784
	v_cvt_pk_bf16_f32 v32, v55, s0
	ds_write_b16 v64, v0 offset:13120
	v_cvt_pk_bf16_f32 v0, v25, s0
	ds_write_b16 v64, v32 offset:2992
	v_cvt_pk_bf16_f32 v32, v39, s0
	ds_write_b16 v64, v0 offset:13328
	v_cvt_pk_bf16_f32 v0, v9, s0
	ds_write_b16 v64, v32 offset:3056
	v_cvt_pk_bf16_f32 v32, v56, s0
	ds_write_b16 v64, v0 offset:13392
	v_cvt_pk_bf16_f32 v0, v26, s0
	ds_write_b16 v64, v32 offset:4352
	v_cvt_pk_bf16_f32 v32, v40, s0
	ds_write_b16 v64, v0 offset:13600
	v_cvt_pk_bf16_f32 v0, v10, s0
	ds_write_b16 v64, v32 offset:4416
	v_cvt_pk_bf16_f32 v32, v57, s0
	ds_write_b16 v64, v0 offset:13664
	v_cvt_pk_bf16_f32 v0, v27, s0
	ds_write_b16 v64, v32 offset:4624
	v_cvt_pk_bf16_f32 v32, v41, s0
	ds_write_b16 v64, v0 offset:13872
	v_cvt_pk_bf16_f32 v0, v11, s0
	ds_write_b16 v64, v32 offset:4688
	v_cvt_pk_bf16_f32 v32, v58, s0
	ds_write_b16 v64, v0 offset:13936
	v_cvt_pk_bf16_f32 v0, v28, s0
	ds_write_b16 v64, v32 offset:4896
	v_cvt_pk_bf16_f32 v32, v42, s0
	ds_write_b16 v64, v0 offset:15232
	v_cvt_pk_bf16_f32 v0, v12, s0
	ds_write_b16 v64, v32 offset:4960
	v_cvt_pk_bf16_f32 v32, v59, s0
	ds_write_b16 v64, v0 offset:15296
	v_cvt_pk_bf16_f32 v0, v29, s0
	ds_write_b16 v64, v32 offset:5168
	v_cvt_pk_bf16_f32 v32, v43, s0
	ds_write_b16 v64, v0 offset:15504
	v_cvt_pk_bf16_f32 v0, v13, s0
	ds_write_b16 v64, v32 offset:5232
	v_cvt_pk_bf16_f32 v32, v60, s0
	ds_write_b16 v64, v0 offset:15568
	v_cvt_pk_bf16_f32 v0, v30, s0
	ds_write_b16 v64, v32 offset:6528
	v_cvt_pk_bf16_f32 v32, v44, s0
	ds_write_b16 v64, v0 offset:15776
	v_cvt_pk_bf16_f32 v0, v14, s0
	s_mul_i32 s11, s11, 0x160000
	ds_write_b16 v64, v32 offset:6592
	v_cvt_pk_bf16_f32 v32, v61, s0
	ds_write_b16 v64, v0 offset:15840
	v_cvt_pk_bf16_f32 v0, v31, s0
	s_add_u32 s41, s13, s11
	ds_write_b16 v64, v32 offset:6800
	v_cvt_pk_bf16_f32 v32, v45, s0
	ds_write_b16 v64, v0 offset:16048
	v_cvt_pk_bf16_f32 v0, v15, s0
	s_addc_u32 s42, s14, 0
	s_ashr_i32 s11, s10, 31
	ds_write_b16 v64, v32 offset:6864
	v_cvt_pk_bf16_f32 v32, v62, s0
	ds_write_b16 v64, v0 offset:16112
	s_lshl_b64 s[10:11], s[10:11], 1
	v_lshlrev_b32_e32 v0, 4, v102
	ds_write_b16 v64, v32 offset:7072
	v_cvt_pk_bf16_f32 v32, v46, s0
	s_add_u32 s10, s41, s10
	v_and_b32_e32 v96, 0xf0, v0
	ds_write_b16 v64, v32 offset:7136
	v_cvt_pk_bf16_f32 v32, v63, s0
	s_addc_u32 s11, s42, s11
	v_add_u32_e32 v8, 32, v96
	v_ashrrev_i32_e32 v9, 4, v102
	v_add_u32_e32 v4, 0x100, v102
	v_cvt_pk_bf16_f32 v48, v48, s0
	ds_write_b16 v64, v32 offset:7344
	v_cvt_pk_bf16_f32 v32, v47, s0
	v_cvt_pk_bf16_f32 v16, v16, s0
	v_lshl_add_u64 v[10:11], s[10:11], 0, v[96:97]
	v_mad_u64_u32 v[0:1], s[10:11], v9, s36, v[8:9]
	v_ashrrev_i32_e32 v14, 4, v4
	ds_write_b16 v64, v48
	ds_write_b16 v64, v32 offset:7408
	ds_write_b16 v64, v16 offset:8704
	s_waitcnt lgkmcnt(0)
	s_barrier
	ds_read_b128 v[0:3], v0
	v_mad_u64_u32 v[4:5], s[10:11], v14, s36, v[8:9]
	ds_read_b128 v[4:7], v4
	v_mad_i64_i32 v[12:13], s[10:11], v9, s37, v[10:11]
	s_waitcnt lgkmcnt(1)
	global_store_dwordx4 v[12:13], v[0:3], off
	s_nop 1
	v_mad_i64_i32 v[0:1], s[10:11], v14, s37, v[10:11]
	s_waitcnt lgkmcnt(0)
	global_store_dwordx4 v[0:1], v[4:7], off
	v_add_u32_e32 v0, 0x200, v102
	v_ashrrev_i32_e32 v9, 4, v0
	v_add_u32_e32 v4, 0x300, v102
	v_mad_u64_u32 v[0:1], s[10:11], v9, s36, v[8:9]
	v_ashrrev_i32_e32 v14, 4, v4
	ds_read_b128 v[0:3], v0
	v_mad_u64_u32 v[4:5], s[10:11], v14, s36, v[8:9]
	ds_read_b128 v[4:7], v4
	v_mad_i64_i32 v[12:13], s[10:11], v9, s37, v[10:11]
	s_waitcnt lgkmcnt(1)
	global_store_dwordx4 v[12:13], v[0:3], off
	s_nop 1
	v_mad_i64_i32 v[0:1], s[10:11], v14, s37, v[10:11]
	s_waitcnt lgkmcnt(0)
	global_store_dwordx4 v[0:1], v[4:7], off
	v_add_u32_e32 v0, 0x400, v102
	v_ashrrev_i32_e32 v9, 4, v0
	v_add_u32_e32 v4, 0x500, v102
	v_mad_u64_u32 v[0:1], s[10:11], v9, s36, v[8:9]
	v_ashrrev_i32_e32 v14, 4, v4
	ds_read_b128 v[0:3], v0
	v_mad_u64_u32 v[4:5], s[10:11], v14, s36, v[8:9]
	ds_read_b128 v[4:7], v4
	v_mad_i64_i32 v[12:13], s[10:11], v9, s37, v[10:11]
	s_waitcnt lgkmcnt(1)
	global_store_dwordx4 v[12:13], v[0:3], off
	s_nop 1
	v_mad_i64_i32 v[0:1], s[10:11], v14, s37, v[10:11]
	s_waitcnt lgkmcnt(0)
	global_store_dwordx4 v[0:1], v[4:7], off
	v_add_u32_e32 v0, 0x600, v102
	v_ashrrev_i32_e32 v9, 4, v0
	v_add_u32_e32 v4, 0x700, v102
	v_mad_u64_u32 v[0:1], s[10:11], v9, s36, v[8:9]
	v_ashrrev_i32_e32 v12, 4, v4
	ds_read_b128 v[0:3], v0
	v_mad_u64_u32 v[4:5], s[10:11], v12, s36, v[8:9]
	ds_read_b128 v[4:7], v4
	v_mad_i64_i32 v[8:9], s[10:11], v9, s37, v[10:11]
	s_waitcnt lgkmcnt(1)
	global_store_dwordx4 v[8:9], v[0:3], off
	s_nop 1
	v_mad_i64_i32 v[0:1], s[10:11], v12, s37, v[10:11]
	s_waitcnt lgkmcnt(0)
	global_store_dwordx4 v[0:1], v[4:7], off
	s_branch .LBB0_3926

.LBB0_4050:
	s_and_b32 s0, s62, 7
	s_or_b32 s1, s0, s3
	s_lshl_b32 s0, s62, 4
	v_mov_b32_e32 v0, v234
	s_waitcnt vmcnt(6)
	v_mov_b32_e32 v33, v234
	s_and_b32 s27, s0, 0xffffff80
	s_lshl_b32 s0, s1, 7
	s_waitcnt lgkmcnt(0)
	v_ashrrev_i32_e32 v32, 3, v33
	v_add_u32_e32 v0, s0, v32
	v_lshlrev_b32_e32 v2, 4, v33
	v_mad_i64_i32 v[0:1], s[24:25], v0, s42, v[96:97]
	v_and_b32_e32 v98, 0x70, v2
	s_waitcnt vmcnt(5)
	v_lshl_add_u64 v[34:35], v[0:1], 0, v[98:99]
	s_waitcnt vmcnt(4)
	v_add_co_u32_e32 v38, vcc, s43, v34
	v_add_u32_e32 v0, s27, v32
	s_nop 0
	v_addc_co_u32_e32 v39, vcc, 0, v35, vcc
	v_add_co_u32_e32 v40, vcc, s44, v34
	v_mad_i64_i32 v[0:1], s[24:25], v0, s42, v[100:101]
	s_nop 0
	v_addc_co_u32_e32 v41, vcc, 0, v35, vcc
	v_add_co_u32_e32 v42, vcc, s45, v34
	v_lshl_add_u64 v[36:37], v[0:1], 0, v[98:99]
	s_nop 0
	v_addc_co_u32_e32 v43, vcc, 0, v35, vcc
	v_add_co_u32_e32 v44, vcc, s43, v36
	s_barrier
	s_nop 0
	v_addc_co_u32_e32 v45, vcc, 0, v37, vcc
	v_add_co_u32_e32 v46, vcc, s44, v36
	s_nop 1
	v_addc_co_u32_e32 v47, vcc, 0, v37, vcc
	v_add_co_u32_e32 v48, vcc, s45, v36
	global_load_dwordx4 v[0:3], v[34:35], off
	global_load_dwordx4 v[4:7], v[38:39], off
	v_addc_co_u32_e32 v49, vcc, 0, v37, vcc
	global_load_dwordx4 v[8:11], v[40:41], off
	global_load_dwordx4 v[12:15], v[42:43], off
	global_load_dwordx4 v[16:19], v[36:37], off
	global_load_dwordx4 v[20:23], v[44:45], off
	global_load_dwordx4 v[24:27], v[46:47], off
	global_load_dwordx4 v[28:31], v[48:49], off
	global_load_dwordx4 v[68:71], v[34:35], off offset:128
	global_load_dwordx4 v[64:67], v[36:37], off offset:128
	global_load_dwordx4 v[84:87], v[38:39], off offset:128
	global_load_dwordx4 v[88:91], v[40:41], off offset:128
	global_load_dwordx4 v[92:95], v[42:43], off offset:128
	global_load_dwordx4 v[72:75], v[44:45], off offset:128
	global_load_dwordx4 v[76:79], v[46:47], off offset:128
	global_load_dwordx4 v[80:83], v[48:49], off offset:128
	v_and_b32_e32 v52, 0x5f, v33
	v_mul_lo_u32 v53, v32, s46
	v_lshrrev_b32_e32 v50, 1, v33
	v_and_b32_e32 v51, 31, v33
	v_mul_u32_u24_e32 v52, 0x48, v52
	v_add3_u32 v111, 32, v53, v98
	s_and_b32 s24, s36, 0xffffff80
	s_and_b32 s12, s35, 7
	v_and_or_b32 v51, v50, s47, v51
	v_and_b32_e32 v50, 16, v50
	s_lshl_b32 s26, s12, 7
	s_ashr_i32 s25, s24, 31
	v_mul_lo_u32 v51, v51, s46
	v_add3_u32 v109, 32, v51, v50
	v_add_u32_e32 v112, 0xd800, v111
	s_mov_b32 s12, -2
	v_mov_b32_e32 v34, v99
	v_mov_b32_e32 v35, v99
	v_mov_b32_e32 v36, v99
	v_mov_b32_e32 v37, v99
	v_mov_b32_e32 v38, v99
	v_mov_b32_e32 v39, v99
	v_mov_b32_e32 v40, v99
	v_mov_b32_e32 v41, v99
	v_mov_b32_e32 v42, v99
	v_mov_b32_e32 v43, v99
	v_mov_b32_e32 v44, v99
	v_mov_b32_e32 v45, v99
	v_mov_b32_e32 v46, v99
	v_mov_b32_e32 v47, v99
	v_mov_b32_e32 v48, v99
	v_mov_b32_e32 v49, v99
	v_mov_b32_e32 v51, v99
	v_mov_b32_e32 v53, v99
	v_mov_b32_e32 v54, v99
	v_mov_b32_e32 v55, v99
	v_mov_b32_e32 v56, v99
	s_waitcnt vmcnt(15)
	ds_write_b128 v111, v[0:3]
	s_waitcnt vmcnt(11)
	ds_write_b128 v111, v[16:19] offset:36864
	ds_write_b128 v111, v[4:7] offset:4608
	ds_write_b128 v111, v[8:11] offset:9216
	ds_write_b128 v111, v[12:15] offset:13824
	s_waitcnt vmcnt(10)
	ds_write_b128 v111, v[20:23] offset:41472
	s_waitcnt vmcnt(9)
	ds_write_b128 v111, v[24:27] offset:46080
	s_waitcnt vmcnt(8)
	ds_write_b128 v111, v[28:31] offset:50688
	v_lshlrev_b32_e32 v0, 1, v52
	v_add3_u32 v110, 32, v0, v50
	v_and_b32_e32 v0, 7, v33
	v_ashrrev_i32_e32 v33, 31, v32
	v_lshlrev_b32_e32 v98, 4, v0
	v_lshl_add_u64 v[0:1], v[32:33], 0, s[24:25]
	s_add_i32 s25, s26, s38
	v_mad_u64_u32 v[104:105], s[66:67], v0, s42, v[102:103]
	v_add_u32_e32 v0, s25, v32
	v_mad_i32_i24 v105, v1, s42, v105
	v_mad_i64_i32 v[106:107], s[66:67], v0, s42, v[102:103]
	v_mov_b32_e32 v0, v99
	v_mov_b32_e32 v1, v99
	v_mov_b32_e32 v2, v99
	v_mov_b32_e32 v3, v99
	v_mov_b32_e32 v4, v99
	v_mov_b32_e32 v5, v99
	v_mov_b32_e32 v6, v99
	v_mov_b32_e32 v7, v99
	v_mov_b32_e32 v8, v99
	v_mov_b32_e32 v9, v99
	v_mov_b32_e32 v10, v99
	v_mov_b32_e32 v11, v99
	v_mov_b32_e32 v12, v99
	v_mov_b32_e32 v13, v99
	v_mov_b32_e32 v14, v99
	v_mov_b32_e32 v15, v99
	v_mov_b32_e32 v16, v99
	v_mov_b32_e32 v17, v99
	v_mov_b32_e32 v18, v99
	v_mov_b32_e32 v19, v99
	v_mov_b32_e32 v20, v99
	v_mov_b32_e32 v21, v99
	v_mov_b32_e32 v22, v99
	v_mov_b32_e32 v23, v99
	v_mov_b32_e32 v24, v99
	v_mov_b32_e32 v25, v99
	v_mov_b32_e32 v26, v99
	v_mov_b32_e32 v27, v99
	v_mov_b32_e32 v28, v99
	v_mov_b32_e32 v29, v99
	v_mov_b32_e32 v30, v99
	v_mov_b32_e32 v31, v99
	v_mov_b32_e32 v32, v99
	v_mov_b32_e32 v33, v99
	v_mov_b32_e32 v50, v99
	v_mov_b32_e32 v52, v99
	v_mov_b32_e32 v57, v99
	v_mov_b32_e32 v58, v99
	v_mov_b32_e32 v59, v99
	v_mov_b32_e32 v60, v99
	v_mov_b32_e32 v61, v99
	v_mov_b32_e32 v62, v99
	v_mov_b32_e32 v63, v99
	v_lshl_add_u64 v[122:123], v[106:107], 0, v[98:99]
	v_add_co_u32_e32 v174, vcc, s48, v122
	v_lshl_add_u64 v[138:139], v[104:105], 0, v[98:99]
	s_nop 0
	v_addc_co_u32_e32 v175, vcc, 0, v123, vcc
	v_add_co_u32_e32 v176, vcc, s49, v122
	s_nop 1
	v_addc_co_u32_e32 v177, vcc, 0, v123, vcc
	v_add_co_u32_e32 v178, vcc, s50, v122
	s_nop 1
	v_addc_co_u32_e32 v179, vcc, 0, v123, vcc
	v_add_co_u32_e32 v180, vcc, s51, v122
	s_nop 1
	v_addc_co_u32_e32 v181, vcc, 0, v123, vcc
	v_add_co_u32_e32 v182, vcc, s52, v138
	s_nop 1
	v_addc_co_u32_e32 v183, vcc, 0, v139, vcc
	v_add_co_u32_e32 v184, vcc, s53, v138
	s_nop 1
	v_addc_co_u32_e32 v185, vcc, 0, v139, vcc
	v_add_co_u32_e32 v186, vcc, s54, v138
	s_nop 1
	v_addc_co_u32_e32 v187, vcc, 0, v139, vcc
	v_add_co_u32_e32 v188, vcc, s55, v138
	s_nop 1
	v_addc_co_u32_e32 v189, vcc, 0, v139, vcc
	v_subrev_u32_e32 v174, s30, v174
	v_subrev_u32_e32 v176, s30, v176
	v_subrev_u32_e32 v178, s30, v178
	v_subrev_u32_e32 v180, s30, v180
	v_subrev_u32_e32 v182, s30, v182
	v_subrev_u32_e32 v184, s30, v184
	v_subrev_u32_e32 v186, s30, v186
	v_subrev_u32_e32 v188, s30, v188
	s_mov_b64 s[98:99], s[30:31]
	s_waitcnt lgkmcnt(0)
	s_barrier
.LBB0_4051:
	s_setprio 1
	ds_read_b128 v[146:149], v109
	ds_read_b128 v[150:153], v110 offset:36864
	ds_read_b128 v[154:157], v109 offset:32
	ds_read_b128 v[158:161], v110 offset:36896
	ds_read_b128 v[162:165], v110 offset:41472
	ds_read_b128 v[166:169], v110 offset:41504
	s_waitcnt lgkmcnt(4)
	v_mfma_f32_32x32x16_bf16 v[48:63], v[146:149], v[150:153], v[48:63]
	global_load_dwordx4 v[114:117], v174, s[98:99] offset:3840
	global_load_dwordx4 v[118:121], v176, s[98:99] offset:3840
	s_waitcnt lgkmcnt(1)
	v_mfma_f32_32x32x16_bf16 v[32:47], v[146:149], v[162:165], v[32:47]
	global_load_dwordx4 v[122:125], v178, s[98:99] offset:3840
	global_load_dwordx4 v[126:129], v180, s[98:99] offset:3840
	ds_read_b128 v[146:149], v109 offset:4608
	ds_read_b128 v[170:173], v109 offset:4640
	s_waitcnt lgkmcnt(1)
	v_mfma_f32_32x32x16_bf16 v[16:31], v[146:149], v[150:153], v[16:31]
	global_load_dwordx4 v[130:133], v182, s[98:99] offset:3840
	global_load_dwordx4 v[134:137], v184, s[98:99] offset:3840
	v_mfma_f32_32x32x16_bf16 v[0:15], v[146:149], v[162:165], v[0:15]
	global_load_dwordx4 v[138:141], v186, s[98:99] offset:3840
	global_load_dwordx4 v[142:145], v188, s[98:99] offset:3840
	v_mfma_f32_32x32x16_bf16 v[48:63], v[154:157], v[158:161], v[48:63]
	v_mfma_f32_32x32x16_bf16 v[32:47], v[154:157], v[166:169], v[32:47]
	s_waitcnt lgkmcnt(0)
	v_mfma_f32_32x32x16_bf16 v[16:31], v[170:173], v[158:161], v[16:31]
	ds_read_b128 v[146:149], v109 offset:64
	ds_read_b128 v[150:153], v110 offset:36928
	ds_read_b128 v[154:157], v109 offset:96
	ds_read_b128 v[158:161], v110 offset:36960
	v_mfma_f32_32x32x16_bf16 v[0:15], v[170:173], v[166:169], v[0:15]
	s_waitcnt vmcnt(15)
	ds_write_b128 v111, v[68:71] offset:18432
	ds_read_b128 v[162:165], v110 offset:41536
	ds_read_b128 v[166:169], v110 offset:41568
	s_waitcnt lgkmcnt(5)
	v_mfma_f32_32x32x16_bf16 v[48:63], v[146:149], v[150:153], v[48:63]
	s_waitcnt vmcnt(13)
	ds_write_b128 v111, v[84:87] offset:23040
	s_waitcnt lgkmcnt(2)
	v_mfma_f32_32x32x16_bf16 v[32:47], v[146:149], v[162:165], v[32:47]
	s_waitcnt vmcnt(12)
	ds_write_b128 v111, v[88:91] offset:27648
	ds_read_b128 v[146:149], v109 offset:4672
	ds_read_b128 v[170:173], v109 offset:4704
	s_waitcnt lgkmcnt(1)
	v_mfma_f32_32x32x16_bf16 v[16:31], v[146:149], v[150:153], v[16:31]
	s_waitcnt vmcnt(11)
	ds_write_b128 v111, v[92:95] offset:32256
	v_mfma_f32_32x32x16_bf16 v[0:15], v[146:149], v[162:165], v[0:15]
	ds_write_b128 v111, v[64:67] offset:55296
	v_mfma_f32_32x32x16_bf16 v[48:63], v[154:157], v[158:161], v[48:63]
	s_waitcnt vmcnt(10)
	ds_write_b128 v111, v[72:75] offset:59904
	v_mfma_f32_32x32x16_bf16 v[32:47], v[154:157], v[166:169], v[32:47]
	s_waitcnt vmcnt(9)
	ds_write_b128 v111, v[76:79] offset:64512
	s_waitcnt lgkmcnt(4)
	v_mfma_f32_32x32x16_bf16 v[16:31], v[170:173], v[158:161], v[16:31]
	s_waitcnt vmcnt(8)
	ds_write_b128 v112, v[80:83] offset:13824
	v_mfma_f32_32x32x16_bf16 v[0:15], v[170:173], v[166:169], v[0:15]
	s_setprio 0
	s_waitcnt lgkmcnt(0)
	s_barrier
	s_setprio 1
	ds_read_b128 v[146:149], v109 offset:18432
	ds_read_b128 v[150:153], v110 offset:55296
	ds_read_b128 v[154:157], v109 offset:18464
	ds_read_b128 v[158:161], v110 offset:55328
	ds_read_b128 v[162:165], v110 offset:59904
	ds_read_b128 v[166:169], v110 offset:59936
	s_waitcnt lgkmcnt(4)
	v_mfma_f32_32x32x16_bf16 v[48:63], v[146:149], v[150:153], v[48:63]
	global_load_dwordx4 v[68:71], v174, s[98:99] offset:3968
	global_load_dwordx4 v[84:87], v176, s[98:99] offset:3968
	s_waitcnt lgkmcnt(1)
	v_mfma_f32_32x32x16_bf16 v[32:47], v[146:149], v[162:165], v[32:47]
	global_load_dwordx4 v[88:91], v178, s[98:99] offset:3968
	global_load_dwordx4 v[92:95], v180, s[98:99] offset:3968
	ds_read_b128 v[146:149], v109 offset:23040
	ds_read_b128 v[170:173], v109 offset:23072
	s_waitcnt lgkmcnt(1)
	v_mfma_f32_32x32x16_bf16 v[16:31], v[146:149], v[150:153], v[16:31]
	global_load_dwordx4 v[64:67], v182, s[98:99] offset:3968
	global_load_dwordx4 v[72:75], v184, s[98:99] offset:3968
	v_mfma_f32_32x32x16_bf16 v[0:15], v[146:149], v[162:165], v[0:15]
	global_load_dwordx4 v[76:79], v186, s[98:99] offset:3968
	global_load_dwordx4 v[80:83], v188, s[98:99] offset:3968
	v_mfma_f32_32x32x16_bf16 v[48:63], v[154:157], v[158:161], v[48:63]
	v_mfma_f32_32x32x16_bf16 v[32:47], v[154:157], v[166:169], v[32:47]
	s_waitcnt lgkmcnt(0)
	v_mfma_f32_32x32x16_bf16 v[16:31], v[170:173], v[158:161], v[16:31]
	ds_read_b128 v[146:149], v109 offset:18496
	ds_read_b128 v[150:153], v110 offset:55360
	ds_read_b128 v[154:157], v109 offset:18528
	ds_read_b128 v[158:161], v110 offset:55392
	v_mfma_f32_32x32x16_bf16 v[0:15], v[170:173], v[166:169], v[0:15]
	s_add_u32 s98, s98, 0x100
	s_addc_u32 s99, s99, 0
	s_add_i32 s12, s12, 2
	s_cmp_lt_u32 s12, 39
	s_waitcnt vmcnt(15)
	ds_write_b128 v111, v[114:117]
	ds_read_b128 v[162:165], v110 offset:59968
	ds_read_b128 v[166:169], v110 offset:60000
	s_waitcnt lgkmcnt(5)
	v_mfma_f32_32x32x16_bf16 v[48:63], v[146:149], v[150:153], v[48:63]
	s_waitcnt vmcnt(14)
	ds_write_b128 v111, v[118:121] offset:4608
	s_waitcnt lgkmcnt(2)
	v_mfma_f32_32x32x16_bf16 v[32:47], v[146:149], v[162:165], v[32:47]
	s_waitcnt vmcnt(13)
	ds_write_b128 v111, v[122:125] offset:9216
	ds_read_b128 v[146:149], v109 offset:23104
	ds_read_b128 v[170:173], v109 offset:23136
	s_waitcnt lgkmcnt(1)
	v_mfma_f32_32x32x16_bf16 v[16:31], v[146:149], v[150:153], v[16:31]
	s_waitcnt vmcnt(12)
	ds_write_b128 v111, v[126:129] offset:13824
	v_mfma_f32_32x32x16_bf16 v[0:15], v[146:149], v[162:165], v[0:15]
	s_waitcnt vmcnt(11)
	ds_write_b128 v111, v[130:133] offset:36864
	v_mfma_f32_32x32x16_bf16 v[48:63], v[154:157], v[158:161], v[48:63]
	s_waitcnt vmcnt(10)
	ds_write_b128 v111, v[134:137] offset:41472
	v_mfma_f32_32x32x16_bf16 v[32:47], v[154:157], v[166:169], v[32:47]
	s_waitcnt vmcnt(9)
	ds_write_b128 v111, v[138:141] offset:46080
	s_waitcnt lgkmcnt(4)
	v_mfma_f32_32x32x16_bf16 v[16:31], v[170:173], v[158:161], v[16:31]
	s_waitcnt vmcnt(8)
	ds_write_b128 v111, v[142:145] offset:50688
	v_mfma_f32_32x32x16_bf16 v[0:15], v[170:173], v[166:169], v[0:15]
	s_setprio 0
	s_waitcnt lgkmcnt(0)
	s_barrier
	s_cbranch_scc1 .LBB0_4051
	s_setprio 1
	ds_read_b128 v[104:107], v109
	ds_read_b128 v[114:117], v110 offset:36864
	ds_read_b128 v[118:121], v109 offset:32
	ds_read_b128 v[122:125], v110 offset:36896
	ds_read_b128 v[126:129], v110 offset:41472
	ds_read_b128 v[130:133], v110 offset:41504
	s_waitcnt lgkmcnt(4)
	v_mfma_f32_32x32x16_bf16 v[48:63], v[104:107], v[114:117], v[48:63]
	s_waitcnt lgkmcnt(1)
	v_mfma_f32_32x32x16_bf16 v[32:47], v[104:107], v[126:129], v[32:47]
	ds_read_b128 v[104:107], v109 offset:4608
	ds_read_b128 v[134:137], v109 offset:4640
	s_waitcnt lgkmcnt(1)
	v_mfma_f32_32x32x16_bf16 v[16:31], v[104:107], v[114:117], v[16:31]
	v_mfma_f32_32x32x16_bf16 v[0:15], v[104:107], v[126:129], v[0:15]
	v_mfma_f32_32x32x16_bf16 v[48:63], v[118:121], v[122:125], v[48:63]
	v_mfma_f32_32x32x16_bf16 v[32:47], v[118:121], v[130:133], v[32:47]
	s_waitcnt lgkmcnt(0)
	v_mfma_f32_32x32x16_bf16 v[16:31], v[134:137], v[122:125], v[16:31]
	ds_read_b128 v[104:107], v109 offset:64
	ds_read_b128 v[114:117], v110 offset:36928
	ds_read_b128 v[118:121], v109 offset:96
	ds_read_b128 v[122:125], v110 offset:36960
	v_mfma_f32_32x32x16_bf16 v[0:15], v[134:137], v[130:133], v[0:15]
	s_waitcnt vmcnt(7)
	ds_write_b128 v111, v[68:71] offset:18432
	ds_read_b128 v[126:129], v110 offset:41536
	ds_read_b128 v[130:133], v110 offset:41568
	s_waitcnt lgkmcnt(5)
	v_mfma_f32_32x32x16_bf16 v[48:63], v[104:107], v[114:117], v[48:63]
	s_waitcnt vmcnt(6)
	ds_write_b128 v111, v[84:87] offset:23040
	s_waitcnt lgkmcnt(2)
	v_mfma_f32_32x32x16_bf16 v[32:47], v[104:107], v[126:129], v[32:47]
	s_waitcnt vmcnt(5)
	ds_write_b128 v111, v[88:91] offset:27648
	ds_read_b128 v[104:107], v109 offset:4672
	ds_read_b128 v[134:137], v109 offset:4704
	s_waitcnt lgkmcnt(1)
	v_mfma_f32_32x32x16_bf16 v[16:31], v[104:107], v[114:117], v[16:31]
	s_waitcnt vmcnt(4)
	ds_write_b128 v111, v[92:95] offset:32256
	v_mfma_f32_32x32x16_bf16 v[0:15], v[104:107], v[126:129], v[0:15]
	s_waitcnt vmcnt(3)
	ds_write_b128 v111, v[64:67] offset:55296
	v_mfma_f32_32x32x16_bf16 v[32:47], v[118:121], v[130:133], v[32:47]
	s_waitcnt vmcnt(2)
	ds_write_b128 v111, v[72:75] offset:59904
	s_waitcnt lgkmcnt(3)
	v_mfma_f32_32x32x16_bf16 v[16:31], v[134:137], v[122:125], v[16:31]
	s_waitcnt vmcnt(1)
	ds_write_b128 v111, v[76:79] offset:64512
	v_mfma_f32_32x32x16_bf16 v[0:15], v[134:137], v[130:133], v[0:15]
	s_waitcnt vmcnt(0)
	ds_write_b128 v112, v[80:83] offset:13824
	v_mfma_f32_32x32x16_bf16 v[48:63], v[118:121], v[122:125], v[48:63]
	s_setprio 0
	s_waitcnt lgkmcnt(0)
	s_barrier
	s_setprio 1
	ds_read_b128 v[64:67], v109 offset:18432
	ds_read_b128 v[68:71], v110 offset:55296
	ds_read_b128 v[72:75], v109 offset:18464
	ds_read_b128 v[76:79], v110 offset:55328
	ds_read_b128 v[80:83], v110 offset:59904
	ds_read_b128 v[84:87], v110 offset:59936
	s_waitcnt lgkmcnt(4)
	v_mfma_f32_32x32x16_bf16 v[48:63], v[64:67], v[68:71], v[48:63]
	s_waitcnt lgkmcnt(1)
	v_mfma_f32_32x32x16_bf16 v[32:47], v[64:67], v[80:83], v[32:47]
	ds_read_b128 v[64:67], v109 offset:23040
	ds_read_b128 v[88:91], v109 offset:23072
	s_waitcnt lgkmcnt(1)
	v_mfma_f32_32x32x16_bf16 v[16:31], v[64:67], v[68:71], v[16:31]
	v_mfma_f32_32x32x16_bf16 v[0:15], v[64:67], v[80:83], v[0:15]
	v_mfma_f32_32x32x16_bf16 v[48:63], v[72:75], v[76:79], v[48:63]
	v_mfma_f32_32x32x16_bf16 v[32:47], v[72:75], v[84:87], v[32:47]
	s_waitcnt lgkmcnt(0)
	v_mfma_f32_32x32x16_bf16 v[16:31], v[88:91], v[76:79], v[16:31]
	ds_read_b128 v[64:67], v109 offset:18496
	ds_read_b128 v[68:71], v110 offset:55360
	ds_read_b128 v[72:75], v109 offset:18528
	ds_read_b128 v[76:79], v110 offset:55392
	v_mfma_f32_32x32x16_bf16 v[0:15], v[88:91], v[84:87], v[0:15]
	ds_read_b128 v[80:83], v110 offset:59968
	ds_read_b128 v[84:87], v110 offset:60000
	s_waitcnt lgkmcnt(4)
	v_mfma_f32_32x32x16_bf16 v[48:63], v[64:67], v[68:71], v[48:63]
	s_waitcnt lgkmcnt(1)
	v_mfma_f32_32x32x16_bf16 v[32:47], v[64:67], v[80:83], v[32:47]
	ds_read_b128 v[64:67], v109 offset:23104
	ds_read_b128 v[88:91], v109 offset:23136
	s_waitcnt lgkmcnt(1)
	v_mfma_f32_32x32x16_bf16 v[16:31], v[64:67], v[68:71], v[16:31]
	v_mfma_f32_32x32x16_bf16 v[0:15], v[64:67], v[80:83], v[0:15]
	v_mfma_f32_32x32x16_bf16 v[32:47], v[72:75], v[84:87], v[32:47]
	s_waitcnt lgkmcnt(0)
	v_mfma_f32_32x32x16_bf16 v[16:31], v[88:91], v[76:79], v[16:31]
	v_mfma_f32_32x32x16_bf16 v[0:15], v[88:91], v[84:87], v[0:15]
	v_mfma_f32_32x32x16_bf16 v[48:63], v[72:75], v[76:79], v[48:63]
	s_setprio 0
	s_addk_i32 s0, 0xf000
	s_lshr_b32 s12, s0, 10
	s_mulk_i32 s12, 0x1800
	s_add_i32 s12, s12, 0x9000
	s_and_b64 s[66:67], s[4:5], exec
	s_cselect_b32 s12, 0x7800, s12
	v_mov_b32_e32 v68, v234
	s_barrier
	s_lshl_b64 s[66:67], s[12:13], 2
	s_add_u32 s66, s30, s66
	v_and_b32_e32 v69, 0x5f, v68
	v_or_b32_e32 v64, s27, v69
	s_addc_u32 s67, s31, s67
	v_ashrrev_i32_e32 v65, 31, v64
	v_lshl_add_u64 v[64:65], v[64:65], 2, s[66:67]
	v_lshl_add_u64 v[66:67], v[64:65], 0, s[16:17]
	v_add_co_u32_e32 v64, vcc, s56, v64
	v_lshlrev_b32_e32 v69, 2, v69
	s_nop 0
	v_addc_co_u32_e32 v65, vcc, 0, v65, vcc
	global_load_dword v64, v[64:65], off
	s_nop 0
	global_load_dword v65, v[66:67], off offset:128
	v_lshrrev_b32_e32 v67, 3, v68
	v_lshrrev_b32_e32 v66, 1, v68
	v_and_b32_e32 v67, 4, v67
	v_and_or_b32 v66, v66, s47, v67
	v_mul_lo_u32 v66, v66, s57
	v_add3_u32 v66, 32, v69, v66
	v_add_u32_e32 v67, 0x400, v66
	v_add_u32_e32 v69, 0x1000, v66
	v_add_u32_e32 v70, 0x1400, v66
	v_add_u32_e32 v71, 0x2000, v66
	v_add_u32_e32 v72, 0x2400, v66
	v_add_u32_e32 v73, 0x3000, v66
	v_add_u32_e32 v74, 0x3200, v66
	v_add_u32_e32 v75, 0x3400, v66
	v_add_u32_e32 v76, 0x3600, v66
	v_add_u32_e32 v77, 0x4000, v66
	s_lshl_b32 s1, s1, 19
	s_add_u32 s12, s19, s1
	s_mov_b32 s1, s13
	s_waitcnt vmcnt(1)
	v_mul_f32_e32 v48, v48, v64
	s_waitcnt vmcnt(0)
	v_mul_f32_e32 v32, v32, v65
	v_mul_f32_e32 v16, v16, v64
	v_mul_f32_e32 v0, v0, v65
	v_mul_f32_e32 v49, v49, v64
	v_mul_f32_e32 v33, v33, v65
	v_mul_f32_e32 v50, v50, v64
	v_mul_f32_e32 v34, v34, v65
	v_mul_f32_e32 v51, v51, v64
	v_mul_f32_e32 v35, v35, v65
	v_mul_f32_e32 v52, v52, v64
	v_mul_f32_e32 v36, v36, v65
	v_mul_f32_e32 v53, v53, v64
	v_mul_f32_e32 v37, v37, v65
	v_mul_f32_e32 v54, v54, v64
	v_mul_f32_e32 v38, v38, v65
	v_mul_f32_e32 v55, v55, v64
	v_mul_f32_e32 v39, v39, v65
	v_mul_f32_e32 v56, v56, v64
	v_mul_f32_e32 v40, v40, v65
	v_mul_f32_e32 v57, v57, v64
	v_mul_f32_e32 v41, v41, v65
	v_mul_f32_e32 v58, v58, v64
	v_mul_f32_e32 v42, v42, v65
	v_mul_f32_e32 v59, v59, v64
	v_mul_f32_e32 v43, v43, v65
	v_mul_f32_e32 v60, v60, v64
	v_mul_f32_e32 v44, v44, v65
	v_mul_f32_e32 v61, v61, v64
	v_mul_f32_e32 v45, v45, v65
	v_mul_f32_e32 v62, v62, v64
	v_mul_f32_e32 v46, v46, v65
	v_mul_f32_e32 v63, v63, v64
	v_mul_f32_e32 v47, v47, v65
	ds_write2_b32 v66, v48, v32 offset1:32
	ds_write2_b32 v66, v49, v33 offset0:132 offset1:164
	ds_write2_b32 v67, v50, v34 offset0:8 offset1:40
	ds_write2_b32 v67, v51, v35 offset0:140 offset1:172
	ds_write2_b32 v69, v52, v36 offset0:32 offset1:64
	ds_write2_b32 v69, v53, v37 offset0:164 offset1:196
	ds_write2_b32 v70, v54, v38 offset0:40 offset1:72
	ds_write2_b32 v70, v55, v39 offset0:172 offset1:204
	ds_write2_b32 v71, v56, v40 offset0:64 offset1:96
	ds_write2_b32 v71, v57, v41 offset0:196 offset1:228
	ds_write2_b32 v72, v58, v42 offset0:72 offset1:104
	ds_write2_b32 v72, v59, v43 offset0:204 offset1:236
	ds_write2_b32 v73, v60, v44 offset0:96 offset1:128
	ds_write2_b32 v74, v61, v45 offset0:100 offset1:132
	ds_write2_b32 v75, v62, v46 offset0:104 offset1:136
	ds_write2_b32 v76, v63, v47 offset0:108 offset1:140
	ds_write2_b32 v77, v16, v0 offset0:128 offset1:160
	v_mul_f32_e32 v0, v17, v64
	v_mul_f32_e32 v1, v1, v65
	v_add_u32_e32 v16, 0x4400, v66
	ds_write2_b32 v16, v0, v1 offset0:4 offset1:36
	v_mul_f32_e32 v0, v18, v64
	v_mul_f32_e32 v1, v2, v65
	ds_write2_b32 v16, v0, v1 offset0:136 offset1:168
	v_mul_f32_e32 v0, v19, v64
	v_mul_f32_e32 v1, v3, v65
	v_add_u32_e32 v2, 0x4800, v66
	ds_write2_b32 v2, v0, v1 offset0:12 offset1:44
	v_mul_f32_e32 v0, v20, v64
	v_mul_f32_e32 v1, v4, v65
	v_add_u32_e32 v2, 0x5000, v66
	ds_write2_b32 v2, v0, v1 offset0:160 offset1:192
	v_mul_f32_e32 v0, v21, v64
	v_mul_f32_e32 v1, v5, v65
	v_add_u32_e32 v2, 0x5400, v66
	ds_write2_b32 v2, v0, v1 offset0:36 offset1:68
	v_mul_f32_e32 v0, v22, v64
	v_mul_f32_e32 v1, v6, v65
	ds_write2_b32 v2, v0, v1 offset0:168 offset1:200
	v_mul_f32_e32 v0, v23, v64
	v_mul_f32_e32 v1, v7, v65
	v_add_u32_e32 v2, 0x5800, v66
	ds_write2_b32 v2, v0, v1 offset0:44 offset1:76
	v_mul_f32_e32 v0, v24, v64
	v_mul_f32_e32 v1, v8, v65
	v_add_u32_e32 v2, 0x6000, v66
	ds_write2_b32 v2, v0, v1 offset0:192 offset1:224
	v_mul_f32_e32 v0, v25, v64
	v_mul_f32_e32 v1, v9, v65
	v_add_u32_e32 v2, 0x6400, v66
	ds_write2_b32 v2, v0, v1 offset0:68 offset1:100
	v_mul_f32_e32 v0, v26, v64
	v_mul_f32_e32 v1, v10, v65
	ds_write2_b32 v2, v0, v1 offset0:200 offset1:232
	v_mul_f32_e32 v0, v27, v64
	v_mul_f32_e32 v1, v11, v65
	v_add_u32_e32 v2, 0x6800, v66
	ds_write2_b32 v2, v0, v1 offset0:76 offset1:108
	v_mul_f32_e32 v0, v28, v64
	v_mul_f32_e32 v1, v12, v65
	v_add_u32_e32 v2, 0x7200, v66
	ds_write2_b32 v2, v0, v1 offset0:96 offset1:128
	v_mul_f32_e32 v0, v29, v64
	v_mul_f32_e32 v1, v13, v65
	v_add_u32_e32 v2, 0x7400, v66
	ds_write2_b32 v2, v0, v1 offset0:100 offset1:132
	v_mul_f32_e32 v0, v30, v64
	v_mul_f32_e32 v1, v14, v65
	v_add_u32_e32 v2, 0x7600, v66
	v_and_b32_e32 v12, 31, v68
	ds_write2_b32 v2, v0, v1 offset0:104 offset1:136
	v_mul_f32_e32 v0, v31, v64
	v_mul_f32_e32 v1, v15, v65
	v_add_u32_e32 v2, 0x7800, v66
	v_lshlrev_b32_e32 v8, 2, v12
	ds_write2_b32 v2, v0, v1 offset0:108 offset1:140
	v_or_b32_e32 v0, s27, v8
	v_ashrrev_i32_e32 v1, 31, v0
	v_lshlrev_b64 v[0:1], 2, v[0:1]
	v_lshl_add_u64 v[2:3], s[6:7], 0, v[0:1]
	v_lshl_add_u64 v[4:5], s[8:9], 0, v[0:1]
	s_waitcnt lgkmcnt(0)
	s_barrier
	global_load_dwordx4 v[0:3], v[2:3], off
	s_nop 0
	global_load_dwordx4 v[4:7], v[4:5], off
	v_and_b32_e32 v9, 64, v108
	v_add_u32_e32 v9, 64, v9
	v_xor_b32_e32 v10, 1, v108
	v_cmp_lt_i32_e32 vcc, v10, v9
	s_addc_u32 s27, s21, 0
	s_lshl_b64 s[0:1], s[0:1], 12
	v_cndmask_b32_e32 v10, v108, v10, vcc
	v_lshlrev_b32_e32 v32, 2, v10
	v_xor_b32_e32 v10, 2, v108
	v_cmp_lt_i32_e32 vcc, v10, v9
	s_add_u32 s63, s33, s0
	s_addc_u32 s65, s34, s1
	v_cndmask_b32_e32 v10, v108, v10, vcc
	v_lshlrev_b32_e32 v33, 2, v10
	v_xor_b32_e32 v10, 4, v108
	v_cmp_lt_i32_e32 vcc, v10, v9
	s_and_b64 s[0:1], s[4:5], exec
	v_ashrrev_i32_e32 v22, 5, v68
	v_cndmask_b32_e32 v10, v108, v10, vcc
	v_lshlrev_b32_e32 v34, 2, v10
	v_xor_b32_e32 v10, 8, v108
	s_cselect_b32 s67, s27, s65
	s_cselect_b32 s66, s12, s63
	v_cmp_lt_i32_e32 vcc, v10, v9
	s_add_i32 s12, s26, s39
	v_add_u32_e32 v16, s12, v22
	v_cndmask_b32_e32 v10, v108, v10, vcc
	s_add_i32 s12, s26, s40
	s_add_i32 s26, s26, s41
	v_lshlrev_b32_e32 v35, 2, v10
	v_xor_b32_e32 v10, 16, v108
	v_add_u32_e32 v20, s12, v22
	v_add_u32_e32 v24, s26, v22
	v_cmp_eq_u32_e64 s[0:1], 0, v12
	v_cmp_lt_i32_e32 vcc, v10, v9
	v_ashrrev_i32_e32 v23, 31, v22
	v_mul_lo_u32 v13, v22, s57
	v_lshlrev_b32_e32 v12, 4, v12
	v_add_u32_e32 v26, s25, v22
	v_ashrrev_i32_e32 v17, 31, v16
	v_ashrrev_i32_e32 v21, 31, v20
	v_ashrrev_i32_e32 v25, 31, v24
	v_cndmask_b32_e32 v9, v108, v10, vcc
	v_add_u32_e32 v8, s24, v8
	v_lshlrev_b64 v[10:11], 12, v[22:23]
	v_add3_u32 v37, v13, v12, 32
	v_lshlrev_b32_e32 v12, 1, v26
	v_lshlrev_b64 v[14:15], 12, v[16:17]
	v_lshlrev_b32_e32 v16, 1, v16
	v_lshlrev_b64 v[18:19], 12, v[20:21]
	v_lshlrev_b32_e32 v20, 1, v20
	v_lshlrev_b64 v[22:23], 12, v[24:25]
	v_lshlrev_b32_e32 v24, 1, v24
	v_ashrrev_i32_e32 v27, 31, v26
	v_lshlrev_b32_e32 v36, 2, v9
	v_ashrrev_i32_e32 v9, 31, v8
	v_ashrrev_i32_e32 v13, 31, v12
	v_ashrrev_i32_e32 v17, 31, v16
	v_ashrrev_i32_e32 v21, 31, v20
	v_ashrrev_i32_e32 v25, 31, v24
	v_lshlrev_b64 v[26:27], 12, v[26:27]
	v_lshlrev_b64 v[8:9], 2, v[8:9]
	v_lshl_add_u64 v[10:11], s[66:67], 0, v[10:11]
	v_lshl_add_u64 v[12:13], v[12:13], 2, s[30:31]
	v_lshl_add_u64 v[14:15], s[28:29], 0, v[14:15]
	v_lshl_add_u64 v[16:17], v[16:17], 2, s[30:31]
	v_lshl_add_u64 v[18:19], s[28:29], 0, v[18:19]
	v_lshl_add_u64 v[20:21], v[20:21], 2, s[30:31]
	v_lshl_add_u64 v[22:23], s[28:29], 0, v[22:23]
	v_lshl_add_u64 v[24:25], v[24:25], 2, s[30:31]
	v_lshl_add_u64 v[26:27], s[10:11], 0, v[26:27]
	s_mov_b64 s[24:25], 0
	s_branch .LBB0_4054

	.amdhsa_kernel _Z4mega6Paramsii
		.amdhsa_group_segment_fixed_size 32
		.amdhsa_private_segment_fixed_size 0
		.amdhsa_kernarg_size 536
		.amdhsa_user_sgpr_count 2
		.amdhsa_user_sgpr_dispatch_ptr 0
		.amdhsa_user_sgpr_queue_ptr 0
		.amdhsa_user_sgpr_kernarg_segment_ptr 1
		.amdhsa_user_sgpr_dispatch_id 0
		.amdhsa_user_sgpr_kernarg_preload_length 0
		.amdhsa_user_sgpr_kernarg_preload_offset 0
		.amdhsa_user_sgpr_private_segment_size 0
		.amdhsa_uses_dynamic_stack 0
		.amdhsa_enable_private_segment 0
		.amdhsa_system_sgpr_workgroup_id_x 1
		.amdhsa_system_sgpr_workgroup_id_y 0
		.amdhsa_system_sgpr_workgroup_id_z 0
		.amdhsa_system_sgpr_workgroup_info 0
		.amdhsa_system_vgpr_workitem_id 2
		.amdhsa_next_free_vgpr 252
		.amdhsa_next_free_sgpr 102
		.amdhsa_accum_offset 252
		.amdhsa_reserve_vcc 1
		.amdhsa_float_round_mode_32 0
		.amdhsa_float_round_mode_16_64 0
		.amdhsa_float_denorm_mode_32 3
		.amdhsa_float_denorm_mode_16_64 3
		.amdhsa_dx10_clamp 1
		.amdhsa_ieee_mode 1
		.amdhsa_fp16_overflow 0
		.amdhsa_tg_split 0
		.amdhsa_exception_fp_ieee_invalid_op 0
		.amdhsa_exception_fp_denorm_src 0
		.amdhsa_exception_fp_ieee_div_zero 0
		.amdhsa_exception_fp_ieee_overflow 0
		.amdhsa_exception_fp_ieee_underflow 0
		.amdhsa_exception_fp_ieee_inexact 0
		.amdhsa_exception_int_div_zero 0
	.end_amdhsa_kernel

amdhsa.kernels:
  - .agpr_count:     0
    .args:
      - .offset:         0
        .size:           272
        .value_kind:     by_value
      - .offset:         272
        .size:           4
        .value_kind:     by_value
      - .offset:         276
        .size:           4
        .value_kind:     by_value
      - .offset:         280
        .size:           4
        .value_kind:     hidden_block_count_x
      - .offset:         284
        .size:           4
        .value_kind:     hidden_block_count_y
      - .offset:         288
        .size:           4
        .value_kind:     hidden_block_count_z
      - .offset:         292
        .size:           2
        .value_kind:     hidden_group_size_x
      - .offset:         294
        .size:           2
        .value_kind:     hidden_group_size_y
      - .offset:         296
        .size:           2
        .value_kind:     hidden_group_size_z
      - .offset:         298
        .size:           2
        .value_kind:     hidden_remainder_x
      - .offset:         300
        .size:           2
        .value_kind:     hidden_remainder_y
      - .offset:         302
        .size:           2
        .value_kind:     hidden_remainder_z
      - .offset:         320
        .size:           8
        .value_kind:     hidden_global_offset_x
      - .offset:         328
        .size:           8
        .value_kind:     hidden_global_offset_y
      - .offset:         336
        .size:           8
        .value_kind:     hidden_global_offset_z
      - .offset:         344
        .size:           2
        .value_kind:     hidden_grid_dims
      - .offset:         368
        .size:           8
        .value_kind:     hidden_multigrid_sync_arg
      - .offset:         400
        .size:           4
        .value_kind:     hidden_dynamic_lds_size
    .group_segment_fixed_size: 32
    .kernarg_segment_align: 8
    .kernarg_segment_size: 536
    .language:       OpenCL C
    .language_version:
      - 2
      - 0
    .max_flat_workgroup_size: 256
    .name:           _Z4mega6Paramsii
    .private_segment_fixed_size: 0
    .sgpr_count:     108
    .sgpr_spill_count: 166
    .symbol:         _Z4mega6Paramsii.kd
    .uniform_work_group_size: 1
    .uses_dynamic_stack: false
    .vgpr_count:     252
    .vgpr_spill_count: 0
    .wavefront_size: 64
